# fp8 attention step bodies (no-mask variants): the 16 per-step accumulator copies removed: rescale runs in place and the PV MFMAs take C from the home registers
# speedup vs baseline: 1.0971x; 1.0096x over previous
; template <bool SLC, bool NOMASK> ...
;     const int kq = lane >> 4;
;     const int pos0 = SLC ? (dcur & 0xfffff) : dcur;
;     const int lo = SLC ? ((((dcur >> 20) == qi) | ((dcur >> 20) == 4)) ? 0 : (1 << 30)) : lo_in;
;     load_frag8(nxt, KF, VF, SLC ? (dnext & 0xfffff) : dnext, lane);
;     f32x4 sa[2] = {(f32x4){0.f, 0.f, 0.f, 0.f}, (f32x4){0.f, 0.f, 0.f, 0.f}};
; #pragma unroll
;     for (int T = 0; T < 2; ++T)
; #pragma unroll
;         for (int s2 = 0; s2 < 4; ++s2) sa[T] = __builtin_amdgcn_mfma_f32_16x16x32_fp8_fp8(cur.k[T][s2], qf[s2], sa[T], 0, 0, 0);
;     float sc[8]; bool vd[8]; float mx = -1e30f;
;     const bool act = lo == 0 || !SLC;
;     if (NOMASK) {
; #pragma unroll
;         for (int j = 0; j < 8; ++j) { sc[j] = sa[j >> 2][j & 3]; vd[j] = act; }
;         mx = fmaxf(fmaxf(fmaxf(sc[0], sc[1]), fmaxf(sc[2], sc[3])), fmaxf(fmaxf(sc[4], sc[5]), fmaxf(sc[6], sc[7])));
;         mx = act ? mx : -1e30f;
;     } else {
; #pragma unroll
;         for (int T = 0; T < 2; ++T)
; #pragma unroll
;             for (int r = 0; r < 4; ++r) { const int p = pos0 + 16 * T + 4 * kq + r; const bool v = (p >= lo) & (p <= hi); const float x = sa[T][r];
;                 sc[4 * T + r] = x; vd[4 * T + r] = v; mx = v ? fmaxf(mx, x) : mx; }
;     }
;     if (__builtin_amdgcn_ballot_w64(mx > st.m + 4.f) != 0ull) {
;         mx = fmaxf(mx, __shfl_xor(mx, 16)); mx = fmaxf(mx, __shfl_xor(mx, 32));
;         const float mn = fmaxf(st.m, mx), alpha = __builtin_amdgcn_exp2f(st.m - mn); st.m = mn; st.l *= alpha;
; #pragma unroll
;         for (int j = 0; j < 8; ++j) st.o[j] = st.o[j] * alpha;
;     }
;     f32x4 pa, pb; float ps = 0.f;
;     const float mref = st.m - 4.f;
;     if (NOMASK) {
; #pragma unroll
;         for (int j = 0; j < 4; ++j) { pa[j] = __builtin_amdgcn_exp2f(sc[j] - mref); pb[j] = __builtin_amdgcn_exp2f(sc[4 + j] - mref); }
;         if (SLC) {
; #pragma unroll
;             for (int j = 0; j < 4; ++j) { pa[j] = act ? pa[j] : 0.f; pb[j] = act ? pb[j] : 0.f; }
;         }
; #pragma unroll
;         for (int j = 0; j < 4; ++j) ps += pa[j] + pb[j];
;     } else {
; #pragma unroll
;         for (int j = 0; j < 4; ++j) { pa[j] = vd[j] ? __builtin_amdgcn_exp2f(sc[j] - mref) : 0.f; pb[j] = vd[4 + j] ? __builtin_amdgcn_exp2f(sc[4 + j] - mref) : 0.f; ps += pa[j] + pb[j]; }
;     }
;     st.l += ps;
;     const u32x2 pw = pack8_fp8(pa, pb);
.LBB0_704:
	v_lshl_add_u64 v[244:245], v[198:199], 0, v[98:99]
	global_load_dwordx4 v[180:183], v[244:245], off
	global_load_dwordx4 v[184:187], v[244:245], off offset:1024
	global_load_dwordx4 v[188:191], v[244:245], off offset:2048
	global_load_dwordx4 v[192:195], v[244:245], off offset:3072
	v_lshl_add_u64 v[246:247], v[196:197], 0, v[98:99]
	global_load_dwordx4 v[164:167], v[246:247], off
	global_load_dwordx4 v[168:171], v[246:247], off offset:1024
	global_load_dwordx4 v[172:175], v[246:247], off offset:2048
	global_load_dwordx4 v[176:179], v[246:247], off offset:3072
	s_waitcnt vmcnt(20)
	v_mfma_f32_16x16x32_fp8_fp8 v[2:5], v[132:133], v[74:75], 0
	v_mfma_f32_16x16x32_fp8_fp8 v[6:9], v[140:141], v[74:75], 0
	v_mfma_f32_16x16x32_fp8_fp8 v[2:5], v[134:135], v[76:77], v[2:5]
	v_mov_b32_e32 v207, v210
	v_mfma_f32_16x16x32_fp8_fp8 v[6:9], v[142:143], v[76:77], v[6:9]
	v_mfma_f32_16x16x32_fp8_fp8 v[2:5], v[136:137], v[78:79], v[2:5]
	v_mfma_f32_16x16x32_fp8_fp8 v[6:9], v[144:145], v[78:79], v[6:9]
	v_mov_b32_e32 v208, v209
	v_mfma_f32_16x16x32_fp8_fp8 v[2:5], v[138:139], v[80:81], v[2:5]
	v_mfma_f32_16x16x32_fp8_fp8 v[6:9], v[146:147], v[80:81], v[6:9]
	s_nop 6
	v_max_f32_e32 v0, v3, v3
	v_max_f32_e32 v10, v2, v2
	v_max_f32_e32 v0, v10, v0
	v_max_f32_e32 v10, v5, v5
	v_max_f32_e32 v11, v4, v4
	v_max_f32_e32 v10, v11, v10
	v_max_f32_e32 v11, v9, v9
	v_max_f32_e32 v12, v8, v8
	v_max_f32_e32 v11, v12, v11
	v_max3_f32 v11, v6, v7, v11
	v_max3_f32 v0, v0, v10, v11
	v_cmp_gt_f32_e32 vcc, v0, v211
	s_cbranch_vccz .LBB0_706
	v_and_b32_e32 v11, 64, v204
	v_xor_b32_e32 v10, 16, v204
	v_add_u32_e32 v11, 64, v11
	v_cmp_lt_i32_e32 vcc, v10, v11
	v_xor_b32_e32 v12, 32, v204
	s_nop 0
	v_cndmask_b32_e32 v10, v204, v10, vcc
	v_lshlrev_b32_e32 v10, 2, v10
	ds_bpermute_b32 v10, v10, v0
	v_max_f32_e32 v0, v0, v0
	v_cmp_lt_i32_e32 vcc, v12, v11
	s_waitcnt lgkmcnt(0)
	v_max_f32_e32 v10, v10, v10
	v_max_f32_e32 v0, v0, v10
	v_cndmask_b32_e32 v10, v204, v12, vcc
	v_lshlrev_b32_e32 v10, 2, v10
	ds_bpermute_b32 v10, v10, v0
	s_waitcnt lgkmcnt(0)
	v_max3_f32 v207, v210, v0, v10
	v_sub_f32_e32 v0, v210, v207
	v_exp_f32_e32 v0, v0
	s_nop 0
	v_mul_f32_e32 v208, v209, v0
	v_pk_mul_f32 v[36:37], v[36:37], v[0:1] op_sel_hi:[1,0]
	v_pk_mul_f32 v[34:35], v[34:35], v[0:1] op_sel_hi:[1,0]
	v_pk_mul_f32 v[40:41], v[40:41], v[0:1] op_sel_hi:[1,0]
	v_pk_mul_f32 v[38:39], v[38:39], v[0:1] op_sel_hi:[1,0]
	v_pk_mul_f32 v[44:45], v[44:45], v[0:1] op_sel_hi:[1,0]
	v_pk_mul_f32 v[42:43], v[42:43], v[0:1] op_sel_hi:[1,0]
	v_pk_mul_f32 v[56:57], v[56:57], v[0:1] op_sel_hi:[1,0]
	v_pk_mul_f32 v[54:55], v[54:55], v[0:1] op_sel_hi:[1,0]
	v_pk_mul_f32 v[64:65], v[64:65], v[0:1] op_sel_hi:[1,0]
	v_pk_mul_f32 v[62:63], v[62:63], v[0:1] op_sel_hi:[1,0]
	v_pk_mul_f32 v[60:61], v[60:61], v[0:1] op_sel_hi:[1,0]
	v_pk_mul_f32 v[58:59], v[58:59], v[0:1] op_sel_hi:[1,0]
	v_pk_mul_f32 v[52:53], v[52:53], v[0:1] op_sel_hi:[1,0]
	v_pk_mul_f32 v[50:51], v[50:51], v[0:1] op_sel_hi:[1,0]
	v_pk_mul_f32 v[48:49], v[48:49], v[0:1] op_sel_hi:[1,0]
	v_pk_mul_f32 v[46:47], v[46:47], v[0:1] op_sel_hi:[1,0]
.LBB0_706:
	v_add_f32_e32 v213, -4.0, v207
	v_sub_f32_e32 v0, v2, v213
	v_exp_f32_e32 v215, v0
	v_sub_f32_e32 v0, v6, v213
	v_exp_f32_e32 v217, v0
	v_sub_f32_e32 v0, v3, v213
	v_exp_f32_e32 v212, v0
	v_sub_f32_e32 v0, v7, v213
	v_exp_f32_e32 v0, v0
	v_sub_f32_e32 v2, v4, v213
	v_exp_f32_e32 v220, v2
	v_sub_f32_e32 v2, v8, v213
	v_exp_f32_e32 v221, v2
	v_sub_f32_e32 v2, v5, v213
	v_exp_f32_e32 v214, v2
	v_sub_f32_e32 v2, v9, v213
	v_mov_b32_e32 v218, v1
	v_mov_b32_e32 v219, v1
	v_exp_f32_e32 v216, v2
	v_cvt_pk_fp8_f32 v218, v215, v212
	v_cvt_pk_fp8_f32 v219, v217, v0
	v_add_f32_e32 v213, v215, v217
	v_add_f32_e32 v215, v220, v221
	v_cvt_pk_fp8_f32 v218, v220, v214 op_sel:[0,0,1]
	v_cvt_pk_fp8_f32 v219, v221, v216 op_sel:[0,0,1]
	s_nop 0
	s_waitcnt vmcnt(19)
	v_mfma_f32_16x16x32_fp8_fp8 v[2:5], v[86:87], v[218:219], v[34:37]
	v_mfma_f32_16x16x32_fp8_fp8 v[10:13], v[90:91], v[218:219], v[42:45]
	s_waitcnt vmcnt(18)
	v_mfma_f32_16x16x32_fp8_fp8 v[18:21], v[94:95], v[218:219], v[62:65]
	s_nop 2
	v_add_f32_e64 v26, v212, v0
	v_add_f32_e64 v27, v213, v1
	v_mfma_f32_16x16x32_fp8_fp8 v[6:9], v[88:89], v[218:219], v[38:41]
	v_pk_add_f32 v[26:27], v[26:27], v[26:27] op_sel_hi:[0,1]
	v_mov_b32_e32 v217, v27
	v_pk_add_f32 v[26:27], v[214:215], v[216:217]
	s_waitcnt vmcnt(17)
	v_mfma_f32_16x16x32_fp8_fp8 v[14:17], v[92:93], v[218:219], v[54:57]
	v_add_f32_e32 v0, v26, v27
	v_add_f32_e32 v208, v0, v208
	v_mfma_f32_16x16x32_fp8_fp8 v[22:25], v[96:97], v[218:219], v[58:61]
	s_waitcnt vmcnt(16)
	v_mfma_f32_16x16x32_fp8_fp8 v[30:33], v[112:113], v[218:219], v[50:53]
	v_mfma_f32_16x16x32_fp8_fp8 v[26:29], v[114:115], v[218:219], v[46:49]
	s_nop 1
	s_branch .LBB0_700

; template <bool SLC, bool NOMASK> ...
;     const int kq = lane >> 4;
;     const int pos0 = SLC ? (dcur & 0xfffff) : dcur;
;     const int lo = SLC ? ((((dcur >> 20) == qi) | ((dcur >> 20) == 4)) ? 0 : (1 << 30)) : lo_in;
;     load_frag8(nxt, KF, VF, SLC ? (dnext & 0xfffff) : dnext, lane);
;     f32x4 sa[2] = {(f32x4){0.f, 0.f, 0.f, 0.f}, (f32x4){0.f, 0.f, 0.f, 0.f}};
; #pragma unroll
;     for (int T = 0; T < 2; ++T)
; #pragma unroll
;         for (int s2 = 0; s2 < 4; ++s2) sa[T] = __builtin_amdgcn_mfma_f32_16x16x32_fp8_fp8(cur.k[T][s2], qf[s2], sa[T], 0, 0, 0);
;     float sc[8]; bool vd[8]; float mx = -1e30f;
;     const bool act = lo == 0 || !SLC;
;     if (NOMASK) {
; #pragma unroll
;         for (int j = 0; j < 8; ++j) { sc[j] = sa[j >> 2][j & 3]; vd[j] = act; }
;         mx = fmaxf(fmaxf(fmaxf(sc[0], sc[1]), fmaxf(sc[2], sc[3])), fmaxf(fmaxf(sc[4], sc[5]), fmaxf(sc[6], sc[7])));
;         mx = act ? mx : -1e30f;
;     } else {
; #pragma unroll
;         for (int T = 0; T < 2; ++T)
; #pragma unroll
;             for (int r = 0; r < 4; ++r) { const int p = pos0 + 16 * T + 4 * kq + r; const bool v = (p >= lo) & (p <= hi); const float x = sa[T][r];
;                 sc[4 * T + r] = x; vd[4 * T + r] = v; mx = v ? fmaxf(mx, x) : mx; }
;     }
;     if (__builtin_amdgcn_ballot_w64(mx > st.m + 4.f) != 0ull) {
;         mx = fmaxf(mx, __shfl_xor(mx, 16)); mx = fmaxf(mx, __shfl_xor(mx, 32));
;         const float mn = fmaxf(st.m, mx), alpha = __builtin_amdgcn_exp2f(st.m - mn); st.m = mn; st.l *= alpha;
; #pragma unroll
;         for (int j = 0; j < 8; ++j) st.o[j] = st.o[j] * alpha;
;     }
;     f32x4 pa, pb; float ps = 0.f;
;     const float mref = st.m - 4.f;
;     if (NOMASK) {
; #pragma unroll
;         for (int j = 0; j < 4; ++j) { pa[j] = __builtin_amdgcn_exp2f(sc[j] - mref); pb[j] = __builtin_amdgcn_exp2f(sc[4 + j] - mref); }
;         if (SLC) {
; #pragma unroll
;             for (int j = 0; j < 4; ++j) { pa[j] = act ? pa[j] : 0.f; pb[j] = act ? pb[j] : 0.f; }
;         }
; #pragma unroll
;         for (int j = 0; j < 4; ++j) ps += pa[j] + pb[j];
;     } else {
; #pragma unroll
;         for (int j = 0; j < 4; ++j) { pa[j] = vd[j] ? __builtin_amdgcn_exp2f(sc[j] - mref) : 0.f; pb[j] = vd[4 + j] ? __builtin_amdgcn_exp2f(sc[4 + j] - mref) : 0.f; ps += pa[j] + pb[j]; }
;     }
;     st.l += ps;
;     const u32x2 pw = pack8_fp8(pa, pb);
.LBB0_711:
	v_lshl_add_u64 v[244:245], v[198:199], 0, v[98:99]
	global_load_dwordx4 v[132:135], v[244:245], off
	global_load_dwordx4 v[136:139], v[244:245], off offset:1024
	global_load_dwordx4 v[140:143], v[244:245], off offset:2048
	global_load_dwordx4 v[144:147], v[244:245], off offset:3072
	v_lshl_add_u64 v[246:247], v[196:197], 0, v[98:99]
	global_load_dwordx4 v[86:89], v[246:247], off
	global_load_dwordx4 v[90:93], v[246:247], off offset:1024
	global_load_dwordx4 v[94:97], v[246:247], off offset:2048
	global_load_dwordx4 v[112:115], v[246:247], off offset:3072
	s_waitcnt vmcnt(20)
	v_mfma_f32_16x16x32_fp8_fp8 v[34:37], v[148:149], v[74:75], 0
	v_mfma_f32_16x16x32_fp8_fp8 v[38:41], v[156:157], v[74:75], 0
	v_mfma_f32_16x16x32_fp8_fp8 v[34:37], v[150:151], v[76:77], v[34:37]
	v_mov_b32_e32 v209, v207
	v_mfma_f32_16x16x32_fp8_fp8 v[38:41], v[158:159], v[76:77], v[38:41]
	v_mfma_f32_16x16x32_fp8_fp8 v[34:37], v[152:153], v[78:79], v[34:37]
	v_mfma_f32_16x16x32_fp8_fp8 v[38:41], v[160:161], v[78:79], v[38:41]
	v_mov_b32_e32 v210, v208
	v_mfma_f32_16x16x32_fp8_fp8 v[34:37], v[154:155], v[80:81], v[34:37]
	v_mfma_f32_16x16x32_fp8_fp8 v[38:41], v[162:163], v[80:81], v[38:41]
	s_nop 6
	v_max_f32_e32 v0, v35, v35
	v_max_f32_e32 v42, v34, v34
	v_max_f32_e32 v0, v42, v0
	v_max_f32_e32 v42, v37, v37
	v_max_f32_e32 v43, v36, v36
	v_max_f32_e32 v42, v43, v42
	v_max_f32_e32 v43, v41, v41
	v_max_f32_e32 v44, v40, v40
	v_max_f32_e32 v43, v44, v43
	v_max3_f32 v43, v38, v39, v43
	v_max3_f32 v0, v0, v42, v43
	v_cmp_gt_f32_e32 vcc, v0, v211
	s_cbranch_vccz .LBB0_713
	v_and_b32_e32 v43, 64, v204
	v_xor_b32_e32 v42, 16, v204
	v_add_u32_e32 v43, 64, v43
	v_cmp_lt_i32_e32 vcc, v42, v43
	v_xor_b32_e32 v44, 32, v204
	s_nop 0
	v_cndmask_b32_e32 v42, v204, v42, vcc
	v_lshlrev_b32_e32 v42, 2, v42
	ds_bpermute_b32 v42, v42, v0
	v_max_f32_e32 v0, v0, v0
	v_cmp_lt_i32_e32 vcc, v44, v43
	s_waitcnt lgkmcnt(0)
	v_max_f32_e32 v42, v42, v42
	v_max_f32_e32 v0, v0, v42
	v_cndmask_b32_e32 v42, v204, v44, vcc
	v_lshlrev_b32_e32 v42, 2, v42
	ds_bpermute_b32 v42, v42, v0
	s_waitcnt lgkmcnt(0)
	v_max3_f32 v209, v207, v0, v42
	v_sub_f32_e32 v0, v207, v209
	v_exp_f32_e32 v0, v0
	s_nop 0
	v_mul_f32_e32 v210, v208, v0
	v_pk_mul_f32 v[4:5], v[4:5], v[0:1] op_sel_hi:[1,0]
	v_pk_mul_f32 v[2:3], v[2:3], v[0:1] op_sel_hi:[1,0]
	v_pk_mul_f32 v[8:9], v[8:9], v[0:1] op_sel_hi:[1,0]
	v_pk_mul_f32 v[6:7], v[6:7], v[0:1] op_sel_hi:[1,0]
	v_pk_mul_f32 v[12:13], v[12:13], v[0:1] op_sel_hi:[1,0]
	v_pk_mul_f32 v[10:11], v[10:11], v[0:1] op_sel_hi:[1,0]
	v_pk_mul_f32 v[16:17], v[16:17], v[0:1] op_sel_hi:[1,0]
	v_pk_mul_f32 v[14:15], v[14:15], v[0:1] op_sel_hi:[1,0]
	v_pk_mul_f32 v[20:21], v[20:21], v[0:1] op_sel_hi:[1,0]
	v_pk_mul_f32 v[18:19], v[18:19], v[0:1] op_sel_hi:[1,0]
	v_pk_mul_f32 v[24:25], v[24:25], v[0:1] op_sel_hi:[1,0]
	v_pk_mul_f32 v[22:23], v[22:23], v[0:1] op_sel_hi:[1,0]
	v_pk_mul_f32 v[32:33], v[32:33], v[0:1] op_sel_hi:[1,0]
	v_pk_mul_f32 v[30:31], v[30:31], v[0:1] op_sel_hi:[1,0]
	v_pk_mul_f32 v[28:29], v[28:29], v[0:1] op_sel_hi:[1,0]
	v_pk_mul_f32 v[26:27], v[26:27], v[0:1] op_sel_hi:[1,0]
.LBB0_713:
	v_add_f32_e32 v213, -4.0, v209
	v_sub_f32_e32 v0, v34, v213
	v_exp_f32_e32 v215, v0
	v_sub_f32_e32 v0, v38, v213
	v_exp_f32_e32 v217, v0
	v_sub_f32_e32 v0, v35, v213
	v_exp_f32_e32 v212, v0
	v_sub_f32_e32 v0, v39, v213
	v_exp_f32_e32 v0, v0
	v_sub_f32_e32 v34, v36, v213
	v_exp_f32_e32 v220, v34
	v_sub_f32_e32 v34, v40, v213
	v_exp_f32_e32 v221, v34
	v_sub_f32_e32 v34, v37, v213
	v_exp_f32_e32 v214, v34
	v_sub_f32_e32 v34, v41, v213
	v_mov_b32_e32 v218, v1
	v_mov_b32_e32 v219, v1
	v_exp_f32_e32 v216, v34
	v_cvt_pk_fp8_f32 v218, v215, v212
	v_cvt_pk_fp8_f32 v219, v217, v0
	v_add_f32_e32 v213, v215, v217
	v_add_f32_e32 v215, v220, v221
	v_cvt_pk_fp8_f32 v218, v220, v214 op_sel:[0,0,1]
	v_cvt_pk_fp8_f32 v219, v221, v216 op_sel:[0,0,1]
	s_nop 0
	s_waitcnt vmcnt(19)
	v_mfma_f32_16x16x32_fp8_fp8 v[34:37], v[116:117], v[218:219], v[2:5]
	v_mfma_f32_16x16x32_fp8_fp8 v[42:45], v[120:121], v[218:219], v[10:13]
	s_waitcnt vmcnt(18)
	v_mfma_f32_16x16x32_fp8_fp8 v[50:53], v[124:125], v[218:219], v[18:21]
	s_nop 2
	v_add_f32_e64 v58, v212, v0
	v_add_f32_e64 v59, v213, v1
	v_mfma_f32_16x16x32_fp8_fp8 v[38:41], v[118:119], v[218:219], v[6:9]
	v_pk_add_f32 v[58:59], v[58:59], v[58:59] op_sel_hi:[0,1]
	v_mov_b32_e32 v217, v59
	s_waitcnt vmcnt(17)
	v_mfma_f32_16x16x32_fp8_fp8 v[46:49], v[122:123], v[218:219], v[14:17]
	v_mfma_f32_16x16x32_fp8_fp8 v[54:57], v[126:127], v[218:219], v[22:25]
	s_nop 2
	v_add_f32_e64 v62, v214, v216
	v_add_f32_e64 v63, v215, v217
	s_waitcnt vmcnt(16)
	v_mfma_f32_16x16x32_fp8_fp8 v[58:61], v[128:129], v[218:219], v[30:33]
	v_add_f32_e32 v0, v62, v63
	v_add_f32_e32 v210, v0, v210
	v_mfma_f32_16x16x32_fp8_fp8 v[62:65], v[130:131], v[218:219], v[26:29]
	s_nop 1
	s_branch .LBB0_703

; template <bool SLC, bool NOMASK> ...
;     const int kq = lane >> 4;
;     const int pos0 = SLC ? (dcur & 0xfffff) : dcur;
;     const int lo = SLC ? ((((dcur >> 20) == qi) | ((dcur >> 20) == 4)) ? 0 : (1 << 30)) : lo_in;
;     load_frag8(nxt, KF, VF, SLC ? (dnext & 0xfffff) : dnext, lane);
;     f32x4 sa[2] = {(f32x4){0.f, 0.f, 0.f, 0.f}, (f32x4){0.f, 0.f, 0.f, 0.f}};
; #pragma unroll
;     for (int T = 0; T < 2; ++T)
; #pragma unroll
;         for (int s2 = 0; s2 < 4; ++s2) sa[T] = __builtin_amdgcn_mfma_f32_16x16x32_fp8_fp8(cur.k[T][s2], qf[s2], sa[T], 0, 0, 0);
;     float sc[8]; bool vd[8]; float mx = -1e30f;
;     const bool act = lo == 0 || !SLC;
;     if (NOMASK) {
; #pragma unroll
;         for (int j = 0; j < 8; ++j) { sc[j] = sa[j >> 2][j & 3]; vd[j] = act; }
;         mx = fmaxf(fmaxf(fmaxf(sc[0], sc[1]), fmaxf(sc[2], sc[3])), fmaxf(fmaxf(sc[4], sc[5]), fmaxf(sc[6], sc[7])));
;         mx = act ? mx : -1e30f;
;     } else {
; #pragma unroll
;         for (int T = 0; T < 2; ++T)
; #pragma unroll
;             for (int r = 0; r < 4; ++r) { const int p = pos0 + 16 * T + 4 * kq + r; const bool v = (p >= lo) & (p <= hi); const float x = sa[T][r];
;                 sc[4 * T + r] = x; vd[4 * T + r] = v; mx = v ? fmaxf(mx, x) : mx; }
;     }
;     if (__builtin_amdgcn_ballot_w64(mx > st.m + 4.f) != 0ull) {
;         mx = fmaxf(mx, __shfl_xor(mx, 16)); mx = fmaxf(mx, __shfl_xor(mx, 32));
;         const float mn = fmaxf(st.m, mx), alpha = __builtin_amdgcn_exp2f(st.m - mn); st.m = mn; st.l *= alpha;
; #pragma unroll
;         for (int j = 0; j < 8; ++j) st.o[j] = st.o[j] * alpha;
;     }
;     f32x4 pa, pb; float ps = 0.f;
;     const float mref = st.m - 4.f;
;     if (NOMASK) {
; #pragma unroll
;         for (int j = 0; j < 4; ++j) { pa[j] = __builtin_amdgcn_exp2f(sc[j] - mref); pb[j] = __builtin_amdgcn_exp2f(sc[4 + j] - mref); }
;         if (SLC) {
; #pragma unroll
;             for (int j = 0; j < 4; ++j) { pa[j] = act ? pa[j] : 0.f; pb[j] = act ? pb[j] : 0.f; }
;         }
; #pragma unroll
;         for (int j = 0; j < 4; ++j) ps += pa[j] + pb[j];
;     } else {
; #pragma unroll
;         for (int j = 0; j < 4; ++j) { pa[j] = vd[j] ? __builtin_amdgcn_exp2f(sc[j] - mref) : 0.f; pb[j] = vd[4 + j] ? __builtin_amdgcn_exp2f(sc[4 + j] - mref) : 0.f; ps += pa[j] + pb[j]; }
;     }
;     st.l += ps;
;     const u32x2 pw = pack8_fp8(pa, pb);
.LBB0_717:
	s_add_i32 s66, s66, 4
	s_min_i32 s4, s66, s74
	s_add_i32 s6, s4, s73
	s_lshl_b32 s76, s6, 5
	s_and_b32 s4, s76, 0x3fffffe0
	s_lshr_b32 s26, s4, 4
	s_lshl_b64 s[4:5], s[26:27], 11
	s_and_b32 s26, s6, 0x1ffffff
	s_and_b32 s8, s42, 0x2000000
	s_lshl_b64 s[6:7], s[26:27], 12
	s_cmp_eq_u32 s8, 0
	v_lshl_add_u64 v[198:199], v[82:83], 0, s[4:5]
	v_lshl_add_u64 v[196:197], v[84:85], 0, s[6:7]
	s_mov_b64 s[4:5], -1
	v_add_f32_e32 v211, 4.0, v209
	s_cbranch_scc1 .LBB0_721
	v_lshl_add_u64 v[244:245], v[198:199], 0, v[98:99]
	global_load_dwordx4 v[148:151], v[244:245], off
	global_load_dwordx4 v[152:155], v[244:245], off offset:1024
	global_load_dwordx4 v[156:159], v[244:245], off offset:2048
	global_load_dwordx4 v[160:163], v[244:245], off offset:3072
	v_lshl_add_u64 v[246:247], v[196:197], 0, v[98:99]
	global_load_dwordx4 v[116:119], v[246:247], off
	global_load_dwordx4 v[120:123], v[246:247], off offset:1024
	global_load_dwordx4 v[124:127], v[246:247], off offset:2048
	global_load_dwordx4 v[128:131], v[246:247], off offset:3072
	s_waitcnt vmcnt(20)
	v_mfma_f32_16x16x32_fp8_fp8 v[2:5], v[180:181], v[74:75], 0
	v_mfma_f32_16x16x32_fp8_fp8 v[6:9], v[188:189], v[74:75], 0
	v_mfma_f32_16x16x32_fp8_fp8 v[2:5], v[182:183], v[76:77], v[2:5]
	v_mov_b32_e32 v207, v209
	v_mfma_f32_16x16x32_fp8_fp8 v[6:9], v[190:191], v[76:77], v[6:9]
	v_mfma_f32_16x16x32_fp8_fp8 v[2:5], v[184:185], v[78:79], v[2:5]
	v_mfma_f32_16x16x32_fp8_fp8 v[6:9], v[192:193], v[78:79], v[6:9]
	v_mov_b32_e32 v208, v210
	v_mfma_f32_16x16x32_fp8_fp8 v[2:5], v[186:187], v[80:81], v[2:5]
	v_mfma_f32_16x16x32_fp8_fp8 v[6:9], v[194:195], v[80:81], v[6:9]
	s_nop 6
	v_max_f32_e32 v0, v3, v3
	v_max_f32_e32 v10, v2, v2
	v_max_f32_e32 v0, v10, v0
	v_max_f32_e32 v10, v5, v5
	v_max_f32_e32 v11, v4, v4
	v_max_f32_e32 v10, v11, v10
	v_max_f32_e32 v11, v9, v9
	v_max_f32_e32 v12, v8, v8
	v_max_f32_e32 v11, v12, v11
	v_max3_f32 v11, v6, v7, v11
	v_max3_f32 v0, v0, v10, v11
	v_cmp_gt_f32_e32 vcc, v0, v211
	s_cbranch_vccz .LBB0_720
	v_and_b32_e32 v11, 64, v204
	v_xor_b32_e32 v10, 16, v204
	v_add_u32_e32 v11, 64, v11
	v_cmp_lt_i32_e32 vcc, v10, v11
	v_xor_b32_e32 v12, 32, v204
	s_nop 0
	v_cndmask_b32_e32 v10, v204, v10, vcc
	v_lshlrev_b32_e32 v10, 2, v10
	ds_bpermute_b32 v10, v10, v0
	v_max_f32_e32 v0, v0, v0
	v_cmp_lt_i32_e32 vcc, v12, v11
	s_waitcnt lgkmcnt(0)
	v_max_f32_e32 v10, v10, v10
	v_max_f32_e32 v0, v0, v10
	v_cndmask_b32_e32 v10, v204, v12, vcc
	v_lshlrev_b32_e32 v10, 2, v10
	ds_bpermute_b32 v10, v10, v0
	s_waitcnt lgkmcnt(0)
	v_max3_f32 v207, v209, v0, v10
	v_sub_f32_e32 v0, v209, v207
	v_exp_f32_e32 v0, v0
	s_nop 0
	v_mul_f32_e32 v208, v210, v0
	v_pk_mul_f32 v[36:37], v[36:37], v[0:1] op_sel_hi:[1,0]
	v_pk_mul_f32 v[34:35], v[34:35], v[0:1] op_sel_hi:[1,0]
	v_pk_mul_f32 v[40:41], v[40:41], v[0:1] op_sel_hi:[1,0]
	v_pk_mul_f32 v[38:39], v[38:39], v[0:1] op_sel_hi:[1,0]
	v_pk_mul_f32 v[44:45], v[44:45], v[0:1] op_sel_hi:[1,0]
	v_pk_mul_f32 v[42:43], v[42:43], v[0:1] op_sel_hi:[1,0]
	v_pk_mul_f32 v[48:49], v[48:49], v[0:1] op_sel_hi:[1,0]
	v_pk_mul_f32 v[46:47], v[46:47], v[0:1] op_sel_hi:[1,0]
	v_pk_mul_f32 v[52:53], v[52:53], v[0:1] op_sel_hi:[1,0]
	v_pk_mul_f32 v[50:51], v[50:51], v[0:1] op_sel_hi:[1,0]
	v_pk_mul_f32 v[56:57], v[56:57], v[0:1] op_sel_hi:[1,0]
	v_pk_mul_f32 v[54:55], v[54:55], v[0:1] op_sel_hi:[1,0]
	v_pk_mul_f32 v[60:61], v[60:61], v[0:1] op_sel_hi:[1,0]
	v_pk_mul_f32 v[58:59], v[58:59], v[0:1] op_sel_hi:[1,0]
	v_pk_mul_f32 v[64:65], v[64:65], v[0:1] op_sel_hi:[1,0]
	v_pk_mul_f32 v[62:63], v[62:63], v[0:1] op_sel_hi:[1,0]
.LBB0_720:
	v_add_f32_e32 v213, -4.0, v207
	v_sub_f32_e32 v0, v2, v213
	v_exp_f32_e32 v215, v0
	v_sub_f32_e32 v0, v6, v213
	v_exp_f32_e32 v217, v0
	v_sub_f32_e32 v0, v3, v213
	v_exp_f32_e32 v212, v0
	v_sub_f32_e32 v0, v7, v213
	v_exp_f32_e32 v0, v0
	v_sub_f32_e32 v2, v4, v213
	v_exp_f32_e32 v220, v2
	v_sub_f32_e32 v2, v8, v213
	v_exp_f32_e32 v221, v2
	v_sub_f32_e32 v2, v5, v213
	v_exp_f32_e32 v214, v2
	v_sub_f32_e32 v2, v9, v213
	v_mov_b32_e32 v218, v1
	v_mov_b32_e32 v219, v1
	v_exp_f32_e32 v216, v2
	v_cvt_pk_fp8_f32 v218, v215, v212
	v_cvt_pk_fp8_f32 v219, v217, v0
	v_add_f32_e32 v213, v215, v217
	v_add_f32_e32 v215, v220, v221
	v_cvt_pk_fp8_f32 v218, v220, v214 op_sel:[0,0,1]
	v_cvt_pk_fp8_f32 v219, v221, v216 op_sel:[0,0,1]
	s_mov_b64 s[4:5], 0
	s_waitcnt vmcnt(19)
	v_mfma_f32_16x16x32_fp8_fp8 v[2:5], v[164:165], v[218:219], v[34:37]
	v_mfma_f32_16x16x32_fp8_fp8 v[10:13], v[168:169], v[218:219], v[42:45]
	s_waitcnt vmcnt(18)
	v_mfma_f32_16x16x32_fp8_fp8 v[18:21], v[172:173], v[218:219], v[50:53]
	s_nop 2
	v_add_f32_e64 v26, v212, v0
	v_add_f32_e64 v27, v213, v1
	v_mfma_f32_16x16x32_fp8_fp8 v[6:9], v[166:167], v[218:219], v[38:41]
	v_pk_add_f32 v[26:27], v[26:27], v[26:27] op_sel_hi:[0,1]
	v_mov_b32_e32 v217, v27
	v_pk_add_f32 v[26:27], v[214:215], v[216:217]
	s_waitcnt vmcnt(17)
	v_mfma_f32_16x16x32_fp8_fp8 v[14:17], v[170:171], v[218:219], v[46:49]
	v_add_f32_e32 v0, v26, v27
	v_add_f32_e32 v208, v0, v208
	v_mfma_f32_16x16x32_fp8_fp8 v[22:25], v[174:175], v[218:219], v[54:57]
	s_waitcnt vmcnt(16)
	v_mfma_f32_16x16x32_fp8_fp8 v[30:33], v[176:177], v[218:219], v[58:61]
	v_mfma_f32_16x16x32_fp8_fp8 v[26:29], v[178:179], v[218:219], v[62:65]
	s_nop 1

; template <bool SLC, bool NOMASK> ...
;     const int kq = lane >> 4;
;     const int pos0 = SLC ? (dcur & 0xfffff) : dcur;
;     const int lo = SLC ? ((((dcur >> 20) == qi) | ((dcur >> 20) == 4)) ? 0 : (1 << 30)) : lo_in;
;     load_frag8(nxt, KF, VF, SLC ? (dnext & 0xfffff) : dnext, lane);
;     f32x4 sa[2] = {(f32x4){0.f, 0.f, 0.f, 0.f}, (f32x4){0.f, 0.f, 0.f, 0.f}};
; #pragma unroll
;     for (int T = 0; T < 2; ++T)
; #pragma unroll
;         for (int s2 = 0; s2 < 4; ++s2) sa[T] = __builtin_amdgcn_mfma_f32_16x16x32_fp8_fp8(cur.k[T][s2], qf[s2], sa[T], 0, 0, 0);
;     float sc[8]; bool vd[8]; float mx = -1e30f;
;     const bool act = lo == 0 || !SLC;
;     if (NOMASK) {
; #pragma unroll
;         for (int j = 0; j < 8; ++j) { sc[j] = sa[j >> 2][j & 3]; vd[j] = act; }
;         mx = fmaxf(fmaxf(fmaxf(sc[0], sc[1]), fmaxf(sc[2], sc[3])), fmaxf(fmaxf(sc[4], sc[5]), fmaxf(sc[6], sc[7])));
;         mx = act ? mx : -1e30f;
;     } else {
; #pragma unroll
;         for (int T = 0; T < 2; ++T)
; #pragma unroll
;             for (int r = 0; r < 4; ++r) { const int p = pos0 + 16 * T + 4 * kq + r; const bool v = (p >= lo) & (p <= hi); const float x = sa[T][r];
;                 sc[4 * T + r] = x; vd[4 * T + r] = v; mx = v ? fmaxf(mx, x) : mx; }
;     }
;     if (__builtin_amdgcn_ballot_w64(mx > st.m + 4.f) != 0ull) {
;         mx = fmaxf(mx, __shfl_xor(mx, 16)); mx = fmaxf(mx, __shfl_xor(mx, 32));
;         const float mn = fmaxf(st.m, mx), alpha = __builtin_amdgcn_exp2f(st.m - mn); st.m = mn; st.l *= alpha;
; #pragma unroll
;         for (int j = 0; j < 8; ++j) st.o[j] = st.o[j] * alpha;
;     }
;     f32x4 pa, pb; float ps = 0.f;
;     const float mref = st.m - 4.f;
;     if (NOMASK) {
; #pragma unroll
;         for (int j = 0; j < 4; ++j) { pa[j] = __builtin_amdgcn_exp2f(sc[j] - mref); pb[j] = __builtin_amdgcn_exp2f(sc[4 + j] - mref); }
;         if (SLC) {
; #pragma unroll
;             for (int j = 0; j < 4; ++j) { pa[j] = act ? pa[j] : 0.f; pb[j] = act ? pb[j] : 0.f; }
;         }
; #pragma unroll
;         for (int j = 0; j < 4; ++j) ps += pa[j] + pb[j];
;     } else {
; #pragma unroll
;         for (int j = 0; j < 4; ++j) { pa[j] = vd[j] ? __builtin_amdgcn_exp2f(sc[j] - mref) : 0.f; pb[j] = vd[4 + j] ? __builtin_amdgcn_exp2f(sc[4 + j] - mref) : 0.f; ps += pa[j] + pb[j]; }
;     }
;     st.l += ps;
;     const u32x2 pw = pack8_fp8(pa, pb);
.LBB0_745:
	v_lshl_add_u64 v[244:245], v[198:199], 0, v[98:99]
	global_load_dwordx4 v[180:183], v[244:245], off
	global_load_dwordx4 v[184:187], v[244:245], off offset:1024
	global_load_dwordx4 v[188:191], v[244:245], off offset:2048
	global_load_dwordx4 v[192:195], v[244:245], off offset:3072
	v_lshl_add_u64 v[246:247], v[196:197], 0, v[98:99]
	global_load_dwordx4 v[164:167], v[246:247], off
	global_load_dwordx4 v[168:171], v[246:247], off offset:1024
	global_load_dwordx4 v[172:175], v[246:247], off offset:2048
	global_load_dwordx4 v[176:179], v[246:247], off offset:3072
	s_waitcnt vmcnt(20)
	v_mfma_f32_16x16x32_fp8_fp8 v[2:5], v[132:133], v[74:75], 0
	v_mfma_f32_16x16x32_fp8_fp8 v[6:9], v[140:141], v[74:75], 0
	v_mfma_f32_16x16x32_fp8_fp8 v[2:5], v[134:135], v[76:77], v[2:5]
	v_mov_b32_e32 v205, v208
	v_mfma_f32_16x16x32_fp8_fp8 v[6:9], v[142:143], v[76:77], v[6:9]
	v_mfma_f32_16x16x32_fp8_fp8 v[2:5], v[136:137], v[78:79], v[2:5]
	v_mfma_f32_16x16x32_fp8_fp8 v[6:9], v[144:145], v[78:79], v[6:9]
	v_mov_b32_e32 v206, v207
	v_mfma_f32_16x16x32_fp8_fp8 v[2:5], v[138:139], v[80:81], v[2:5]
	v_mfma_f32_16x16x32_fp8_fp8 v[6:9], v[146:147], v[80:81], v[6:9]
	s_nop 6
	v_max_f32_e32 v0, v3, v3
	v_max_f32_e32 v10, v2, v2
	v_max_f32_e32 v0, v10, v0
	v_max_f32_e32 v10, v5, v5
	v_max_f32_e32 v11, v4, v4
	v_max_f32_e32 v10, v11, v10
	v_max_f32_e32 v11, v9, v9
	v_max_f32_e32 v12, v8, v8
	v_max_f32_e32 v11, v12, v11
	v_max3_f32 v11, v6, v7, v11
	v_max3_f32 v0, v0, v10, v11
	v_add_f32_e32 v10, 4.0, v208
	v_cmp_gt_f32_e32 vcc, v0, v10
	s_cbranch_vccz .LBB0_747
	v_and_b32_e32 v11, 64, v200
	v_xor_b32_e32 v10, 16, v200
	v_add_u32_e32 v11, 64, v11
	v_cmp_lt_i32_e32 vcc, v10, v11
	v_xor_b32_e32 v12, 32, v200
	s_nop 0
	v_cndmask_b32_e32 v10, v200, v10, vcc
	v_lshlrev_b32_e32 v10, 2, v10
	ds_bpermute_b32 v10, v10, v0
	v_max_f32_e32 v0, v0, v0
	v_cmp_lt_i32_e32 vcc, v12, v11
	s_waitcnt lgkmcnt(0)
	v_max_f32_e32 v10, v10, v10
	v_max_f32_e32 v0, v0, v10
	v_cndmask_b32_e32 v10, v200, v12, vcc
	v_lshlrev_b32_e32 v10, 2, v10
	ds_bpermute_b32 v10, v10, v0
	s_waitcnt lgkmcnt(0)
	v_max3_f32 v205, v208, v0, v10
	v_sub_f32_e32 v0, v208, v205
	v_exp_f32_e32 v0, v0
	s_nop 0
	v_mul_f32_e32 v206, v207, v0
	v_pk_mul_f32 v[36:37], v[36:37], v[0:1] op_sel_hi:[1,0]
	v_pk_mul_f32 v[34:35], v[34:35], v[0:1] op_sel_hi:[1,0]
	v_pk_mul_f32 v[40:41], v[40:41], v[0:1] op_sel_hi:[1,0]
	v_pk_mul_f32 v[38:39], v[38:39], v[0:1] op_sel_hi:[1,0]
	v_pk_mul_f32 v[44:45], v[44:45], v[0:1] op_sel_hi:[1,0]
	v_pk_mul_f32 v[42:43], v[42:43], v[0:1] op_sel_hi:[1,0]
	v_pk_mul_f32 v[56:57], v[56:57], v[0:1] op_sel_hi:[1,0]
	v_pk_mul_f32 v[54:55], v[54:55], v[0:1] op_sel_hi:[1,0]
	v_pk_mul_f32 v[64:65], v[64:65], v[0:1] op_sel_hi:[1,0]
	v_pk_mul_f32 v[62:63], v[62:63], v[0:1] op_sel_hi:[1,0]
	v_pk_mul_f32 v[60:61], v[60:61], v[0:1] op_sel_hi:[1,0]
	v_pk_mul_f32 v[58:59], v[58:59], v[0:1] op_sel_hi:[1,0]
	v_pk_mul_f32 v[52:53], v[52:53], v[0:1] op_sel_hi:[1,0]
	v_pk_mul_f32 v[50:51], v[50:51], v[0:1] op_sel_hi:[1,0]
	v_pk_mul_f32 v[48:49], v[48:49], v[0:1] op_sel_hi:[1,0]
	v_pk_mul_f32 v[46:47], v[46:47], v[0:1] op_sel_hi:[1,0]
.LBB0_747:
	v_add_f32_e32 v209, -4.0, v205
	v_sub_f32_e32 v0, v2, v209
	v_exp_f32_e32 v211, v0
	v_sub_f32_e32 v0, v6, v209
	v_exp_f32_e32 v213, v0
	v_sub_f32_e32 v0, v3, v209
	v_exp_f32_e32 v210, v0
	v_sub_f32_e32 v0, v7, v209
	v_exp_f32_e32 v0, v0
	v_sub_f32_e32 v2, v4, v209
	v_exp_f32_e32 v215, v2
	v_sub_f32_e32 v2, v8, v209
	v_exp_f32_e32 v218, v2
	v_sub_f32_e32 v2, v5, v209
	v_exp_f32_e32 v212, v2
	v_sub_f32_e32 v2, v9, v209
	v_mov_b32_e32 v216, v1
	v_mov_b32_e32 v217, v1
	v_exp_f32_e32 v214, v2
	v_cvt_pk_fp8_f32 v216, v211, v210
	v_cvt_pk_fp8_f32 v217, v213, v0
	v_add_f32_e32 v211, v211, v213
	v_add_f32_e32 v213, v215, v218
	v_cvt_pk_fp8_f32 v216, v215, v212 op_sel:[0,0,1]
	v_cvt_pk_fp8_f32 v217, v218, v214 op_sel:[0,0,1]
	s_nop 0
	s_waitcnt vmcnt(19)
	v_mfma_f32_16x16x32_fp8_fp8 v[2:5], v[86:87], v[216:217], v[34:37]
	v_mfma_f32_16x16x32_fp8_fp8 v[10:13], v[90:91], v[216:217], v[42:45]
	s_waitcnt vmcnt(18)
	v_mfma_f32_16x16x32_fp8_fp8 v[18:21], v[94:95], v[216:217], v[62:65]
	s_nop 2
	v_add_f32_e64 v26, v210, v0
	v_add_f32_e64 v27, v211, v1
	v_mfma_f32_16x16x32_fp8_fp8 v[6:9], v[88:89], v[216:217], v[38:41]
	v_pk_add_f32 v[26:27], v[26:27], v[26:27] op_sel_hi:[0,1]
	v_mov_b32_e32 v215, v27
	v_pk_add_f32 v[26:27], v[212:213], v[214:215]
	s_waitcnt vmcnt(17)
	v_mfma_f32_16x16x32_fp8_fp8 v[14:17], v[92:93], v[216:217], v[54:57]
	v_add_f32_e32 v0, v26, v27
	v_add_f32_e32 v206, v0, v206
	v_mfma_f32_16x16x32_fp8_fp8 v[22:25], v[96:97], v[216:217], v[58:61]
	s_waitcnt vmcnt(16)
	v_mfma_f32_16x16x32_fp8_fp8 v[30:33], v[112:113], v[216:217], v[50:53]
	v_mfma_f32_16x16x32_fp8_fp8 v[26:29], v[114:115], v[216:217], v[46:49]
	s_nop 1
	s_branch .LBB0_741

; template <bool SLC, bool NOMASK> ...
;     const int kq = lane >> 4;
;     const int pos0 = SLC ? (dcur & 0xfffff) : dcur;
;     const int lo = SLC ? ((((dcur >> 20) == qi) | ((dcur >> 20) == 4)) ? 0 : (1 << 30)) : lo_in;
;     load_frag8(nxt, KF, VF, SLC ? (dnext & 0xfffff) : dnext, lane);
;     f32x4 sa[2] = {(f32x4){0.f, 0.f, 0.f, 0.f}, (f32x4){0.f, 0.f, 0.f, 0.f}};
; #pragma unroll
;     for (int T = 0; T < 2; ++T)
; #pragma unroll
;         for (int s2 = 0; s2 < 4; ++s2) sa[T] = __builtin_amdgcn_mfma_f32_16x16x32_fp8_fp8(cur.k[T][s2], qf[s2], sa[T], 0, 0, 0);
;     float sc[8]; bool vd[8]; float mx = -1e30f;
;     const bool act = lo == 0 || !SLC;
;     if (NOMASK) {
; #pragma unroll
;         for (int j = 0; j < 8; ++j) { sc[j] = sa[j >> 2][j & 3]; vd[j] = act; }
;         mx = fmaxf(fmaxf(fmaxf(sc[0], sc[1]), fmaxf(sc[2], sc[3])), fmaxf(fmaxf(sc[4], sc[5]), fmaxf(sc[6], sc[7])));
;         mx = act ? mx : -1e30f;
;     } else {
; #pragma unroll
;         for (int T = 0; T < 2; ++T)
; #pragma unroll
;             for (int r = 0; r < 4; ++r) { const int p = pos0 + 16 * T + 4 * kq + r; const bool v = (p >= lo) & (p <= hi); const float x = sa[T][r];
;                 sc[4 * T + r] = x; vd[4 * T + r] = v; mx = v ? fmaxf(mx, x) : mx; }
;     }
;     if (__builtin_amdgcn_ballot_w64(mx > st.m + 4.f) != 0ull) {
;         mx = fmaxf(mx, __shfl_xor(mx, 16)); mx = fmaxf(mx, __shfl_xor(mx, 32));
;         const float mn = fmaxf(st.m, mx), alpha = __builtin_amdgcn_exp2f(st.m - mn); st.m = mn; st.l *= alpha;
; #pragma unroll
;         for (int j = 0; j < 8; ++j) st.o[j] = st.o[j] * alpha;
;     }
;     f32x4 pa, pb; float ps = 0.f;
;     const float mref = st.m - 4.f;
;     if (NOMASK) {
; #pragma unroll
;         for (int j = 0; j < 4; ++j) { pa[j] = __builtin_amdgcn_exp2f(sc[j] - mref); pb[j] = __builtin_amdgcn_exp2f(sc[4 + j] - mref); }
;         if (SLC) {
; #pragma unroll
;             for (int j = 0; j < 4; ++j) { pa[j] = act ? pa[j] : 0.f; pb[j] = act ? pb[j] : 0.f; }
;         }
; #pragma unroll
;         for (int j = 0; j < 4; ++j) ps += pa[j] + pb[j];
;     } else {
; #pragma unroll
;         for (int j = 0; j < 4; ++j) { pa[j] = vd[j] ? __builtin_amdgcn_exp2f(sc[j] - mref) : 0.f; pb[j] = vd[4 + j] ? __builtin_amdgcn_exp2f(sc[4 + j] - mref) : 0.f; ps += pa[j] + pb[j]; }
;     }
;     st.l += ps;
;     const u32x2 pw = pack8_fp8(pa, pb);
.LBB0_752:
	v_lshl_add_u64 v[244:245], v[198:199], 0, v[98:99]
	global_load_dwordx4 v[132:135], v[244:245], off
	global_load_dwordx4 v[136:139], v[244:245], off offset:1024
	global_load_dwordx4 v[140:143], v[244:245], off offset:2048
	global_load_dwordx4 v[144:147], v[244:245], off offset:3072
	v_lshl_add_u64 v[246:247], v[196:197], 0, v[98:99]
	global_load_dwordx4 v[86:89], v[246:247], off
	global_load_dwordx4 v[90:93], v[246:247], off offset:1024
	global_load_dwordx4 v[94:97], v[246:247], off offset:2048
	global_load_dwordx4 v[112:115], v[246:247], off offset:3072
	s_waitcnt vmcnt(20)
	v_mfma_f32_16x16x32_fp8_fp8 v[34:37], v[148:149], v[74:75], 0
	v_mfma_f32_16x16x32_fp8_fp8 v[38:41], v[156:157], v[74:75], 0
	v_mfma_f32_16x16x32_fp8_fp8 v[34:37], v[150:151], v[76:77], v[34:37]
	v_mov_b32_e32 v207, v205
	v_mfma_f32_16x16x32_fp8_fp8 v[38:41], v[158:159], v[76:77], v[38:41]
	v_mfma_f32_16x16x32_fp8_fp8 v[34:37], v[152:153], v[78:79], v[34:37]
	v_mfma_f32_16x16x32_fp8_fp8 v[38:41], v[160:161], v[78:79], v[38:41]
	v_mov_b32_e32 v208, v206
	v_mfma_f32_16x16x32_fp8_fp8 v[34:37], v[154:155], v[80:81], v[34:37]
	v_mfma_f32_16x16x32_fp8_fp8 v[38:41], v[162:163], v[80:81], v[38:41]
	s_nop 6
	v_max_f32_e32 v0, v35, v35
	v_max_f32_e32 v42, v34, v34
	v_max_f32_e32 v0, v42, v0
	v_max_f32_e32 v42, v37, v37
	v_max_f32_e32 v43, v36, v36
	v_max_f32_e32 v42, v43, v42
	v_max_f32_e32 v43, v41, v41
	v_max_f32_e32 v44, v40, v40
	v_max_f32_e32 v43, v44, v43
	v_max3_f32 v43, v38, v39, v43
	v_max3_f32 v0, v0, v42, v43
	v_add_f32_e32 v42, 4.0, v205
	v_cmp_gt_f32_e32 vcc, v0, v42
	s_cbranch_vccz .LBB0_754
	v_and_b32_e32 v43, 64, v200
	v_xor_b32_e32 v42, 16, v200
	v_add_u32_e32 v43, 64, v43
	v_cmp_lt_i32_e32 vcc, v42, v43
	v_xor_b32_e32 v44, 32, v200
	s_nop 0
	v_cndmask_b32_e32 v42, v200, v42, vcc
	v_lshlrev_b32_e32 v42, 2, v42
	ds_bpermute_b32 v42, v42, v0
	v_max_f32_e32 v0, v0, v0
	v_cmp_lt_i32_e32 vcc, v44, v43
	s_waitcnt lgkmcnt(0)
	v_max_f32_e32 v42, v42, v42
	v_max_f32_e32 v0, v0, v42
	v_cndmask_b32_e32 v42, v200, v44, vcc
	v_lshlrev_b32_e32 v42, 2, v42
	ds_bpermute_b32 v42, v42, v0
	s_waitcnt lgkmcnt(0)
	v_max3_f32 v207, v205, v0, v42
	v_sub_f32_e32 v0, v205, v207
	v_exp_f32_e32 v0, v0
	s_nop 0
	v_mul_f32_e32 v208, v206, v0
	v_pk_mul_f32 v[4:5], v[4:5], v[0:1] op_sel_hi:[1,0]
	v_pk_mul_f32 v[2:3], v[2:3], v[0:1] op_sel_hi:[1,0]
	v_pk_mul_f32 v[8:9], v[8:9], v[0:1] op_sel_hi:[1,0]
	v_pk_mul_f32 v[6:7], v[6:7], v[0:1] op_sel_hi:[1,0]
	v_pk_mul_f32 v[12:13], v[12:13], v[0:1] op_sel_hi:[1,0]
	v_pk_mul_f32 v[10:11], v[10:11], v[0:1] op_sel_hi:[1,0]
	v_pk_mul_f32 v[16:17], v[16:17], v[0:1] op_sel_hi:[1,0]
	v_pk_mul_f32 v[14:15], v[14:15], v[0:1] op_sel_hi:[1,0]
	v_pk_mul_f32 v[20:21], v[20:21], v[0:1] op_sel_hi:[1,0]
	v_pk_mul_f32 v[18:19], v[18:19], v[0:1] op_sel_hi:[1,0]
	v_pk_mul_f32 v[24:25], v[24:25], v[0:1] op_sel_hi:[1,0]
	v_pk_mul_f32 v[22:23], v[22:23], v[0:1] op_sel_hi:[1,0]
	v_pk_mul_f32 v[32:33], v[32:33], v[0:1] op_sel_hi:[1,0]
	v_pk_mul_f32 v[30:31], v[30:31], v[0:1] op_sel_hi:[1,0]
	v_pk_mul_f32 v[28:29], v[28:29], v[0:1] op_sel_hi:[1,0]
	v_pk_mul_f32 v[26:27], v[26:27], v[0:1] op_sel_hi:[1,0]
.LBB0_754:
	v_add_f32_e32 v209, -4.0, v207
	v_sub_f32_e32 v0, v34, v209
	v_exp_f32_e32 v211, v0
	v_sub_f32_e32 v0, v38, v209
	v_exp_f32_e32 v213, v0
	v_sub_f32_e32 v0, v35, v209
	v_exp_f32_e32 v210, v0
	v_sub_f32_e32 v0, v39, v209
	v_exp_f32_e32 v0, v0
	v_sub_f32_e32 v34, v36, v209
	v_exp_f32_e32 v215, v34
	v_sub_f32_e32 v34, v40, v209
	v_exp_f32_e32 v218, v34
	v_sub_f32_e32 v34, v37, v209
	v_exp_f32_e32 v212, v34
	v_sub_f32_e32 v34, v41, v209
	v_mov_b32_e32 v216, v1
	v_mov_b32_e32 v217, v1
	v_exp_f32_e32 v214, v34
	v_cvt_pk_fp8_f32 v216, v211, v210
	v_cvt_pk_fp8_f32 v217, v213, v0
	v_add_f32_e32 v211, v211, v213
	v_add_f32_e32 v213, v215, v218
	v_cvt_pk_fp8_f32 v216, v215, v212 op_sel:[0,0,1]
	v_cvt_pk_fp8_f32 v217, v218, v214 op_sel:[0,0,1]
	s_nop 0
	s_waitcnt vmcnt(19)
	v_mfma_f32_16x16x32_fp8_fp8 v[34:37], v[116:117], v[216:217], v[2:5]
	v_mfma_f32_16x16x32_fp8_fp8 v[42:45], v[120:121], v[216:217], v[10:13]
	s_waitcnt vmcnt(18)
	v_mfma_f32_16x16x32_fp8_fp8 v[50:53], v[124:125], v[216:217], v[18:21]
	s_nop 2
	v_add_f32_e64 v58, v210, v0
	v_add_f32_e64 v59, v211, v1
	v_mfma_f32_16x16x32_fp8_fp8 v[38:41], v[118:119], v[216:217], v[6:9]
	v_pk_add_f32 v[58:59], v[58:59], v[58:59] op_sel_hi:[0,1]
	v_mov_b32_e32 v215, v59
	s_waitcnt vmcnt(17)
	v_mfma_f32_16x16x32_fp8_fp8 v[46:49], v[122:123], v[216:217], v[14:17]
	v_mfma_f32_16x16x32_fp8_fp8 v[54:57], v[126:127], v[216:217], v[22:25]
	s_nop 2
	v_add_f32_e64 v62, v212, v214
	v_add_f32_e64 v63, v213, v215
	s_waitcnt vmcnt(16)
	v_mfma_f32_16x16x32_fp8_fp8 v[58:61], v[128:129], v[216:217], v[30:33]
	v_add_f32_e32 v0, v62, v63
	v_add_f32_e32 v208, v0, v208
	v_mfma_f32_16x16x32_fp8_fp8 v[62:65], v[130:131], v[216:217], v[26:29]
	s_nop 1
	s_branch .LBB0_744

; template <bool SLC, bool NOMASK> ...
;     const int kq = lane >> 4;
;     const int pos0 = SLC ? (dcur & 0xfffff) : dcur;
;     const int lo = SLC ? ((((dcur >> 20) == qi) | ((dcur >> 20) == 4)) ? 0 : (1 << 30)) : lo_in;
;     load_frag8(nxt, KF, VF, SLC ? (dnext & 0xfffff) : dnext, lane);
;     f32x4 sa[2] = {(f32x4){0.f, 0.f, 0.f, 0.f}, (f32x4){0.f, 0.f, 0.f, 0.f}};
; #pragma unroll
;     for (int T = 0; T < 2; ++T)
; #pragma unroll
;         for (int s2 = 0; s2 < 4; ++s2) sa[T] = __builtin_amdgcn_mfma_f32_16x16x32_fp8_fp8(cur.k[T][s2], qf[s2], sa[T], 0, 0, 0);
;     float sc[8]; bool vd[8]; float mx = -1e30f;
;     const bool act = lo == 0 || !SLC;
;     if (NOMASK) {
; #pragma unroll
;         for (int j = 0; j < 8; ++j) { sc[j] = sa[j >> 2][j & 3]; vd[j] = act; }
;         mx = fmaxf(fmaxf(fmaxf(sc[0], sc[1]), fmaxf(sc[2], sc[3])), fmaxf(fmaxf(sc[4], sc[5]), fmaxf(sc[6], sc[7])));
;         mx = act ? mx : -1e30f;
;     } else {
; #pragma unroll
;         for (int T = 0; T < 2; ++T)
; #pragma unroll
;             for (int r = 0; r < 4; ++r) { const int p = pos0 + 16 * T + 4 * kq + r; const bool v = (p >= lo) & (p <= hi); const float x = sa[T][r];
;                 sc[4 * T + r] = x; vd[4 * T + r] = v; mx = v ? fmaxf(mx, x) : mx; }
;     }
;     if (__builtin_amdgcn_ballot_w64(mx > st.m + 4.f) != 0ull) {
;         mx = fmaxf(mx, __shfl_xor(mx, 16)); mx = fmaxf(mx, __shfl_xor(mx, 32));
;         const float mn = fmaxf(st.m, mx), alpha = __builtin_amdgcn_exp2f(st.m - mn); st.m = mn; st.l *= alpha;
; #pragma unroll
;         for (int j = 0; j < 8; ++j) st.o[j] = st.o[j] * alpha;
;     }
;     f32x4 pa, pb; float ps = 0.f;
;     const float mref = st.m - 4.f;
;     if (NOMASK) {
; #pragma unroll
;         for (int j = 0; j < 4; ++j) { pa[j] = __builtin_amdgcn_exp2f(sc[j] - mref); pb[j] = __builtin_amdgcn_exp2f(sc[4 + j] - mref); }
;         if (SLC) {
; #pragma unroll
;             for (int j = 0; j < 4; ++j) { pa[j] = act ? pa[j] : 0.f; pb[j] = act ? pb[j] : 0.f; }
;         }
; #pragma unroll
;         for (int j = 0; j < 4; ++j) ps += pa[j] + pb[j];
;     } else {
; #pragma unroll
;         for (int j = 0; j < 4; ++j) { pa[j] = vd[j] ? __builtin_amdgcn_exp2f(sc[j] - mref) : 0.f; pb[j] = vd[4 + j] ? __builtin_amdgcn_exp2f(sc[4 + j] - mref) : 0.f; ps += pa[j] + pb[j]; }
;     }
;     st.l += ps;
;     const u32x2 pw = pack8_fp8(pa, pb);
.LBB0_758:
	s_add_i32 s66, s66, 4
	s_min_i32 s4, s66, s61
	s_add_i32 s6, s4, s60
	s_lshl_b32 s63, s6, 5
	s_and_b32 s4, s63, 0x3fffffe0
	s_lshr_b32 s24, s4, 4
	s_lshl_b64 s[4:5], s[24:25], 11
	s_and_b32 s24, s6, 0x1ffffff
	s_and_b32 s8, s42, 0x2000000
	s_lshl_b64 s[6:7], s[24:25], 12
	s_cmp_eq_u32 s8, 0
	v_lshl_add_u64 v[198:199], v[82:83], 0, s[4:5]
	v_lshl_add_u64 v[196:197], v[84:85], 0, s[6:7]
	s_mov_b64 s[4:5], -1
	v_add_f32_e32 v209, 4.0, v207
	s_cbranch_scc1 .LBB0_762
	v_lshl_add_u64 v[244:245], v[198:199], 0, v[98:99]
	global_load_dwordx4 v[148:151], v[244:245], off
	global_load_dwordx4 v[152:155], v[244:245], off offset:1024
	global_load_dwordx4 v[156:159], v[244:245], off offset:2048
	global_load_dwordx4 v[160:163], v[244:245], off offset:3072
	v_lshl_add_u64 v[246:247], v[196:197], 0, v[98:99]
	global_load_dwordx4 v[116:119], v[246:247], off
	global_load_dwordx4 v[120:123], v[246:247], off offset:1024
	global_load_dwordx4 v[124:127], v[246:247], off offset:2048
	global_load_dwordx4 v[128:131], v[246:247], off offset:3072
	s_waitcnt vmcnt(20)
	v_mfma_f32_16x16x32_fp8_fp8 v[2:5], v[180:181], v[74:75], 0
	v_mfma_f32_16x16x32_fp8_fp8 v[6:9], v[188:189], v[74:75], 0
	v_mfma_f32_16x16x32_fp8_fp8 v[2:5], v[182:183], v[76:77], v[2:5]
	v_mov_b32_e32 v205, v207
	v_mfma_f32_16x16x32_fp8_fp8 v[6:9], v[190:191], v[76:77], v[6:9]
	v_mfma_f32_16x16x32_fp8_fp8 v[2:5], v[184:185], v[78:79], v[2:5]
	v_mfma_f32_16x16x32_fp8_fp8 v[6:9], v[192:193], v[78:79], v[6:9]
	v_mov_b32_e32 v206, v208
	v_mfma_f32_16x16x32_fp8_fp8 v[2:5], v[186:187], v[80:81], v[2:5]
	v_mfma_f32_16x16x32_fp8_fp8 v[6:9], v[194:195], v[80:81], v[6:9]
	s_nop 6
	v_max_f32_e32 v0, v3, v3
	v_max_f32_e32 v10, v2, v2
	v_max_f32_e32 v0, v10, v0
	v_max_f32_e32 v10, v5, v5
	v_max_f32_e32 v11, v4, v4
	v_max_f32_e32 v10, v11, v10
	v_max_f32_e32 v11, v9, v9
	v_max_f32_e32 v12, v8, v8
	v_max_f32_e32 v11, v12, v11
	v_max3_f32 v11, v6, v7, v11
	v_max3_f32 v0, v0, v10, v11
	v_cmp_gt_f32_e32 vcc, v0, v209
	s_cbranch_vccz .LBB0_761
	v_and_b32_e32 v11, 64, v200
	v_xor_b32_e32 v10, 16, v200
	v_add_u32_e32 v11, 64, v11
	v_cmp_lt_i32_e32 vcc, v10, v11
	v_xor_b32_e32 v12, 32, v200
	s_nop 0
	v_cndmask_b32_e32 v10, v200, v10, vcc
	v_lshlrev_b32_e32 v10, 2, v10
	ds_bpermute_b32 v10, v10, v0
	v_max_f32_e32 v0, v0, v0
	v_cmp_lt_i32_e32 vcc, v12, v11
	s_waitcnt lgkmcnt(0)
	v_max_f32_e32 v10, v10, v10
	v_max_f32_e32 v0, v0, v10
	v_cndmask_b32_e32 v10, v200, v12, vcc
	v_lshlrev_b32_e32 v10, 2, v10
	ds_bpermute_b32 v10, v10, v0
	s_waitcnt lgkmcnt(0)
	v_max3_f32 v205, v207, v0, v10
	v_sub_f32_e32 v0, v207, v205
	v_exp_f32_e32 v0, v0
	s_nop 0
	v_mul_f32_e32 v206, v208, v0
	v_pk_mul_f32 v[36:37], v[36:37], v[0:1] op_sel_hi:[1,0]
	v_pk_mul_f32 v[34:35], v[34:35], v[0:1] op_sel_hi:[1,0]
	v_pk_mul_f32 v[40:41], v[40:41], v[0:1] op_sel_hi:[1,0]
	v_pk_mul_f32 v[38:39], v[38:39], v[0:1] op_sel_hi:[1,0]
	v_pk_mul_f32 v[44:45], v[44:45], v[0:1] op_sel_hi:[1,0]
	v_pk_mul_f32 v[42:43], v[42:43], v[0:1] op_sel_hi:[1,0]
	v_pk_mul_f32 v[48:49], v[48:49], v[0:1] op_sel_hi:[1,0]
	v_pk_mul_f32 v[46:47], v[46:47], v[0:1] op_sel_hi:[1,0]
	v_pk_mul_f32 v[52:53], v[52:53], v[0:1] op_sel_hi:[1,0]
	v_pk_mul_f32 v[50:51], v[50:51], v[0:1] op_sel_hi:[1,0]
	v_pk_mul_f32 v[56:57], v[56:57], v[0:1] op_sel_hi:[1,0]
	v_pk_mul_f32 v[54:55], v[54:55], v[0:1] op_sel_hi:[1,0]
	v_pk_mul_f32 v[60:61], v[60:61], v[0:1] op_sel_hi:[1,0]
	v_pk_mul_f32 v[58:59], v[58:59], v[0:1] op_sel_hi:[1,0]
	v_pk_mul_f32 v[64:65], v[64:65], v[0:1] op_sel_hi:[1,0]
	v_pk_mul_f32 v[62:63], v[62:63], v[0:1] op_sel_hi:[1,0]
.LBB0_761:
	v_add_f32_e32 v211, -4.0, v205
	v_sub_f32_e32 v0, v2, v211
	v_exp_f32_e32 v213, v0
	v_sub_f32_e32 v0, v6, v211
	v_exp_f32_e32 v215, v0
	v_sub_f32_e32 v0, v3, v211
	v_exp_f32_e32 v210, v0
	v_sub_f32_e32 v0, v7, v211
	v_exp_f32_e32 v0, v0
	v_sub_f32_e32 v2, v4, v211
	v_exp_f32_e32 v218, v2
	v_sub_f32_e32 v2, v8, v211
	v_exp_f32_e32 v219, v2
	v_sub_f32_e32 v2, v5, v211
	v_exp_f32_e32 v212, v2
	v_sub_f32_e32 v2, v9, v211
	v_mov_b32_e32 v216, v1
	v_mov_b32_e32 v217, v1
	v_exp_f32_e32 v214, v2
	v_cvt_pk_fp8_f32 v216, v213, v210
	v_cvt_pk_fp8_f32 v217, v215, v0
	v_add_f32_e32 v211, v213, v215
	v_add_f32_e32 v213, v218, v219
	v_cvt_pk_fp8_f32 v216, v218, v212 op_sel:[0,0,1]
	v_cvt_pk_fp8_f32 v217, v219, v214 op_sel:[0,0,1]
	s_mov_b64 s[4:5], 0
	s_waitcnt vmcnt(19)
	v_mfma_f32_16x16x32_fp8_fp8 v[2:5], v[164:165], v[216:217], v[34:37]
	v_mfma_f32_16x16x32_fp8_fp8 v[10:13], v[168:169], v[216:217], v[42:45]
	s_waitcnt vmcnt(18)
	v_mfma_f32_16x16x32_fp8_fp8 v[18:21], v[172:173], v[216:217], v[50:53]
	s_nop 2
	v_add_f32_e64 v26, v210, v0
	v_add_f32_e64 v27, v211, v1
	v_mfma_f32_16x16x32_fp8_fp8 v[6:9], v[166:167], v[216:217], v[38:41]
	v_pk_add_f32 v[26:27], v[26:27], v[26:27] op_sel_hi:[0,1]
	v_mov_b32_e32 v215, v27
	v_pk_add_f32 v[26:27], v[212:213], v[214:215]
	s_waitcnt vmcnt(17)
	v_mfma_f32_16x16x32_fp8_fp8 v[14:17], v[170:171], v[216:217], v[46:49]
	v_add_f32_e32 v0, v26, v27
	v_add_f32_e32 v206, v0, v206
	v_mfma_f32_16x16x32_fp8_fp8 v[22:25], v[174:175], v[216:217], v[54:57]
	s_waitcnt vmcnt(16)
	v_mfma_f32_16x16x32_fp8_fp8 v[30:33], v[176:177], v[216:217], v[58:61]
	v_mfma_f32_16x16x32_fp8_fp8 v[26:29], v[178:179], v[216:217], v[62:65]
	s_nop 1

; template <bool SLC, bool NOMASK> ...
;     const int kq = lane >> 4;
;     const int pos0 = SLC ? (dcur & 0xfffff) : dcur;
;     const int lo = SLC ? ((((dcur >> 20) == qi) | ((dcur >> 20) == 4)) ? 0 : (1 << 30)) : lo_in;
;     load_frag8(nxt, KF, VF, SLC ? (dnext & 0xfffff) : dnext, lane);
;     f32x4 sa[2] = {(f32x4){0.f, 0.f, 0.f, 0.f}, (f32x4){0.f, 0.f, 0.f, 0.f}};
; #pragma unroll
;     for (int T = 0; T < 2; ++T)
; #pragma unroll
;         for (int s2 = 0; s2 < 4; ++s2) sa[T] = __builtin_amdgcn_mfma_f32_16x16x32_fp8_fp8(cur.k[T][s2], qf[s2], sa[T], 0, 0, 0);
;     float sc[8]; bool vd[8]; float mx = -1e30f;
;     const bool act = lo == 0 || !SLC;
;     if (NOMASK) {
; #pragma unroll
;         for (int j = 0; j < 8; ++j) { sc[j] = sa[j >> 2][j & 3]; vd[j] = act; }
;         mx = fmaxf(fmaxf(fmaxf(sc[0], sc[1]), fmaxf(sc[2], sc[3])), fmaxf(fmaxf(sc[4], sc[5]), fmaxf(sc[6], sc[7])));
;         mx = act ? mx : -1e30f;
;     } else {
; #pragma unroll
;         for (int T = 0; T < 2; ++T)
; #pragma unroll
;             for (int r = 0; r < 4; ++r) { const int p = pos0 + 16 * T + 4 * kq + r; const bool v = (p >= lo) & (p <= hi); const float x = sa[T][r];
;                 sc[4 * T + r] = x; vd[4 * T + r] = v; mx = v ? fmaxf(mx, x) : mx; }
;     }
;     if (__builtin_amdgcn_ballot_w64(mx > st.m + 4.f) != 0ull) {
;         mx = fmaxf(mx, __shfl_xor(mx, 16)); mx = fmaxf(mx, __shfl_xor(mx, 32));
;         const float mn = fmaxf(st.m, mx), alpha = __builtin_amdgcn_exp2f(st.m - mn); st.m = mn; st.l *= alpha;
; #pragma unroll
;         for (int j = 0; j < 8; ++j) st.o[j] = st.o[j] * alpha;
;     }
;     f32x4 pa, pb; float ps = 0.f;
;     const float mref = st.m - 4.f;
;     if (NOMASK) {
; #pragma unroll
;         for (int j = 0; j < 4; ++j) { pa[j] = __builtin_amdgcn_exp2f(sc[j] - mref); pb[j] = __builtin_amdgcn_exp2f(sc[4 + j] - mref); }
;         if (SLC) {
; #pragma unroll
;             for (int j = 0; j < 4; ++j) { pa[j] = act ? pa[j] : 0.f; pb[j] = act ? pb[j] : 0.f; }
;         }
; #pragma unroll
;         for (int j = 0; j < 4; ++j) ps += pa[j] + pb[j];
;     } else {
; #pragma unroll
;         for (int j = 0; j < 4; ++j) { pa[j] = vd[j] ? __builtin_amdgcn_exp2f(sc[j] - mref) : 0.f; pb[j] = vd[4 + j] ? __builtin_amdgcn_exp2f(sc[4 + j] - mref) : 0.f; ps += pa[j] + pb[j]; }
;     }
;     st.l += ps;
;     const u32x2 pw = pack8_fp8(pa, pb);
.LBB0_867:
	s_and_b32 s13, s12, 0xfffffbff
	s_cmp_eq_u32 s13, 4
	s_cselect_b64 s[10:11], -1, 0
	s_lshl_b32 s14, s66, 7
	s_and_b32 s50, s14, 0x7fff800
	v_lshl_add_u64 v[10:11], v[86:87], 0, s[50:51]
	s_and_b32 s50, s14, 0x7fff000
	v_lshl_add_u64 v[244:245], v[10:11], 0, v[118:119]
	global_load_dwordx4 v[186:189], v[244:245], off
	global_load_dwordx4 v[190:193], v[244:245], off offset:1024
	global_load_dwordx4 v[194:197], v[244:245], off offset:2048
	global_load_dwordx4 v[198:201], v[244:245], off offset:3072
	v_lshl_add_u64 v[10:11], v[88:89], 0, s[50:51]
	v_lshl_add_u64 v[246:247], v[10:11], 0, v[118:119]
	global_load_dwordx4 v[170:173], v[246:247], off
	global_load_dwordx4 v[174:177], v[246:247], off offset:1024
	global_load_dwordx4 v[178:181], v[246:247], off offset:2048
	global_load_dwordx4 v[182:185], v[246:247], off offset:3072
	s_waitcnt vmcnt(20)
	v_mfma_f32_16x16x32_fp8_fp8 v[2:5], v[138:139], v[78:79], 0
	v_cmp_eq_u32_e32 vcc, s13, v209
	s_or_b64 s[10:11], s[10:11], vcc
	v_mfma_f32_16x16x32_fp8_fp8 v[6:9], v[146:147], v[78:79], 0
	v_mfma_f32_16x16x32_fp8_fp8 v[2:5], v[140:141], v[80:81], v[2:5]
	v_mfma_f32_16x16x32_fp8_fp8 v[6:9], v[148:149], v[80:81], v[6:9]
	v_mfma_f32_16x16x32_fp8_fp8 v[2:5], v[142:143], v[82:83], v[2:5]
	v_mfma_f32_16x16x32_fp8_fp8 v[6:9], v[150:151], v[82:83], v[6:9]
	v_mov_b32_e32 v133, v203
	v_mfma_f32_16x16x32_fp8_fp8 v[2:5], v[144:145], v[84:85], v[2:5]
	v_mfma_f32_16x16x32_fp8_fp8 v[6:9], v[152:153], v[84:85], v[6:9]
	s_nop 6
	v_max_f32_e32 v0, v3, v3
	v_max_f32_e32 v10, v2, v2
	v_max_f32_e32 v0, v10, v0
	v_max_f32_e32 v10, v5, v5
	v_max_f32_e32 v11, v4, v4
	v_max_f32_e32 v10, v11, v10
	v_max_f32_e32 v11, v9, v9
	v_max_f32_e32 v12, v8, v8
	v_max_f32_e32 v11, v12, v11
	v_max3_f32 v11, v6, v7, v11
	v_max3_f32 v0, v0, v10, v11
	v_cndmask_b32_e64 v34, v223, v0, s[10:11]
	v_cmp_gt_f32_e32 vcc, v34, v204
	v_mov_b32_e32 v0, v202
	s_cbranch_vccz .LBB0_869
	ds_bpermute_b32 v0, v227, v34
	v_max_f32_e32 v10, v34, v34
	s_waitcnt lgkmcnt(0)
	v_max_f32_e32 v0, v0, v0
	v_max_f32_e32 v0, v10, v0
	ds_bpermute_b32 v10, v226, v0
	s_waitcnt lgkmcnt(0)
	v_max3_f32 v0, v202, v0, v10
	v_sub_f32_e32 v10, v202, v0
	v_exp_f32_e32 v34, v10
	s_nop 0
	v_mul_f32_e32 v133, v203, v34
	v_pk_mul_f32 v[66:67], v[66:67], v[34:35] op_sel_hi:[1,0]
	v_pk_mul_f32 v[64:65], v[64:65], v[34:35] op_sel_hi:[1,0]
	v_pk_mul_f32 v[62:63], v[62:63], v[34:35] op_sel_hi:[1,0]
	v_pk_mul_f32 v[60:61], v[60:61], v[34:35] op_sel_hi:[1,0]
	v_pk_mul_f32 v[58:59], v[58:59], v[34:35] op_sel_hi:[1,0]
	v_pk_mul_f32 v[56:57], v[56:57], v[34:35] op_sel_hi:[1,0]
	v_pk_mul_f32 v[54:55], v[54:55], v[34:35] op_sel_hi:[1,0]
	v_pk_mul_f32 v[52:53], v[52:53], v[34:35] op_sel_hi:[1,0]
	v_pk_mul_f32 v[50:51], v[50:51], v[34:35] op_sel_hi:[1,0]
	v_pk_mul_f32 v[48:49], v[48:49], v[34:35] op_sel_hi:[1,0]
	v_pk_mul_f32 v[46:47], v[46:47], v[34:35] op_sel_hi:[1,0]
	v_pk_mul_f32 v[44:45], v[44:45], v[34:35] op_sel_hi:[1,0]
	v_pk_mul_f32 v[42:43], v[42:43], v[34:35] op_sel_hi:[1,0]
	v_pk_mul_f32 v[40:41], v[40:41], v[34:35] op_sel_hi:[1,0]
	v_pk_mul_f32 v[38:39], v[38:39], v[34:35] op_sel_hi:[1,0]
	v_pk_mul_f32 v[36:37], v[36:37], v[34:35] op_sel_hi:[1,0]
.LBB0_869:
	v_add_f32_e32 v34, -4.0, v0
	v_sub_f32_e32 v2, v2, v34
	v_sub_f32_e32 v6, v6, v34
	v_sub_f32_e32 v3, v3, v34
	v_sub_f32_e32 v7, v7, v34
	v_exp_f32_e32 v2, v2
	v_exp_f32_e32 v6, v6
	v_exp_f32_e32 v3, v3
	v_exp_f32_e32 v7, v7
	v_sub_f32_e32 v4, v4, v34
	v_sub_f32_e32 v8, v8, v34
	v_sub_f32_e32 v5, v5, v34
	v_sub_f32_e32 v9, v9, v34
	v_exp_f32_e32 v4, v4
	v_exp_f32_e32 v8, v8
	v_exp_f32_e32 v5, v5
	v_exp_f32_e32 v9, v9
	v_cndmask_b32_e64 v34, 0, v2, s[10:11]
	v_cndmask_b32_e64 v6, 0, v6, s[10:11]
	v_cndmask_b32_e64 v35, 0, v3, s[10:11]
	v_cndmask_b32_e64 v7, 0, v7, s[10:11]
	v_mov_b32_e32 v2, v1
	v_mov_b32_e32 v3, v1
	v_cvt_pk_fp8_f32 v2, v34, v35
	v_cvt_pk_fp8_f32 v3, v6, v7
	v_cndmask_b32_e64 v4, 0, v4, s[10:11]
	v_cndmask_b32_e64 v205, 0, v8, s[10:11]
	v_cndmask_b32_e64 v5, 0, v5, s[10:11]
	v_cndmask_b32_e64 v229, 0, v9, s[10:11]
	v_add_f32_e32 v6, v34, v6
	v_cvt_pk_fp8_f32 v2, v4, v5 op_sel:[0,0,1]
	v_cvt_pk_fp8_f32 v3, v205, v229 op_sel:[0,0,1]
	v_add_f32_e32 v6, 0, v6
	v_add_f32_e32 v7, v35, v7
	v_add_f32_e32 v6, v7, v6
	v_add_f32_e32 v4, v4, v205
	v_add_f32_e32 v4, v4, v6
	v_add_f32_e32 v5, v5, v229
	v_add_f32_e32 v4, v5, v4
	s_waitcnt vmcnt(19)
	v_mfma_f32_16x16x32_fp8_fp8 v[8:11], v[90:91], v[2:3], v[64:67]
	v_add_f32_e32 v133, v133, v4
	v_mfma_f32_16x16x32_fp8_fp8 v[12:15], v[92:93], v[2:3], v[60:63]
	s_waitcnt vmcnt(18)
	v_mfma_f32_16x16x32_fp8_fp8 v[16:19], v[94:95], v[2:3], v[56:59]
	v_mfma_f32_16x16x32_fp8_fp8 v[20:23], v[96:97], v[2:3], v[52:55]
	s_waitcnt vmcnt(17)
	v_mfma_f32_16x16x32_fp8_fp8 v[24:27], v[98:99], v[2:3], v[48:51]
	v_mfma_f32_16x16x32_fp8_fp8 v[32:35], v[100:101], v[2:3], v[44:47]
	s_waitcnt vmcnt(16)
	v_mfma_f32_16x16x32_fp8_fp8 v[28:31], v[102:103], v[2:3], v[40:43]
	v_mfma_f32_16x16x32_fp8_fp8 v[4:7], v[104:105], v[2:3], v[36:39]
	s_nop 1
	s_branch .LBB0_863

; template <bool SLC, bool NOMASK> ...
;     const int kq = lane >> 4;
;     const int pos0 = SLC ? (dcur & 0xfffff) : dcur;
;     const int lo = SLC ? ((((dcur >> 20) == qi) | ((dcur >> 20) == 4)) ? 0 : (1 << 30)) : lo_in;
;     load_frag8(nxt, KF, VF, SLC ? (dnext & 0xfffff) : dnext, lane);
;     f32x4 sa[2] = {(f32x4){0.f, 0.f, 0.f, 0.f}, (f32x4){0.f, 0.f, 0.f, 0.f}};
; #pragma unroll
;     for (int T = 0; T < 2; ++T)
; #pragma unroll
;         for (int s2 = 0; s2 < 4; ++s2) sa[T] = __builtin_amdgcn_mfma_f32_16x16x32_fp8_fp8(cur.k[T][s2], qf[s2], sa[T], 0, 0, 0);
;     float sc[8]; bool vd[8]; float mx = -1e30f;
;     const bool act = lo == 0 || !SLC;
;     if (NOMASK) {
; #pragma unroll
;         for (int j = 0; j < 8; ++j) { sc[j] = sa[j >> 2][j & 3]; vd[j] = act; }
;         mx = fmaxf(fmaxf(fmaxf(sc[0], sc[1]), fmaxf(sc[2], sc[3])), fmaxf(fmaxf(sc[4], sc[5]), fmaxf(sc[6], sc[7])));
;         mx = act ? mx : -1e30f;
;     } else {
; #pragma unroll
;         for (int T = 0; T < 2; ++T)
; #pragma unroll
;             for (int r = 0; r < 4; ++r) { const int p = pos0 + 16 * T + 4 * kq + r; const bool v = (p >= lo) & (p <= hi); const float x = sa[T][r];
;                 sc[4 * T + r] = x; vd[4 * T + r] = v; mx = v ? fmaxf(mx, x) : mx; }
;     }
;     if (__builtin_amdgcn_ballot_w64(mx > st.m + 4.f) != 0ull) {
;         mx = fmaxf(mx, __shfl_xor(mx, 16)); mx = fmaxf(mx, __shfl_xor(mx, 32));
;         const float mn = fmaxf(st.m, mx), alpha = __builtin_amdgcn_exp2f(st.m - mn); st.m = mn; st.l *= alpha;
; #pragma unroll
;         for (int j = 0; j < 8; ++j) st.o[j] = st.o[j] * alpha;
;     }
;     f32x4 pa, pb; float ps = 0.f;
;     const float mref = st.m - 4.f;
;     if (NOMASK) {
; #pragma unroll
;         for (int j = 0; j < 4; ++j) { pa[j] = __builtin_amdgcn_exp2f(sc[j] - mref); pb[j] = __builtin_amdgcn_exp2f(sc[4 + j] - mref); }
;         if (SLC) {
; #pragma unroll
;             for (int j = 0; j < 4; ++j) { pa[j] = act ? pa[j] : 0.f; pb[j] = act ? pb[j] : 0.f; }
;         }
; #pragma unroll
;         for (int j = 0; j < 4; ++j) ps += pa[j] + pb[j];
;     } else {
; #pragma unroll
;         for (int j = 0; j < 4; ++j) { pa[j] = vd[j] ? __builtin_amdgcn_exp2f(sc[j] - mref) : 0.f; pb[j] = vd[4 + j] ? __builtin_amdgcn_exp2f(sc[4 + j] - mref) : 0.f; ps += pa[j] + pb[j]; }
;     }
;     st.l += ps;
;     const u32x2 pw = pack8_fp8(pa, pb);
.LBB0_874:
	s_and_b32 s13, s12, 0xfffffbff
	s_cmp_eq_u32 s13, 4
	s_cselect_b64 s[10:11], -1, 0
	s_lshl_b32 s14, s59, 7
	s_and_b32 s50, s14, 0x7fff800
	v_lshl_add_u64 v[44:45], v[86:87], 0, s[50:51]
	s_and_b32 s50, s14, 0x7fff000
	v_lshl_add_u64 v[244:245], v[44:45], 0, v[118:119]
	global_load_dwordx4 v[138:141], v[244:245], off
	global_load_dwordx4 v[142:145], v[244:245], off offset:1024
	global_load_dwordx4 v[146:149], v[244:245], off offset:2048
	global_load_dwordx4 v[150:153], v[244:245], off offset:3072
	v_lshl_add_u64 v[44:45], v[88:89], 0, s[50:51]
	v_lshl_add_u64 v[246:247], v[44:45], 0, v[118:119]
	global_load_dwordx4 v[90:93], v[246:247], off
	global_load_dwordx4 v[94:97], v[246:247], off offset:1024
	global_load_dwordx4 v[98:101], v[246:247], off offset:2048
	global_load_dwordx4 v[102:105], v[246:247], off offset:3072
	s_waitcnt vmcnt(20)
	v_mfma_f32_16x16x32_fp8_fp8 v[36:39], v[154:155], v[78:79], 0
	v_cmp_eq_u32_e32 vcc, s13, v209
	s_or_b64 s[10:11], s[10:11], vcc
	v_mfma_f32_16x16x32_fp8_fp8 v[40:43], v[162:163], v[78:79], 0
	v_mfma_f32_16x16x32_fp8_fp8 v[36:39], v[156:157], v[80:81], v[36:39]
	v_mfma_f32_16x16x32_fp8_fp8 v[40:43], v[164:165], v[80:81], v[40:43]
	v_mov_b32_e32 v203, v0
	v_mfma_f32_16x16x32_fp8_fp8 v[36:39], v[158:159], v[82:83], v[36:39]
	v_mfma_f32_16x16x32_fp8_fp8 v[40:43], v[166:167], v[82:83], v[40:43]
	v_mfma_f32_16x16x32_fp8_fp8 v[36:39], v[160:161], v[84:85], v[36:39]
	v_mfma_f32_16x16x32_fp8_fp8 v[40:43], v[168:169], v[84:85], v[40:43]
	s_nop 6
	v_max_f32_e32 v3, v37, v37
	v_max_f32_e32 v44, v36, v36
	v_max_f32_e32 v3, v44, v3
	v_max_f32_e32 v44, v39, v39
	v_max_f32_e32 v45, v38, v38
	v_max_f32_e32 v44, v45, v44
	v_max_f32_e32 v45, v43, v43
	v_max_f32_e32 v46, v42, v42
	v_max_f32_e32 v45, v46, v45
	v_max3_f32 v45, v40, v41, v45
	v_max3_f32 v3, v3, v44, v45
	v_cndmask_b32_e64 v202, v223, v3, s[10:11]
	v_cmp_gt_f32_e32 vcc, v202, v2
	v_mov_b32_e32 v3, v133
	s_cbranch_vccz .LBB0_876
	ds_bpermute_b32 v3, v227, v202
	v_max_f32_e32 v44, v202, v202
	s_waitcnt lgkmcnt(0)
	v_max_f32_e32 v3, v3, v3
	v_max_f32_e32 v3, v44, v3
	ds_bpermute_b32 v44, v226, v3
	s_waitcnt lgkmcnt(0)
	v_max3_f32 v203, v0, v3, v44
	v_sub_f32_e32 v3, v0, v203
	v_exp_f32_e32 v72, v3
	s_nop 0
	v_mul_f32_e32 v3, v133, v72
	v_pk_mul_f32 v[10:11], v[10:11], v[72:73] op_sel_hi:[1,0]
	v_pk_mul_f32 v[8:9], v[8:9], v[72:73] op_sel_hi:[1,0]
	v_pk_mul_f32 v[14:15], v[14:15], v[72:73] op_sel_hi:[1,0]
	v_pk_mul_f32 v[12:13], v[12:13], v[72:73] op_sel_hi:[1,0]
	v_pk_mul_f32 v[18:19], v[18:19], v[72:73] op_sel_hi:[1,0]
	v_pk_mul_f32 v[16:17], v[16:17], v[72:73] op_sel_hi:[1,0]
	v_pk_mul_f32 v[22:23], v[22:23], v[72:73] op_sel_hi:[1,0]
	v_pk_mul_f32 v[20:21], v[20:21], v[72:73] op_sel_hi:[1,0]
	v_pk_mul_f32 v[26:27], v[26:27], v[72:73] op_sel_hi:[1,0]
	v_pk_mul_f32 v[24:25], v[24:25], v[72:73] op_sel_hi:[1,0]
	v_pk_mul_f32 v[34:35], v[34:35], v[72:73] op_sel_hi:[1,0]
	v_pk_mul_f32 v[32:33], v[32:33], v[72:73] op_sel_hi:[1,0]
	v_pk_mul_f32 v[30:31], v[30:31], v[72:73] op_sel_hi:[1,0]
	v_pk_mul_f32 v[28:29], v[28:29], v[72:73] op_sel_hi:[1,0]
	v_pk_mul_f32 v[6:7], v[6:7], v[72:73] op_sel_hi:[1,0]
	v_pk_mul_f32 v[4:5], v[4:5], v[72:73] op_sel_hi:[1,0]
.LBB0_876:
	v_add_f32_e32 v202, -4.0, v203
	v_sub_f32_e32 v36, v36, v202
	v_sub_f32_e32 v40, v40, v202
	v_sub_f32_e32 v37, v37, v202
	v_sub_f32_e32 v41, v41, v202
	v_exp_f32_e32 v36, v36
	v_exp_f32_e32 v40, v40
	v_exp_f32_e32 v37, v37
	v_exp_f32_e32 v41, v41
	v_sub_f32_e32 v38, v38, v202
	v_sub_f32_e32 v42, v42, v202
	v_sub_f32_e32 v39, v39, v202
	v_sub_f32_e32 v43, v43, v202
	v_exp_f32_e32 v38, v38
	v_exp_f32_e32 v42, v42
	v_exp_f32_e32 v39, v39
	v_exp_f32_e32 v43, v43
	v_cndmask_b32_e64 v202, 0, v36, s[10:11]
	v_cndmask_b32_e64 v204, 0, v40, s[10:11]
	v_cndmask_b32_e64 v205, 0, v37, s[10:11]
	v_cndmask_b32_e64 v229, 0, v41, s[10:11]
	v_mov_b32_e32 v230, v1
	v_mov_b32_e32 v231, v1
	v_cvt_pk_fp8_f32 v230, v202, v205
	v_cvt_pk_fp8_f32 v231, v204, v229
	v_cndmask_b32_e64 v232, 0, v38, s[10:11]
	v_cndmask_b32_e64 v233, 0, v42, s[10:11]
	v_cndmask_b32_e64 v234, 0, v39, s[10:11]
	v_cndmask_b32_e64 v235, 0, v43, s[10:11]
	v_cvt_pk_fp8_f32 v230, v232, v234 op_sel:[0,0,1]
	v_cvt_pk_fp8_f32 v231, v233, v235 op_sel:[0,0,1]
	s_nop 0
	s_waitcnt vmcnt(19)
	v_mfma_f32_16x16x32_fp8_fp8 v[40:43], v[108:109], v[230:231], v[12:15]
	v_mfma_f32_16x16x32_fp8_fp8 v[48:51], v[112:113], v[230:231], v[20:23]
	s_nop 2
	v_add_f32_e32 v56, v202, v204
	s_waitcnt vmcnt(18)
	v_mfma_f32_16x16x32_fp8_fp8 v[36:39], v[106:107], v[230:231], v[8:11]
	v_mfma_f32_16x16x32_fp8_fp8 v[44:47], v[110:111], v[230:231], v[16:19]
	s_waitcnt vmcnt(17)
	v_mfma_f32_16x16x32_fp8_fp8 v[52:55], v[114:115], v[230:231], v[24:27]
	s_nop 2
	v_add_f32_e32 v60, 0, v56
	v_add_f32_e32 v61, v205, v229
	v_add_f32_e32 v60, v61, v60
	v_add_f32_e32 v61, v232, v233
	v_mfma_f32_16x16x32_fp8_fp8 v[56:59], v[116:117], v[230:231], v[32:35]
	s_nop 2
	v_add_f32_e32 v64, v61, v60
	v_add_f32_e32 v65, v234, v235
	v_add_f32_e32 v64, v65, v64
	s_waitcnt vmcnt(16)
	v_mfma_f32_16x16x32_fp8_fp8 v[60:63], v[134:135], v[230:231], v[28:31]
	v_add_f32_e32 v204, v3, v64
	v_mfma_f32_16x16x32_fp8_fp8 v[64:67], v[136:137], v[230:231], v[4:7]
	s_nop 1
	s_branch .LBB0_866

; template <bool SLC, bool NOMASK> ...
;     ...
;     const int pos0 = SLC ? (dcur & 0xfffff) : dcur;
;     const int lo = SLC ? ((((dcur >> 20) == qi) | ((dcur >> 20) == 4)) ? 0 : (1 << 30)) : lo_in;
;     load_frag8(nxt, KF, VF, SLC ? (dnext & 0xfffff) : dnext, lane);
;     f32x4 sa[2] = {(f32x4){0.f, 0.f, 0.f, 0.f}, (f32x4){0.f, 0.f, 0.f, 0.f}};
; #pragma unroll
;     for (int T = 0; T < 2; ++T)
; #pragma unroll
;         for (int s2 = 0; s2 < 4; ++s2) sa[T] = __builtin_amdgcn_mfma_f32_16x16x32_fp8_fp8(cur.k[T][s2], qf[s2], sa[T], 0, 0, 0);
;     float sc[8]; bool vd[8]; float mx = -1e30f;
;     const bool act = lo == 0 || !SLC;
;     if (NOMASK) {
; #pragma unroll
;         for (int j = 0; j < 8; ++j) { sc[j] = sa[j >> 2][j & 3]; vd[j] = act; }
;         mx = fmaxf(fmaxf(fmaxf(sc[0], sc[1]), fmaxf(sc[2], sc[3])), fmaxf(fmaxf(sc[4], sc[5]), fmaxf(sc[6], sc[7])));
;         mx = act ? mx : -1e30f;
;     } else {
; #pragma unroll
;         for (int T = 0; T < 2; ++T)
; #pragma unroll
;             for (int r = 0; r < 4; ++r) { const int p = pos0 + 16 * T + 4 * kq + r; const bool v = (p >= lo) & (p <= hi); const float x = sa[T][r];
;                 sc[4 * T + r] = x; vd[4 * T + r] = v; mx = v ? fmaxf(mx, x) : mx; }
;     }
;     if (__builtin_amdgcn_ballot_w64(mx > st.m + 4.f) != 0ull) {
;         mx = fmaxf(mx, __shfl_xor(mx, 16)); mx = fmaxf(mx, __shfl_xor(mx, 32));
;         const float mn = fmaxf(st.m, mx), alpha = __builtin_amdgcn_exp2f(st.m - mn); st.m = mn; st.l *= alpha;
; #pragma unroll
;         for (int j = 0; j < 8; ++j) st.o[j] = st.o[j] * alpha;
;     }
;     f32x4 pa, pb; float ps = 0.f;
;     const float mref = st.m - 4.f;
;     if (NOMASK) {
; #pragma unroll
;         for (int j = 0; j < 4; ++j) { pa[j] = __builtin_amdgcn_exp2f(sc[j] - mref); pb[j] = __builtin_amdgcn_exp2f(sc[4 + j] - mref); }
;         if (SLC) {
; #pragma unroll
;             for (int j = 0; j < 4; ++j) { pa[j] = act ? pa[j] : 0.f; pb[j] = act ? pb[j] : 0.f; }
;         }
; #pragma unroll
;         for (int j = 0; j < 4; ++j) ps += pa[j] + pb[j];
;     } else {
; #pragma unroll
;         for (int j = 0; j < 4; ++j) { pa[j] = vd[j] ? __builtin_amdgcn_exp2f(sc[j] - mref) : 0.f; pb[j] = vd[4 + j] ? __builtin_amdgcn_exp2f(sc[4 + j] - mref) : 0.f; ps += pa[j] + pb[j]; }
;     }
;     st.l += ps;
;     const u32x2 pw = pack8_fp8(pa, pb);
.LBB0_880:
	s_cmp_lt_u32 s58, s56
	s_cselect_b32 s10, s58, s57
	s_lshl_b32 s10, s10, 2
	s_add_i32 s10, s3, s10
	v_mov_b32_e32 v0, s10
	ds_read_b32 v0, v0 offset:13632
	s_and_b32 s13, s66, 2.0
	s_ashr_i32 s12, s66, 20
	s_mov_b64 s[10:11], -1
	s_cmp_eq_u32 s13, 0
	s_waitcnt lgkmcnt(0)
	v_readfirstlane_b32 s97, v0
	v_add_f32_e32 v0, 4.0, v203
	s_cbranch_scc1 .LBB0_884
	s_and_b32 s13, s12, 0xfffffbff
	s_cmp_eq_u32 s13, 4
	s_cselect_b64 s[10:11], -1, 0
	s_lshl_b32 s14, s97, 7
	s_and_b32 s50, s14, 0x7fff800
	v_lshl_add_u64 v[10:11], v[86:87], 0, s[50:51]
	s_and_b32 s50, s14, 0x7fff000
	v_lshl_add_u64 v[244:245], v[10:11], 0, v[118:119]
	global_load_dwordx4 v[154:157], v[244:245], off
	global_load_dwordx4 v[158:161], v[244:245], off offset:1024
	global_load_dwordx4 v[162:165], v[244:245], off offset:2048
	global_load_dwordx4 v[166:169], v[244:245], off offset:3072
	v_lshl_add_u64 v[10:11], v[88:89], 0, s[50:51]
	v_lshl_add_u64 v[246:247], v[10:11], 0, v[118:119]
	global_load_dwordx4 v[106:109], v[246:247], off
	global_load_dwordx4 v[110:113], v[246:247], off offset:1024
	global_load_dwordx4 v[114:117], v[246:247], off offset:2048
	global_load_dwordx4 v[134:137], v[246:247], off offset:3072
	s_waitcnt vmcnt(20)
	v_mfma_f32_16x16x32_fp8_fp8 v[2:5], v[186:187], v[78:79], 0
	v_cmp_eq_u32_e32 vcc, s13, v209
	s_or_b64 s[10:11], s[10:11], vcc
	v_mfma_f32_16x16x32_fp8_fp8 v[6:9], v[194:195], v[78:79], 0
	v_mfma_f32_16x16x32_fp8_fp8 v[2:5], v[188:189], v[80:81], v[2:5]
	v_mfma_f32_16x16x32_fp8_fp8 v[6:9], v[196:197], v[80:81], v[6:9]
	v_mov_b32_e32 v202, v203
	v_mfma_f32_16x16x32_fp8_fp8 v[2:5], v[190:191], v[82:83], v[2:5]
	v_mfma_f32_16x16x32_fp8_fp8 v[6:9], v[198:199], v[82:83], v[6:9]
	v_mov_b32_e32 v133, v204
	v_mfma_f32_16x16x32_fp8_fp8 v[2:5], v[192:193], v[84:85], v[2:5]
	v_mfma_f32_16x16x32_fp8_fp8 v[6:9], v[200:201], v[84:85], v[6:9]
	s_nop 6
	v_max_f32_e32 v10, v3, v3
	v_max_f32_e32 v11, v2, v2
	v_max_f32_e32 v10, v11, v10
	v_max_f32_e32 v11, v5, v5
	v_max_f32_e32 v12, v4, v4
	v_max_f32_e32 v11, v12, v11
	v_max_f32_e32 v12, v9, v9
	v_max_f32_e32 v13, v8, v8
	v_max_f32_e32 v12, v13, v12
	v_max3_f32 v12, v6, v7, v12
	v_max3_f32 v10, v10, v11, v12
	v_cndmask_b32_e64 v34, v223, v10, s[10:11]
	v_cmp_gt_f32_e32 vcc, v34, v0
	s_cbranch_vccz .LBB0_883
	ds_bpermute_b32 v10, v227, v34
	v_max_f32_e32 v11, v34, v34
	s_waitcnt lgkmcnt(0)
	v_max_f32_e32 v10, v10, v10
	v_max_f32_e32 v10, v11, v10
	ds_bpermute_b32 v11, v226, v10
	s_waitcnt lgkmcnt(0)
	v_max3_f32 v202, v203, v10, v11
	v_sub_f32_e32 v10, v203, v202
	v_exp_f32_e32 v34, v10
	s_nop 0
	v_mul_f32_e32 v133, v204, v34
	v_pk_mul_f32 v[38:39], v[38:39], v[34:35] op_sel_hi:[1,0]
	v_pk_mul_f32 v[36:37], v[36:37], v[34:35] op_sel_hi:[1,0]
	v_pk_mul_f32 v[42:43], v[42:43], v[34:35] op_sel_hi:[1,0]
	v_pk_mul_f32 v[40:41], v[40:41], v[34:35] op_sel_hi:[1,0]
	v_pk_mul_f32 v[46:47], v[46:47], v[34:35] op_sel_hi:[1,0]
	v_pk_mul_f32 v[44:45], v[44:45], v[34:35] op_sel_hi:[1,0]
	v_pk_mul_f32 v[50:51], v[50:51], v[34:35] op_sel_hi:[1,0]
	v_pk_mul_f32 v[48:49], v[48:49], v[34:35] op_sel_hi:[1,0]
	v_pk_mul_f32 v[54:55], v[54:55], v[34:35] op_sel_hi:[1,0]
	v_pk_mul_f32 v[52:53], v[52:53], v[34:35] op_sel_hi:[1,0]
	v_pk_mul_f32 v[58:59], v[58:59], v[34:35] op_sel_hi:[1,0]
	v_pk_mul_f32 v[56:57], v[56:57], v[34:35] op_sel_hi:[1,0]
	v_pk_mul_f32 v[62:63], v[62:63], v[34:35] op_sel_hi:[1,0]
	v_pk_mul_f32 v[60:61], v[60:61], v[34:35] op_sel_hi:[1,0]
	v_pk_mul_f32 v[66:67], v[66:67], v[34:35] op_sel_hi:[1,0]
	v_pk_mul_f32 v[64:65], v[64:65], v[34:35] op_sel_hi:[1,0]
.LBB0_883:
	v_add_f32_e32 v34, -4.0, v202
	v_sub_f32_e32 v2, v2, v34
	v_sub_f32_e32 v6, v6, v34
	v_sub_f32_e32 v3, v3, v34
	v_sub_f32_e32 v7, v7, v34
	v_exp_f32_e32 v2, v2
	v_exp_f32_e32 v6, v6
	v_exp_f32_e32 v3, v3
	v_exp_f32_e32 v7, v7
	v_sub_f32_e32 v4, v4, v34
	v_sub_f32_e32 v8, v8, v34
	v_sub_f32_e32 v5, v5, v34
	v_sub_f32_e32 v9, v9, v34
	v_exp_f32_e32 v4, v4
	v_exp_f32_e32 v8, v8
	v_exp_f32_e32 v5, v5
	v_exp_f32_e32 v9, v9
	v_cndmask_b32_e64 v34, 0, v2, s[10:11]
	v_cndmask_b32_e64 v6, 0, v6, s[10:11]
	v_cndmask_b32_e64 v35, 0, v3, s[10:11]
	v_cndmask_b32_e64 v7, 0, v7, s[10:11]
	v_mov_b32_e32 v2, v1
	v_mov_b32_e32 v3, v1
	v_cvt_pk_fp8_f32 v2, v34, v35
	v_cvt_pk_fp8_f32 v3, v6, v7
	v_cndmask_b32_e64 v4, 0, v4, s[10:11]
	v_cndmask_b32_e64 v205, 0, v8, s[10:11]
	v_cndmask_b32_e64 v5, 0, v5, s[10:11]
	v_cndmask_b32_e64 v229, 0, v9, s[10:11]
	v_add_f32_e32 v6, v34, v6
	v_cvt_pk_fp8_f32 v2, v4, v5 op_sel:[0,0,1]
	v_cvt_pk_fp8_f32 v3, v205, v229 op_sel:[0,0,1]
	v_add_f32_e32 v6, 0, v6
	v_add_f32_e32 v7, v35, v7
	v_add_f32_e32 v6, v7, v6
	v_add_f32_e32 v4, v4, v205
	v_add_f32_e32 v4, v4, v6
	v_add_f32_e32 v5, v5, v229
	v_add_f32_e32 v4, v5, v4
	s_waitcnt vmcnt(19)
	v_mfma_f32_16x16x32_fp8_fp8 v[8:11], v[170:171], v[2:3], v[36:39]
	v_add_f32_e32 v133, v133, v4
	s_mov_b64 s[10:11], 0
	v_mfma_f32_16x16x32_fp8_fp8 v[12:15], v[172:173], v[2:3], v[40:43]
	s_waitcnt vmcnt(18)
	v_mfma_f32_16x16x32_fp8_fp8 v[16:19], v[174:175], v[2:3], v[44:47]
	v_mfma_f32_16x16x32_fp8_fp8 v[20:23], v[176:177], v[2:3], v[48:51]
	s_waitcnt vmcnt(17)
	v_mfma_f32_16x16x32_fp8_fp8 v[24:27], v[178:179], v[2:3], v[52:55]
	v_mfma_f32_16x16x32_fp8_fp8 v[32:35], v[180:181], v[2:3], v[56:59]
	s_waitcnt vmcnt(16)
	v_mfma_f32_16x16x32_fp8_fp8 v[28:31], v[182:183], v[2:3], v[60:63]
	v_mfma_f32_16x16x32_fp8_fp8 v[4:7], v[184:185], v[2:3], v[64:67]
	s_nop 1

; template <bool SLC, bool NOMASK> ...
;     ...
;     load_frag8(nxt, KF, VF, SLC ? (dnext & 0xfffff) : dnext, lane);
;     f32x4 sa[2] = {(f32x4){0.f, 0.f, 0.f, 0.f}, (f32x4){0.f, 0.f, 0.f, 0.f}};
; #pragma unroll
;     for (int T = 0; T < 2; ++T)
; #pragma unroll
;         for (int s2 = 0; s2 < 4; ++s2) sa[T] = __builtin_amdgcn_mfma_f32_16x16x32_fp8_fp8(cur.k[T][s2], qf[s2], sa[T], 0, 0, 0);
;     float sc[8]; bool vd[8]; float mx = -1e30f;
;     const bool act = lo == 0 || !SLC;
;     if (NOMASK) {
; #pragma unroll
;         for (int j = 0; j < 8; ++j) { sc[j] = sa[j >> 2][j & 3]; vd[j] = act; }
;         mx = fmaxf(fmaxf(fmaxf(sc[0], sc[1]), fmaxf(sc[2], sc[3])), fmaxf(fmaxf(sc[4], sc[5]), fmaxf(sc[6], sc[7])));
;         mx = act ? mx : -1e30f;
;     } else {
; #pragma unroll
;         for (int T = 0; T < 2; ++T)
; #pragma unroll
;             for (int r = 0; r < 4; ++r) { const int p = pos0 + 16 * T + 4 * kq + r; const bool v = (p >= lo) & (p <= hi); const float x = sa[T][r];
;                 sc[4 * T + r] = x; vd[4 * T + r] = v; mx = v ? fmaxf(mx, x) : mx; }
;     }
;     if (__builtin_amdgcn_ballot_w64(mx > st.m + 4.f) != 0ull) {
;         mx = fmaxf(mx, __shfl_xor(mx, 16)); mx = fmaxf(mx, __shfl_xor(mx, 32));
;         const float mn = fmaxf(st.m, mx), alpha = __builtin_amdgcn_exp2f(st.m - mn); st.m = mn; st.l *= alpha;
; #pragma unroll
;         for (int j = 0; j < 8; ++j) st.o[j] = st.o[j] * alpha;
;     }
;     f32x4 pa, pb; float ps = 0.f;
;     const float mref = st.m - 4.f;
;     if (NOMASK) {
; #pragma unroll
;         for (int j = 0; j < 4; ++j) { pa[j] = __builtin_amdgcn_exp2f(sc[j] - mref); pb[j] = __builtin_amdgcn_exp2f(sc[4 + j] - mref); }
;         if (SLC) {
; #pragma unroll
;             for (int j = 0; j < 4; ++j) { pa[j] = act ? pa[j] : 0.f; pb[j] = act ? pb[j] : 0.f; }
;         }
; #pragma unroll
;         for (int j = 0; j < 4; ++j) ps += pa[j] + pb[j];
;     } else {
; #pragma unroll
;         for (int j = 0; j < 4; ++j) { pa[j] = vd[j] ? __builtin_amdgcn_exp2f(sc[j] - mref) : 0.f; pb[j] = vd[4 + j] ? __builtin_amdgcn_exp2f(sc[4 + j] - mref) : 0.f; ps += pa[j] + pb[j]; }
;     }
;     st.l += ps;
;     const u32x2 pw = pack8_fp8(pa, pb);
;     const i64_t pf = __builtin_bit_cast(i64_t, pw);
; #pragma unroll
;     for (int db = 0; db < 8; ++db) st.o[db] = __builtin_amdgcn_mfma_f32_16x16x32_fp8_fp8(cur.v[db], pf, st.o[db], 0, 0, 0);
.LBB0_900:
	v_lshl_add_u64 v[244:245], v[204:205], 0, v[118:119]
	global_load_dwordx4 v[186:189], v[244:245], off
	global_load_dwordx4 v[190:193], v[244:245], off offset:1024
	global_load_dwordx4 v[194:197], v[244:245], off offset:2048
	global_load_dwordx4 v[198:201], v[244:245], off offset:3072
	v_lshl_add_u64 v[246:247], v[202:203], 0, v[118:119]
	global_load_dwordx4 v[170:173], v[246:247], off
	global_load_dwordx4 v[174:177], v[246:247], off offset:1024
	global_load_dwordx4 v[178:181], v[246:247], off offset:2048
	global_load_dwordx4 v[182:185], v[246:247], off offset:3072
	s_waitcnt vmcnt(20)
	v_mfma_f32_16x16x32_fp8_fp8 v[2:5], v[138:139], v[78:79], 0
	v_mfma_f32_16x16x32_fp8_fp8 v[6:9], v[146:147], v[78:79], 0
	v_mfma_f32_16x16x32_fp8_fp8 v[2:5], v[140:141], v[80:81], v[2:5]
	v_mov_b32_e32 v229, v133
	v_mfma_f32_16x16x32_fp8_fp8 v[6:9], v[148:149], v[80:81], v[6:9]
	v_mfma_f32_16x16x32_fp8_fp8 v[2:5], v[142:143], v[82:83], v[2:5]
	v_mfma_f32_16x16x32_fp8_fp8 v[6:9], v[150:151], v[82:83], v[6:9]
	v_mov_b32_e32 v34, v230
	v_mfma_f32_16x16x32_fp8_fp8 v[2:5], v[144:145], v[84:85], v[2:5]
	v_mfma_f32_16x16x32_fp8_fp8 v[6:9], v[152:153], v[84:85], v[6:9]
	s_nop 6
	v_max_f32_e32 v0, v3, v3
	v_max_f32_e32 v10, v2, v2
	v_max_f32_e32 v0, v10, v0
	v_max_f32_e32 v10, v5, v5
	v_max_f32_e32 v11, v4, v4
	v_max_f32_e32 v10, v11, v10
	v_max_f32_e32 v11, v9, v9
	v_max_f32_e32 v12, v8, v8
	v_max_f32_e32 v11, v12, v11
	v_max3_f32 v11, v6, v7, v11
	v_max3_f32 v0, v0, v10, v11
	v_cmp_gt_f32_e32 vcc, v0, v231
	s_cbranch_vccz .LBB0_902
	ds_bpermute_b32 v10, v227, v0
	v_max_f32_e32 v0, v0, v0
	s_waitcnt lgkmcnt(0)
	v_max_f32_e32 v10, v10, v10
	v_max_f32_e32 v0, v0, v10
	ds_bpermute_b32 v10, v226, v0
	s_waitcnt lgkmcnt(0)
	v_max3_f32 v229, v133, v0, v10
	v_sub_f32_e32 v0, v133, v229
	v_exp_f32_e32 v0, v0
	s_nop 0
	v_mul_f32_e32 v34, v230, v0
	v_pk_mul_f32 v[66:67], v[66:67], v[0:1] op_sel_hi:[1,0]
	v_pk_mul_f32 v[64:65], v[64:65], v[0:1] op_sel_hi:[1,0]
	v_pk_mul_f32 v[62:63], v[62:63], v[0:1] op_sel_hi:[1,0]
	v_pk_mul_f32 v[60:61], v[60:61], v[0:1] op_sel_hi:[1,0]
	v_pk_mul_f32 v[58:59], v[58:59], v[0:1] op_sel_hi:[1,0]
	v_pk_mul_f32 v[56:57], v[56:57], v[0:1] op_sel_hi:[1,0]
	v_pk_mul_f32 v[54:55], v[54:55], v[0:1] op_sel_hi:[1,0]
	v_pk_mul_f32 v[52:53], v[52:53], v[0:1] op_sel_hi:[1,0]
	v_pk_mul_f32 v[50:51], v[50:51], v[0:1] op_sel_hi:[1,0]
	v_pk_mul_f32 v[48:49], v[48:49], v[0:1] op_sel_hi:[1,0]
	v_pk_mul_f32 v[46:47], v[46:47], v[0:1] op_sel_hi:[1,0]
	v_pk_mul_f32 v[44:45], v[44:45], v[0:1] op_sel_hi:[1,0]
	v_pk_mul_f32 v[42:43], v[42:43], v[0:1] op_sel_hi:[1,0]
	v_pk_mul_f32 v[40:41], v[40:41], v[0:1] op_sel_hi:[1,0]
	v_pk_mul_f32 v[38:39], v[38:39], v[0:1] op_sel_hi:[1,0]
	v_pk_mul_f32 v[36:37], v[36:37], v[0:1] op_sel_hi:[1,0]
.LBB0_902:
	v_add_f32_e32 v232, -4.0, v229
	v_sub_f32_e32 v0, v2, v232
	v_exp_f32_e32 v233, v0
	v_sub_f32_e32 v0, v6, v232
	v_exp_f32_e32 v236, v0
	v_sub_f32_e32 v0, v3, v232
	v_exp_f32_e32 v2, v0
	v_sub_f32_e32 v0, v7, v232
	v_exp_f32_e32 v0, v0
	v_sub_f32_e32 v3, v4, v232
	v_exp_f32_e32 v237, v3
	v_sub_f32_e32 v3, v8, v232
	v_exp_f32_e32 v238, v3
	v_sub_f32_e32 v3, v5, v232
	v_exp_f32_e32 v4, v3
	v_sub_f32_e32 v3, v9, v232
	v_mov_b32_e32 v234, v1
	v_mov_b32_e32 v235, v1
	v_exp_f32_e32 v232, v3
	v_cvt_pk_fp8_f32 v234, v233, v2
	v_cvt_pk_fp8_f32 v235, v236, v0
	v_add_f32_e32 v3, v233, v236
	v_pk_add_f32 v[2:3], v[2:3], v[0:1]
	v_cvt_pk_fp8_f32 v234, v237, v4 op_sel:[0,0,1]
	v_cvt_pk_fp8_f32 v235, v238, v232 op_sel:[0,0,1]
	v_pk_add_f32 v[2:3], v[2:3], v[2:3] op_sel_hi:[0,1]
	v_add_f32_e32 v5, v237, v238
	v_mov_b32_e32 v233, v3
	v_pk_add_f32 v[2:3], v[4:5], v[232:233]
	s_waitcnt vmcnt(19)
	v_mfma_f32_16x16x32_fp8_fp8 v[6:9], v[90:91], v[234:235], v[64:67]
	v_add_f32_e32 v0, v2, v3
	v_add_f32_e32 v34, v0, v34
	v_mfma_f32_16x16x32_fp8_fp8 v[10:13], v[92:93], v[234:235], v[60:63]
	s_waitcnt vmcnt(18)
	v_mfma_f32_16x16x32_fp8_fp8 v[14:17], v[94:95], v[234:235], v[56:59]
	v_mfma_f32_16x16x32_fp8_fp8 v[18:21], v[96:97], v[234:235], v[52:55]
	s_waitcnt vmcnt(17)
	v_mfma_f32_16x16x32_fp8_fp8 v[22:25], v[98:99], v[234:235], v[48:51]
	v_mfma_f32_16x16x32_fp8_fp8 v[26:29], v[100:101], v[234:235], v[44:47]
	s_waitcnt vmcnt(16)
	v_mfma_f32_16x16x32_fp8_fp8 v[30:33], v[102:103], v[234:235], v[40:43]
	v_mfma_f32_16x16x32_fp8_fp8 v[2:5], v[104:105], v[234:235], v[36:39]
	s_nop 1
	s_branch .LBB0_896

; template <bool SLC, bool NOMASK> ...
;     ...
;     load_frag8(nxt, KF, VF, SLC ? (dnext & 0xfffff) : dnext, lane);
;     f32x4 sa[2] = {(f32x4){0.f, 0.f, 0.f, 0.f}, (f32x4){0.f, 0.f, 0.f, 0.f}};
; #pragma unroll
;     for (int T = 0; T < 2; ++T)
; #pragma unroll
;         for (int s2 = 0; s2 < 4; ++s2) sa[T] = __builtin_amdgcn_mfma_f32_16x16x32_fp8_fp8(cur.k[T][s2], qf[s2], sa[T], 0, 0, 0);
;     float sc[8]; bool vd[8]; float mx = -1e30f;
;     const bool act = lo == 0 || !SLC;
;     if (NOMASK) {
; #pragma unroll
;         for (int j = 0; j < 8; ++j) { sc[j] = sa[j >> 2][j & 3]; vd[j] = act; }
;         mx = fmaxf(fmaxf(fmaxf(sc[0], sc[1]), fmaxf(sc[2], sc[3])), fmaxf(fmaxf(sc[4], sc[5]), fmaxf(sc[6], sc[7])));
;         mx = act ? mx : -1e30f;
;     } else {
; #pragma unroll
;         for (int T = 0; T < 2; ++T)
; #pragma unroll
;             for (int r = 0; r < 4; ++r) { const int p = pos0 + 16 * T + 4 * kq + r; const bool v = (p >= lo) & (p <= hi); const float x = sa[T][r];
;                 sc[4 * T + r] = x; vd[4 * T + r] = v; mx = v ? fmaxf(mx, x) : mx; }
;     }
;     if (__builtin_amdgcn_ballot_w64(mx > st.m + 4.f) != 0ull) {
;         mx = fmaxf(mx, __shfl_xor(mx, 16)); mx = fmaxf(mx, __shfl_xor(mx, 32));
;         const float mn = fmaxf(st.m, mx), alpha = __builtin_amdgcn_exp2f(st.m - mn); st.m = mn; st.l *= alpha;
; #pragma unroll
;         for (int j = 0; j < 8; ++j) st.o[j] = st.o[j] * alpha;
;     }
;     f32x4 pa, pb; float ps = 0.f;
;     const float mref = st.m - 4.f;
;     if (NOMASK) {
; #pragma unroll
;         for (int j = 0; j < 4; ++j) { pa[j] = __builtin_amdgcn_exp2f(sc[j] - mref); pb[j] = __builtin_amdgcn_exp2f(sc[4 + j] - mref); }
;         if (SLC) {
; #pragma unroll
;             for (int j = 0; j < 4; ++j) { pa[j] = act ? pa[j] : 0.f; pb[j] = act ? pb[j] : 0.f; }
;         }
; #pragma unroll
;         for (int j = 0; j < 4; ++j) ps += pa[j] + pb[j];
;     } else {
; #pragma unroll
;         for (int j = 0; j < 4; ++j) { pa[j] = vd[j] ? __builtin_amdgcn_exp2f(sc[j] - mref) : 0.f; pb[j] = vd[4 + j] ? __builtin_amdgcn_exp2f(sc[4 + j] - mref) : 0.f; ps += pa[j] + pb[j]; }
;     }
;     st.l += ps;
;     const u32x2 pw = pack8_fp8(pa, pb);
;     const i64_t pf = __builtin_bit_cast(i64_t, pw);
; #pragma unroll
;     for (int db = 0; db < 8; ++db) st.o[db] = __builtin_amdgcn_mfma_f32_16x16x32_fp8_fp8(cur.v[db], pf, st.o[db], 0, 0, 0);
.LBB0_907:
	v_lshl_add_u64 v[244:245], v[204:205], 0, v[118:119]
	global_load_dwordx4 v[138:141], v[244:245], off
	global_load_dwordx4 v[142:145], v[244:245], off offset:1024
	global_load_dwordx4 v[146:149], v[244:245], off offset:2048
	global_load_dwordx4 v[150:153], v[244:245], off offset:3072
	v_lshl_add_u64 v[246:247], v[202:203], 0, v[118:119]
	global_load_dwordx4 v[90:93], v[246:247], off
	global_load_dwordx4 v[94:97], v[246:247], off offset:1024
	global_load_dwordx4 v[98:101], v[246:247], off offset:2048
	global_load_dwordx4 v[102:105], v[246:247], off offset:3072
	s_waitcnt vmcnt(20)
	v_mfma_f32_16x16x32_fp8_fp8 v[36:39], v[154:155], v[78:79], 0
	v_mfma_f32_16x16x32_fp8_fp8 v[40:43], v[162:163], v[78:79], 0
	v_mfma_f32_16x16x32_fp8_fp8 v[36:39], v[156:157], v[80:81], v[36:39]
	v_mov_b32_e32 v230, v229
	v_mfma_f32_16x16x32_fp8_fp8 v[40:43], v[164:165], v[80:81], v[40:43]
	v_mfma_f32_16x16x32_fp8_fp8 v[36:39], v[158:159], v[82:83], v[36:39]
	v_mfma_f32_16x16x32_fp8_fp8 v[40:43], v[166:167], v[82:83], v[40:43]
	v_mov_b32_e32 v231, v34
	v_mfma_f32_16x16x32_fp8_fp8 v[36:39], v[160:161], v[84:85], v[36:39]
	v_mfma_f32_16x16x32_fp8_fp8 v[40:43], v[168:169], v[84:85], v[40:43]
	s_nop 6
	v_max_f32_e32 v0, v37, v37
	v_max_f32_e32 v44, v36, v36
	v_max_f32_e32 v0, v44, v0
	v_max_f32_e32 v44, v39, v39
	v_max_f32_e32 v45, v38, v38
	v_max_f32_e32 v44, v45, v44
	v_max_f32_e32 v45, v43, v43
	v_max_f32_e32 v46, v42, v42
	v_max_f32_e32 v45, v46, v45
	v_max3_f32 v45, v40, v41, v45
	v_max3_f32 v0, v0, v44, v45
	v_cmp_gt_f32_e32 vcc, v0, v133
	s_cbranch_vccz .LBB0_909
	ds_bpermute_b32 v44, v227, v0
	v_max_f32_e32 v0, v0, v0
	s_waitcnt lgkmcnt(0)
	v_max_f32_e32 v44, v44, v44
	v_max_f32_e32 v0, v0, v44
	ds_bpermute_b32 v44, v226, v0
	s_waitcnt lgkmcnt(0)
	v_max3_f32 v230, v229, v0, v44
	v_sub_f32_e32 v0, v229, v230
	v_exp_f32_e32 v0, v0
	s_nop 0
	v_mul_f32_e32 v231, v34, v0
	v_pk_mul_f32 v[8:9], v[8:9], v[0:1] op_sel_hi:[1,0]
	v_pk_mul_f32 v[6:7], v[6:7], v[0:1] op_sel_hi:[1,0]
	v_pk_mul_f32 v[12:13], v[12:13], v[0:1] op_sel_hi:[1,0]
	v_pk_mul_f32 v[10:11], v[10:11], v[0:1] op_sel_hi:[1,0]
	v_pk_mul_f32 v[16:17], v[16:17], v[0:1] op_sel_hi:[1,0]
	v_pk_mul_f32 v[14:15], v[14:15], v[0:1] op_sel_hi:[1,0]
	v_pk_mul_f32 v[20:21], v[20:21], v[0:1] op_sel_hi:[1,0]
	v_pk_mul_f32 v[18:19], v[18:19], v[0:1] op_sel_hi:[1,0]
	v_pk_mul_f32 v[24:25], v[24:25], v[0:1] op_sel_hi:[1,0]
	v_pk_mul_f32 v[22:23], v[22:23], v[0:1] op_sel_hi:[1,0]
	v_pk_mul_f32 v[28:29], v[28:29], v[0:1] op_sel_hi:[1,0]
	v_pk_mul_f32 v[26:27], v[26:27], v[0:1] op_sel_hi:[1,0]
	v_pk_mul_f32 v[32:33], v[32:33], v[0:1] op_sel_hi:[1,0]
	v_pk_mul_f32 v[30:31], v[30:31], v[0:1] op_sel_hi:[1,0]
	v_pk_mul_f32 v[4:5], v[4:5], v[0:1] op_sel_hi:[1,0]
	v_pk_mul_f32 v[2:3], v[2:3], v[0:1] op_sel_hi:[1,0]
.LBB0_909:
	v_add_f32_e32 v233, -4.0, v230
	v_sub_f32_e32 v0, v36, v233
	v_exp_f32_e32 v235, v0
	v_sub_f32_e32 v0, v40, v233
	v_exp_f32_e32 v237, v0
	v_sub_f32_e32 v0, v37, v233
	v_exp_f32_e32 v232, v0
	v_sub_f32_e32 v0, v41, v233
	v_exp_f32_e32 v0, v0
	v_sub_f32_e32 v36, v38, v233
	v_exp_f32_e32 v240, v36
	v_sub_f32_e32 v36, v42, v233
	v_exp_f32_e32 v241, v36
	v_sub_f32_e32 v36, v39, v233
	v_exp_f32_e32 v234, v36
	v_sub_f32_e32 v36, v43, v233
	v_mov_b32_e32 v238, v1
	v_mov_b32_e32 v239, v1
	v_exp_f32_e32 v236, v36
	v_cvt_pk_fp8_f32 v238, v235, v232
	v_cvt_pk_fp8_f32 v239, v237, v0
	v_add_f32_e32 v233, v235, v237
	v_add_f32_e32 v235, v240, v241
	v_cvt_pk_fp8_f32 v238, v240, v234 op_sel:[0,0,1]
	v_cvt_pk_fp8_f32 v239, v241, v236 op_sel:[0,0,1]
	s_nop 0
	s_waitcnt vmcnt(19)
	v_mfma_f32_16x16x32_fp8_fp8 v[36:39], v[106:107], v[238:239], v[6:9]
	v_mfma_f32_16x16x32_fp8_fp8 v[44:47], v[110:111], v[238:239], v[14:17]
	s_waitcnt vmcnt(18)
	v_mfma_f32_16x16x32_fp8_fp8 v[52:55], v[114:115], v[238:239], v[22:25]
	s_nop 2
	v_add_f32_e64 v60, v232, v0
	v_add_f32_e64 v61, v233, v1
	v_mfma_f32_16x16x32_fp8_fp8 v[40:43], v[108:109], v[238:239], v[10:13]
	v_pk_add_f32 v[60:61], v[60:61], v[60:61] op_sel_hi:[0,1]
	v_mov_b32_e32 v237, v61
	s_waitcnt vmcnt(17)
	v_mfma_f32_16x16x32_fp8_fp8 v[48:51], v[112:113], v[238:239], v[18:21]
	v_mfma_f32_16x16x32_fp8_fp8 v[56:59], v[116:117], v[238:239], v[26:29]
	s_nop 2
	v_add_f32_e64 v64, v234, v236
	v_add_f32_e64 v65, v235, v237
	s_waitcnt vmcnt(16)
	v_mfma_f32_16x16x32_fp8_fp8 v[60:63], v[134:135], v[238:239], v[30:33]
	v_add_f32_e32 v0, v64, v65
	v_add_f32_e32 v231, v0, v231
	v_mfma_f32_16x16x32_fp8_fp8 v[64:67], v[136:137], v[238:239], v[2:5]
	s_nop 1
	s_branch .LBB0_899

; template <bool SLC, bool NOMASK> ...
;     ...
;     const int pos0 = SLC ? (dcur & 0xfffff) : dcur;
;     const int lo = SLC ? ((((dcur >> 20) == qi) | ((dcur >> 20) == 4)) ? 0 : (1 << 30)) : lo_in;
;     load_frag8(nxt, KF, VF, SLC ? (dnext & 0xfffff) : dnext, lane);
;     f32x4 sa[2] = {(f32x4){0.f, 0.f, 0.f, 0.f}, (f32x4){0.f, 0.f, 0.f, 0.f}};
; #pragma unroll
;     for (int T = 0; T < 2; ++T)
; #pragma unroll
;         for (int s2 = 0; s2 < 4; ++s2) sa[T] = __builtin_amdgcn_mfma_f32_16x16x32_fp8_fp8(cur.k[T][s2], qf[s2], sa[T], 0, 0, 0);
;     float sc[8]; bool vd[8]; float mx = -1e30f;
;     const bool act = lo == 0 || !SLC;
;     if (NOMASK) {
; #pragma unroll
;         for (int j = 0; j < 8; ++j) { sc[j] = sa[j >> 2][j & 3]; vd[j] = act; }
;         mx = fmaxf(fmaxf(fmaxf(sc[0], sc[1]), fmaxf(sc[2], sc[3])), fmaxf(fmaxf(sc[4], sc[5]), fmaxf(sc[6], sc[7])));
;         mx = act ? mx : -1e30f;
;     } else {
; #pragma unroll
;         for (int T = 0; T < 2; ++T)
; #pragma unroll
;             for (int r = 0; r < 4; ++r) { const int p = pos0 + 16 * T + 4 * kq + r; const bool v = (p >= lo) & (p <= hi); const float x = sa[T][r];
;                 sc[4 * T + r] = x; vd[4 * T + r] = v; mx = v ? fmaxf(mx, x) : mx; }
;     }
;     if (__builtin_amdgcn_ballot_w64(mx > st.m + 4.f) != 0ull) {
;         mx = fmaxf(mx, __shfl_xor(mx, 16)); mx = fmaxf(mx, __shfl_xor(mx, 32));
;         const float mn = fmaxf(st.m, mx), alpha = __builtin_amdgcn_exp2f(st.m - mn); st.m = mn; st.l *= alpha;
; #pragma unroll
;         for (int j = 0; j < 8; ++j) st.o[j] = st.o[j] * alpha;
;     }
;     f32x4 pa, pb; float ps = 0.f;
;     const float mref = st.m - 4.f;
;     if (NOMASK) {
; #pragma unroll
;         for (int j = 0; j < 4; ++j) { pa[j] = __builtin_amdgcn_exp2f(sc[j] - mref); pb[j] = __builtin_amdgcn_exp2f(sc[4 + j] - mref); }
;         if (SLC) {
; #pragma unroll
;             for (int j = 0; j < 4; ++j) { pa[j] = act ? pa[j] : 0.f; pb[j] = act ? pb[j] : 0.f; }
;         }
; #pragma unroll
;         for (int j = 0; j < 4; ++j) ps += pa[j] + pb[j];
;     } else {
; #pragma unroll
;         for (int j = 0; j < 4; ++j) { pa[j] = vd[j] ? __builtin_amdgcn_exp2f(sc[j] - mref) : 0.f; pb[j] = vd[4 + j] ? __builtin_amdgcn_exp2f(sc[4 + j] - mref) : 0.f; ps += pa[j] + pb[j]; }
;     }
;     st.l += ps;
;     const u32x2 pw = pack8_fp8(pa, pb);
.LBB0_913:
	s_cmp_lt_i32 s59, s56
	s_cselect_b64 s[10:11], -1, 0
	s_or_b32 s12, s59, 31
	s_cmp_gt_i32 s12, s96
	s_cselect_b64 s[12:13], -1, 0
	s_or_b64 s[10:11], s[10:11], s[12:13]
	s_and_b64 s[10:11], s[10:11], exec
	s_cselect_b32 s10, 0, 2.0
	s_add_i32 s58, s58, 4
	s_or_b32 s14, s10, s59
	s_min_i32 s10, s58, s27
	s_add_i32 s12, s10, s26
	s_lshl_b32 s43, s12, 5
	s_and_b32 s10, s43, 0x3fffffe0
	s_lshr_b32 s50, s10, 4
	s_lshl_b64 s[10:11], s[50:51], 11
	s_and_b32 s50, s12, 0x1ffffff
	s_lshl_b64 s[12:13], s[50:51], 12
	s_cmp_lt_u32 s14, 2.0
	v_lshl_add_u64 v[204:205], v[86:87], 0, s[10:11]
	v_lshl_add_u64 v[202:203], v[88:89], 0, s[12:13]
	s_mov_b64 s[10:11], -1
	v_add_f32_e32 v229, 4.0, v230
	s_cbranch_scc1 .LBB0_917
	v_lshl_add_u64 v[244:245], v[204:205], 0, v[118:119]
	global_load_dwordx4 v[154:157], v[244:245], off
	global_load_dwordx4 v[158:161], v[244:245], off offset:1024
	global_load_dwordx4 v[162:165], v[244:245], off offset:2048
	global_load_dwordx4 v[166:169], v[244:245], off offset:3072
	v_lshl_add_u64 v[246:247], v[202:203], 0, v[118:119]
	global_load_dwordx4 v[106:109], v[246:247], off
	global_load_dwordx4 v[110:113], v[246:247], off offset:1024
	global_load_dwordx4 v[114:117], v[246:247], off offset:2048
	global_load_dwordx4 v[134:137], v[246:247], off offset:3072
	s_waitcnt vmcnt(20)
	v_mfma_f32_16x16x32_fp8_fp8 v[2:5], v[186:187], v[78:79], 0
	v_mfma_f32_16x16x32_fp8_fp8 v[6:9], v[194:195], v[78:79], 0
	v_mfma_f32_16x16x32_fp8_fp8 v[2:5], v[188:189], v[80:81], v[2:5]
	v_mov_b32_e32 v133, v230
	v_mfma_f32_16x16x32_fp8_fp8 v[6:9], v[196:197], v[80:81], v[6:9]
	v_mfma_f32_16x16x32_fp8_fp8 v[2:5], v[190:191], v[82:83], v[2:5]
	v_mfma_f32_16x16x32_fp8_fp8 v[6:9], v[198:199], v[82:83], v[6:9]
	v_mov_b32_e32 v34, v231
	v_mfma_f32_16x16x32_fp8_fp8 v[2:5], v[192:193], v[84:85], v[2:5]
	v_mfma_f32_16x16x32_fp8_fp8 v[6:9], v[200:201], v[84:85], v[6:9]
	s_nop 6
	v_max_f32_e32 v0, v3, v3
	v_max_f32_e32 v10, v2, v2
	v_max_f32_e32 v0, v10, v0
	v_max_f32_e32 v10, v5, v5
	v_max_f32_e32 v11, v4, v4
	v_max_f32_e32 v10, v11, v10
	v_max_f32_e32 v11, v9, v9
	v_max_f32_e32 v12, v8, v8
	v_max_f32_e32 v11, v12, v11
	v_max3_f32 v11, v6, v7, v11
	v_max3_f32 v0, v0, v10, v11
	v_cmp_gt_f32_e32 vcc, v0, v229
	s_cbranch_vccz .LBB0_916
	ds_bpermute_b32 v10, v227, v0
	v_max_f32_e32 v0, v0, v0
	s_waitcnt lgkmcnt(0)
	v_max_f32_e32 v10, v10, v10
	v_max_f32_e32 v0, v0, v10
	ds_bpermute_b32 v10, v226, v0
	s_waitcnt lgkmcnt(0)
	v_max3_f32 v133, v230, v0, v10
	v_sub_f32_e32 v0, v230, v133
	v_exp_f32_e32 v0, v0
	s_nop 0
	v_mul_f32_e32 v34, v231, v0
	v_pk_mul_f32 v[38:39], v[38:39], v[0:1] op_sel_hi:[1,0]
	v_pk_mul_f32 v[36:37], v[36:37], v[0:1] op_sel_hi:[1,0]
	v_pk_mul_f32 v[42:43], v[42:43], v[0:1] op_sel_hi:[1,0]
	v_pk_mul_f32 v[40:41], v[40:41], v[0:1] op_sel_hi:[1,0]
	v_pk_mul_f32 v[46:47], v[46:47], v[0:1] op_sel_hi:[1,0]
	v_pk_mul_f32 v[44:45], v[44:45], v[0:1] op_sel_hi:[1,0]
	v_pk_mul_f32 v[50:51], v[50:51], v[0:1] op_sel_hi:[1,0]
	v_pk_mul_f32 v[48:49], v[48:49], v[0:1] op_sel_hi:[1,0]
	v_pk_mul_f32 v[54:55], v[54:55], v[0:1] op_sel_hi:[1,0]
	v_pk_mul_f32 v[52:53], v[52:53], v[0:1] op_sel_hi:[1,0]
	v_pk_mul_f32 v[58:59], v[58:59], v[0:1] op_sel_hi:[1,0]
	v_pk_mul_f32 v[56:57], v[56:57], v[0:1] op_sel_hi:[1,0]
	v_pk_mul_f32 v[62:63], v[62:63], v[0:1] op_sel_hi:[1,0]
	v_pk_mul_f32 v[60:61], v[60:61], v[0:1] op_sel_hi:[1,0]
	v_pk_mul_f32 v[66:67], v[66:67], v[0:1] op_sel_hi:[1,0]
	v_pk_mul_f32 v[64:65], v[64:65], v[0:1] op_sel_hi:[1,0]
.LBB0_916:
	v_add_f32_e32 v232, -4.0, v133
	v_sub_f32_e32 v0, v2, v232
	v_exp_f32_e32 v233, v0
	v_sub_f32_e32 v0, v6, v232
	v_exp_f32_e32 v236, v0
	v_sub_f32_e32 v0, v3, v232
	v_exp_f32_e32 v2, v0
	v_sub_f32_e32 v0, v7, v232
	v_exp_f32_e32 v0, v0
	v_sub_f32_e32 v3, v4, v232
	v_exp_f32_e32 v237, v3
	v_sub_f32_e32 v3, v8, v232
	v_exp_f32_e32 v238, v3
	v_sub_f32_e32 v3, v5, v232
	v_exp_f32_e32 v4, v3
	v_sub_f32_e32 v3, v9, v232
	v_mov_b32_e32 v234, v1
	v_mov_b32_e32 v235, v1
	v_exp_f32_e32 v232, v3
	v_cvt_pk_fp8_f32 v234, v233, v2
	v_cvt_pk_fp8_f32 v235, v236, v0
	v_add_f32_e32 v3, v233, v236
	v_pk_add_f32 v[2:3], v[2:3], v[0:1]
	v_cvt_pk_fp8_f32 v234, v237, v4 op_sel:[0,0,1]
	v_cvt_pk_fp8_f32 v235, v238, v232 op_sel:[0,0,1]
	v_pk_add_f32 v[2:3], v[2:3], v[2:3] op_sel_hi:[0,1]
	v_add_f32_e32 v5, v237, v238
	v_mov_b32_e32 v233, v3
	v_pk_add_f32 v[2:3], v[4:5], v[232:233]
	s_waitcnt vmcnt(19)
	v_mfma_f32_16x16x32_fp8_fp8 v[6:9], v[170:171], v[234:235], v[36:39]
	v_add_f32_e32 v0, v2, v3
	v_add_f32_e32 v34, v0, v34
	s_mov_b64 s[10:11], 0
	v_mfma_f32_16x16x32_fp8_fp8 v[10:13], v[172:173], v[234:235], v[40:43]
	s_waitcnt vmcnt(18)
	v_mfma_f32_16x16x32_fp8_fp8 v[14:17], v[174:175], v[234:235], v[44:47]
	v_mfma_f32_16x16x32_fp8_fp8 v[18:21], v[176:177], v[234:235], v[48:51]
	s_waitcnt vmcnt(17)
	v_mfma_f32_16x16x32_fp8_fp8 v[22:25], v[178:179], v[234:235], v[52:55]
	v_mfma_f32_16x16x32_fp8_fp8 v[26:29], v[180:181], v[234:235], v[56:59]
	s_waitcnt vmcnt(16)
	v_mfma_f32_16x16x32_fp8_fp8 v[30:33], v[182:183], v[234:235], v[60:63]
	v_mfma_f32_16x16x32_fp8_fp8 v[2:5], v[184:185], v[234:235], v[64:67]
	s_nop 1

; template <bool SLC, bool NOMASK> ...
;     ...
;     const int pos0 = SLC ? (dcur & 0xfffff) : dcur;
;     const int lo = SLC ? ((((dcur >> 20) == qi) | ((dcur >> 20) == 4)) ? 0 : (1 << 30)) : lo_in;
;     load_frag8(nxt, KF, VF, SLC ? (dnext & 0xfffff) : dnext, lane);
;     f32x4 sa[2] = {(f32x4){0.f, 0.f, 0.f, 0.f}, (f32x4){0.f, 0.f, 0.f, 0.f}};
; #pragma unroll
;     for (int T = 0; T < 2; ++T)
; #pragma unroll
;         for (int s2 = 0; s2 < 4; ++s2) sa[T] = __builtin_amdgcn_mfma_f32_16x16x32_fp8_fp8(cur.k[T][s2], qf[s2], sa[T], 0, 0, 0);
;     float sc[8]; bool vd[8]; float mx = -1e30f;
;     const bool act = lo == 0 || !SLC;
;     if (NOMASK) {
; #pragma unroll
;         for (int j = 0; j < 8; ++j) { sc[j] = sa[j >> 2][j & 3]; vd[j] = act; }
;         mx = fmaxf(fmaxf(fmaxf(sc[0], sc[1]), fmaxf(sc[2], sc[3])), fmaxf(fmaxf(sc[4], sc[5]), fmaxf(sc[6], sc[7])));
;         mx = act ? mx : -1e30f;
;     } else {
; #pragma unroll
;         for (int T = 0; T < 2; ++T)
; #pragma unroll
;             for (int r = 0; r < 4; ++r) { const int p = pos0 + 16 * T + 4 * kq + r; const bool v = (p >= lo) & (p <= hi); const float x = sa[T][r];
;                 sc[4 * T + r] = x; vd[4 * T + r] = v; mx = v ? fmaxf(mx, x) : mx; }
;     }
;     if (__builtin_amdgcn_ballot_w64(mx > st.m + 4.f) != 0ull) {
;         mx = fmaxf(mx, __shfl_xor(mx, 16)); mx = fmaxf(mx, __shfl_xor(mx, 32));
;         const float mn = fmaxf(st.m, mx), alpha = __builtin_amdgcn_exp2f(st.m - mn); st.m = mn; st.l *= alpha;
; #pragma unroll
;         for (int j = 0; j < 8; ++j) st.o[j] = st.o[j] * alpha;
;     }
;     f32x4 pa, pb; float ps = 0.f;
;     const float mref = st.m - 4.f;
;     if (NOMASK) {
; #pragma unroll
;         for (int j = 0; j < 4; ++j) { pa[j] = __builtin_amdgcn_exp2f(sc[j] - mref); pb[j] = __builtin_amdgcn_exp2f(sc[4 + j] - mref); }
;         if (SLC) {
; #pragma unroll
;             for (int j = 0; j < 4; ++j) { pa[j] = act ? pa[j] : 0.f; pb[j] = act ? pb[j] : 0.f; }
;         }
; #pragma unroll
;         for (int j = 0; j < 4; ++j) ps += pa[j] + pb[j];
;     } else {
; #pragma unroll
;         for (int j = 0; j < 4; ++j) { pa[j] = vd[j] ? __builtin_amdgcn_exp2f(sc[j] - mref) : 0.f; pb[j] = vd[4 + j] ? __builtin_amdgcn_exp2f(sc[4 + j] - mref) : 0.f; ps += pa[j] + pb[j]; }
;     }
;     st.l += ps;
;     const u32x2 pw = pack8_fp8(pa, pb);
.LBB0_969:
	s_and_b32 s13, s12, 0xfffffbff
	s_cmp_eq_u32 s13, 4
	s_cselect_b64 s[10:11], -1, 0
	s_lshl_b32 s14, s66, 7
	s_and_b32 s50, s14, 0x7fff800
	v_lshl_add_u64 v[10:11], v[86:87], 0, s[50:51]
	s_and_b32 s50, s14, 0x7fff000
	v_lshl_add_u64 v[246:247], v[10:11], 0, v[120:121]
	global_load_dwordx4 v[186:189], v[246:247], off
	global_load_dwordx4 v[190:193], v[246:247], off offset:1024
	global_load_dwordx4 v[194:197], v[246:247], off offset:2048
	global_load_dwordx4 v[198:201], v[246:247], off offset:3072
	v_lshl_add_u64 v[10:11], v[88:89], 0, s[50:51]
	v_lshl_add_u64 v[244:245], v[10:11], 0, v[120:121]
	global_load_dwordx4 v[170:173], v[244:245], off
	global_load_dwordx4 v[174:177], v[244:245], off offset:1024
	global_load_dwordx4 v[178:181], v[244:245], off offset:2048
	global_load_dwordx4 v[182:185], v[244:245], off offset:3072
	s_waitcnt vmcnt(20)
	v_mfma_f32_16x16x32_fp8_fp8 v[2:5], v[138:139], v[78:79], 0
	v_cmp_eq_u32_e32 vcc, s13, v209
	s_or_b64 s[10:11], s[10:11], vcc
	v_mfma_f32_16x16x32_fp8_fp8 v[6:9], v[146:147], v[78:79], 0
	v_mfma_f32_16x16x32_fp8_fp8 v[2:5], v[140:141], v[80:81], v[2:5]
	v_mfma_f32_16x16x32_fp8_fp8 v[6:9], v[148:149], v[80:81], v[6:9]
	v_mfma_f32_16x16x32_fp8_fp8 v[2:5], v[142:143], v[82:83], v[2:5]
	v_mfma_f32_16x16x32_fp8_fp8 v[6:9], v[150:151], v[82:83], v[6:9]
	v_mov_b32_e32 v133, v203
	v_mfma_f32_16x16x32_fp8_fp8 v[2:5], v[144:145], v[84:85], v[2:5]
	v_mfma_f32_16x16x32_fp8_fp8 v[6:9], v[152:153], v[84:85], v[6:9]
	s_nop 6
	v_max_f32_e32 v0, v3, v3
	v_max_f32_e32 v10, v2, v2
	v_max_f32_e32 v0, v10, v0
	v_max_f32_e32 v10, v5, v5
	v_max_f32_e32 v11, v4, v4
	v_max_f32_e32 v10, v11, v10
	v_max_f32_e32 v11, v9, v9
	v_max_f32_e32 v12, v8, v8
	v_max_f32_e32 v11, v12, v11
	v_max3_f32 v11, v6, v7, v11
	v_max3_f32 v0, v0, v10, v11
	v_cndmask_b32_e64 v34, v220, v0, s[10:11]
	v_cmp_gt_f32_e32 vcc, v34, v204
	v_mov_b32_e32 v0, v202
	s_cbranch_vccz .LBB0_971
	ds_bpermute_b32 v0, v225, v34
	v_max_f32_e32 v10, v34, v34
	s_waitcnt lgkmcnt(0)
	v_max_f32_e32 v0, v0, v0
	v_max_f32_e32 v0, v10, v0
	ds_bpermute_b32 v10, v224, v0
	s_waitcnt lgkmcnt(0)
	v_max3_f32 v0, v202, v0, v10
	v_sub_f32_e32 v10, v202, v0
	v_exp_f32_e32 v34, v10
	s_nop 0
	v_mul_f32_e32 v133, v203, v34
	v_pk_mul_f32 v[66:67], v[66:67], v[34:35] op_sel_hi:[1,0]
	v_pk_mul_f32 v[64:65], v[64:65], v[34:35] op_sel_hi:[1,0]
	v_pk_mul_f32 v[62:63], v[62:63], v[34:35] op_sel_hi:[1,0]
	v_pk_mul_f32 v[60:61], v[60:61], v[34:35] op_sel_hi:[1,0]
	v_pk_mul_f32 v[58:59], v[58:59], v[34:35] op_sel_hi:[1,0]
	v_pk_mul_f32 v[56:57], v[56:57], v[34:35] op_sel_hi:[1,0]
	v_pk_mul_f32 v[54:55], v[54:55], v[34:35] op_sel_hi:[1,0]
	v_pk_mul_f32 v[52:53], v[52:53], v[34:35] op_sel_hi:[1,0]
	v_pk_mul_f32 v[50:51], v[50:51], v[34:35] op_sel_hi:[1,0]
	v_pk_mul_f32 v[48:49], v[48:49], v[34:35] op_sel_hi:[1,0]
	v_pk_mul_f32 v[46:47], v[46:47], v[34:35] op_sel_hi:[1,0]
	v_pk_mul_f32 v[44:45], v[44:45], v[34:35] op_sel_hi:[1,0]
	v_pk_mul_f32 v[42:43], v[42:43], v[34:35] op_sel_hi:[1,0]
	v_pk_mul_f32 v[40:41], v[40:41], v[34:35] op_sel_hi:[1,0]
	v_pk_mul_f32 v[38:39], v[38:39], v[34:35] op_sel_hi:[1,0]
	v_pk_mul_f32 v[36:37], v[36:37], v[34:35] op_sel_hi:[1,0]
.LBB0_971:
	v_add_f32_e32 v34, -4.0, v0
	v_sub_f32_e32 v2, v2, v34
	v_sub_f32_e32 v6, v6, v34
	v_sub_f32_e32 v3, v3, v34
	v_sub_f32_e32 v7, v7, v34
	v_exp_f32_e32 v2, v2
	v_exp_f32_e32 v6, v6
	v_exp_f32_e32 v3, v3
	v_exp_f32_e32 v7, v7
	v_sub_f32_e32 v4, v4, v34
	v_sub_f32_e32 v8, v8, v34
	v_sub_f32_e32 v5, v5, v34
	v_sub_f32_e32 v9, v9, v34
	v_exp_f32_e32 v4, v4
	v_exp_f32_e32 v8, v8
	v_exp_f32_e32 v5, v5
	v_exp_f32_e32 v9, v9
	v_cndmask_b32_e64 v34, 0, v2, s[10:11]
	v_cndmask_b32_e64 v6, 0, v6, s[10:11]
	v_cndmask_b32_e64 v35, 0, v3, s[10:11]
	v_cndmask_b32_e64 v7, 0, v7, s[10:11]
	v_mov_b32_e32 v2, v1
	v_mov_b32_e32 v3, v1
	v_cvt_pk_fp8_f32 v2, v34, v35
	v_cvt_pk_fp8_f32 v3, v6, v7
	v_cndmask_b32_e64 v4, 0, v4, s[10:11]
	v_cndmask_b32_e64 v205, 0, v8, s[10:11]
	v_cndmask_b32_e64 v5, 0, v5, s[10:11]
	v_cndmask_b32_e64 v227, 0, v9, s[10:11]
	v_add_f32_e32 v6, v34, v6
	v_cvt_pk_fp8_f32 v2, v4, v5 op_sel:[0,0,1]
	v_cvt_pk_fp8_f32 v3, v205, v227 op_sel:[0,0,1]
	v_add_f32_e32 v6, 0, v6
	v_add_f32_e32 v7, v35, v7
	v_add_f32_e32 v6, v7, v6
	v_add_f32_e32 v4, v4, v205
	v_add_f32_e32 v4, v4, v6
	v_add_f32_e32 v5, v5, v227
	v_add_f32_e32 v4, v5, v4
	s_waitcnt vmcnt(19)
	v_mfma_f32_16x16x32_fp8_fp8 v[8:11], v[90:91], v[2:3], v[64:67]
	v_add_f32_e32 v133, v133, v4
	v_mfma_f32_16x16x32_fp8_fp8 v[12:15], v[92:93], v[2:3], v[60:63]
	s_waitcnt vmcnt(18)
	v_mfma_f32_16x16x32_fp8_fp8 v[16:19], v[94:95], v[2:3], v[56:59]
	v_mfma_f32_16x16x32_fp8_fp8 v[20:23], v[96:97], v[2:3], v[52:55]
	s_waitcnt vmcnt(17)
	v_mfma_f32_16x16x32_fp8_fp8 v[24:27], v[98:99], v[2:3], v[48:51]
	v_mfma_f32_16x16x32_fp8_fp8 v[32:35], v[100:101], v[2:3], v[44:47]
	s_waitcnt vmcnt(16)
	v_mfma_f32_16x16x32_fp8_fp8 v[28:31], v[102:103], v[2:3], v[40:43]
	v_mfma_f32_16x16x32_fp8_fp8 v[4:7], v[104:105], v[2:3], v[36:39]
	s_nop 1
	s_branch .LBB0_965

; template <bool SLC, bool NOMASK> ...
;     ...
;     const int pos0 = SLC ? (dcur & 0xfffff) : dcur;
;     const int lo = SLC ? ((((dcur >> 20) == qi) | ((dcur >> 20) == 4)) ? 0 : (1 << 30)) : lo_in;
;     load_frag8(nxt, KF, VF, SLC ? (dnext & 0xfffff) : dnext, lane);
;     f32x4 sa[2] = {(f32x4){0.f, 0.f, 0.f, 0.f}, (f32x4){0.f, 0.f, 0.f, 0.f}};
; #pragma unroll
;     for (int T = 0; T < 2; ++T)
; #pragma unroll
;         for (int s2 = 0; s2 < 4; ++s2) sa[T] = __builtin_amdgcn_mfma_f32_16x16x32_fp8_fp8(cur.k[T][s2], qf[s2], sa[T], 0, 0, 0);
;     float sc[8]; bool vd[8]; float mx = -1e30f;
;     const bool act = lo == 0 || !SLC;
;     if (NOMASK) {
; #pragma unroll
;         for (int j = 0; j < 8; ++j) { sc[j] = sa[j >> 2][j & 3]; vd[j] = act; }
;         mx = fmaxf(fmaxf(fmaxf(sc[0], sc[1]), fmaxf(sc[2], sc[3])), fmaxf(fmaxf(sc[4], sc[5]), fmaxf(sc[6], sc[7])));
;         mx = act ? mx : -1e30f;
;     } else {
; #pragma unroll
;         for (int T = 0; T < 2; ++T)
; #pragma unroll
;             for (int r = 0; r < 4; ++r) { const int p = pos0 + 16 * T + 4 * kq + r; const bool v = (p >= lo) & (p <= hi); const float x = sa[T][r];
;                 sc[4 * T + r] = x; vd[4 * T + r] = v; mx = v ? fmaxf(mx, x) : mx; }
;     }
;     if (__builtin_amdgcn_ballot_w64(mx > st.m + 4.f) != 0ull) {
;         mx = fmaxf(mx, __shfl_xor(mx, 16)); mx = fmaxf(mx, __shfl_xor(mx, 32));
;         const float mn = fmaxf(st.m, mx), alpha = __builtin_amdgcn_exp2f(st.m - mn); st.m = mn; st.l *= alpha;
; #pragma unroll
;         for (int j = 0; j < 8; ++j) st.o[j] = st.o[j] * alpha;
;     }
;     f32x4 pa, pb; float ps = 0.f;
;     const float mref = st.m - 4.f;
;     if (NOMASK) {
; #pragma unroll
;         for (int j = 0; j < 4; ++j) { pa[j] = __builtin_amdgcn_exp2f(sc[j] - mref); pb[j] = __builtin_amdgcn_exp2f(sc[4 + j] - mref); }
;         if (SLC) {
; #pragma unroll
;             for (int j = 0; j < 4; ++j) { pa[j] = act ? pa[j] : 0.f; pb[j] = act ? pb[j] : 0.f; }
;         }
; #pragma unroll
;         for (int j = 0; j < 4; ++j) ps += pa[j] + pb[j];
;     } else {
; #pragma unroll
;         for (int j = 0; j < 4; ++j) { pa[j] = vd[j] ? __builtin_amdgcn_exp2f(sc[j] - mref) : 0.f; pb[j] = vd[4 + j] ? __builtin_amdgcn_exp2f(sc[4 + j] - mref) : 0.f; ps += pa[j] + pb[j]; }
;     }
;     st.l += ps;
;     const u32x2 pw = pack8_fp8(pa, pb);
.LBB0_976:
	s_and_b32 s13, s12, 0xfffffbff
	s_cmp_eq_u32 s13, 4
	s_cselect_b64 s[10:11], -1, 0
	s_lshl_b32 s14, s57, 7
	s_and_b32 s50, s14, 0x7fff800
	v_lshl_add_u64 v[44:45], v[86:87], 0, s[50:51]
	s_and_b32 s50, s14, 0x7fff000
	v_lshl_add_u64 v[246:247], v[44:45], 0, v[120:121]
	global_load_dwordx4 v[138:141], v[246:247], off
	global_load_dwordx4 v[142:145], v[246:247], off offset:1024
	global_load_dwordx4 v[146:149], v[246:247], off offset:2048
	global_load_dwordx4 v[150:153], v[246:247], off offset:3072
	v_lshl_add_u64 v[44:45], v[88:89], 0, s[50:51]
	v_lshl_add_u64 v[244:245], v[44:45], 0, v[120:121]
	global_load_dwordx4 v[90:93], v[244:245], off
	global_load_dwordx4 v[94:97], v[244:245], off offset:1024
	global_load_dwordx4 v[98:101], v[244:245], off offset:2048
	global_load_dwordx4 v[102:105], v[244:245], off offset:3072
	s_waitcnt vmcnt(20)
	v_mfma_f32_16x16x32_fp8_fp8 v[36:39], v[154:155], v[78:79], 0
	v_cmp_eq_u32_e32 vcc, s13, v209
	s_or_b64 s[10:11], s[10:11], vcc
	v_mfma_f32_16x16x32_fp8_fp8 v[40:43], v[162:163], v[78:79], 0
	v_mfma_f32_16x16x32_fp8_fp8 v[36:39], v[156:157], v[80:81], v[36:39]
	v_mfma_f32_16x16x32_fp8_fp8 v[40:43], v[164:165], v[80:81], v[40:43]
	v_mov_b32_e32 v203, v0
	v_mfma_f32_16x16x32_fp8_fp8 v[36:39], v[158:159], v[82:83], v[36:39]
	v_mfma_f32_16x16x32_fp8_fp8 v[40:43], v[166:167], v[82:83], v[40:43]
	v_mfma_f32_16x16x32_fp8_fp8 v[36:39], v[160:161], v[84:85], v[36:39]
	v_mfma_f32_16x16x32_fp8_fp8 v[40:43], v[168:169], v[84:85], v[40:43]
	s_nop 6
	v_max_f32_e32 v3, v37, v37
	v_max_f32_e32 v44, v36, v36
	v_max_f32_e32 v3, v44, v3
	v_max_f32_e32 v44, v39, v39
	v_max_f32_e32 v45, v38, v38
	v_max_f32_e32 v44, v45, v44
	v_max_f32_e32 v45, v43, v43
	v_max_f32_e32 v46, v42, v42
	v_max_f32_e32 v45, v46, v45
	v_max3_f32 v45, v40, v41, v45
	v_max3_f32 v3, v3, v44, v45
	v_cndmask_b32_e64 v202, v220, v3, s[10:11]
	v_cmp_gt_f32_e32 vcc, v202, v2
	v_mov_b32_e32 v3, v133
	s_cbranch_vccz .LBB0_978
	ds_bpermute_b32 v3, v225, v202
	v_max_f32_e32 v44, v202, v202
	s_waitcnt lgkmcnt(0)
	v_max_f32_e32 v3, v3, v3
	v_max_f32_e32 v3, v44, v3
	ds_bpermute_b32 v44, v224, v3
	s_waitcnt lgkmcnt(0)
	v_max3_f32 v203, v0, v3, v44
	v_sub_f32_e32 v3, v0, v203
	v_exp_f32_e32 v72, v3
	s_nop 0
	v_mul_f32_e32 v3, v133, v72
	v_pk_mul_f32 v[10:11], v[10:11], v[72:73] op_sel_hi:[1,0]
	v_pk_mul_f32 v[8:9], v[8:9], v[72:73] op_sel_hi:[1,0]
	v_pk_mul_f32 v[14:15], v[14:15], v[72:73] op_sel_hi:[1,0]
	v_pk_mul_f32 v[12:13], v[12:13], v[72:73] op_sel_hi:[1,0]
	v_pk_mul_f32 v[18:19], v[18:19], v[72:73] op_sel_hi:[1,0]
	v_pk_mul_f32 v[16:17], v[16:17], v[72:73] op_sel_hi:[1,0]
	v_pk_mul_f32 v[22:23], v[22:23], v[72:73] op_sel_hi:[1,0]
	v_pk_mul_f32 v[20:21], v[20:21], v[72:73] op_sel_hi:[1,0]
	v_pk_mul_f32 v[26:27], v[26:27], v[72:73] op_sel_hi:[1,0]
	v_pk_mul_f32 v[24:25], v[24:25], v[72:73] op_sel_hi:[1,0]
	v_pk_mul_f32 v[34:35], v[34:35], v[72:73] op_sel_hi:[1,0]
	v_pk_mul_f32 v[32:33], v[32:33], v[72:73] op_sel_hi:[1,0]
	v_pk_mul_f32 v[30:31], v[30:31], v[72:73] op_sel_hi:[1,0]
	v_pk_mul_f32 v[28:29], v[28:29], v[72:73] op_sel_hi:[1,0]
	v_pk_mul_f32 v[6:7], v[6:7], v[72:73] op_sel_hi:[1,0]
	v_pk_mul_f32 v[4:5], v[4:5], v[72:73] op_sel_hi:[1,0]
.LBB0_978:
	v_add_f32_e32 v202, -4.0, v203
	v_sub_f32_e32 v36, v36, v202
	v_sub_f32_e32 v40, v40, v202
	v_sub_f32_e32 v37, v37, v202
	v_sub_f32_e32 v41, v41, v202
	v_exp_f32_e32 v36, v36
	v_exp_f32_e32 v40, v40
	v_exp_f32_e32 v37, v37
	v_exp_f32_e32 v41, v41
	v_sub_f32_e32 v38, v38, v202
	v_sub_f32_e32 v42, v42, v202
	v_sub_f32_e32 v39, v39, v202
	v_sub_f32_e32 v43, v43, v202
	v_exp_f32_e32 v38, v38
	v_exp_f32_e32 v42, v42
	v_exp_f32_e32 v39, v39
	v_exp_f32_e32 v43, v43
	v_cndmask_b32_e64 v202, 0, v36, s[10:11]
	v_cndmask_b32_e64 v204, 0, v40, s[10:11]
	v_cndmask_b32_e64 v205, 0, v37, s[10:11]
	v_cndmask_b32_e64 v227, 0, v41, s[10:11]
	v_mov_b32_e32 v228, v1
	v_mov_b32_e32 v229, v1
	v_cvt_pk_fp8_f32 v228, v202, v205
	v_cvt_pk_fp8_f32 v229, v204, v227
	v_cndmask_b32_e64 v230, 0, v38, s[10:11]
	v_cndmask_b32_e64 v231, 0, v42, s[10:11]
	v_cndmask_b32_e64 v232, 0, v39, s[10:11]
	v_cndmask_b32_e64 v233, 0, v43, s[10:11]
	v_cvt_pk_fp8_f32 v228, v230, v232 op_sel:[0,0,1]
	v_cvt_pk_fp8_f32 v229, v231, v233 op_sel:[0,0,1]
	s_nop 0
	s_waitcnt vmcnt(19)
	v_mfma_f32_16x16x32_fp8_fp8 v[40:43], v[108:109], v[228:229], v[12:15]
	v_mfma_f32_16x16x32_fp8_fp8 v[48:51], v[112:113], v[228:229], v[20:23]
	s_nop 2
	v_add_f32_e32 v56, v202, v204
	s_waitcnt vmcnt(18)
	v_mfma_f32_16x16x32_fp8_fp8 v[36:39], v[106:107], v[228:229], v[8:11]
	v_mfma_f32_16x16x32_fp8_fp8 v[44:47], v[110:111], v[228:229], v[16:19]
	s_waitcnt vmcnt(17)
	v_mfma_f32_16x16x32_fp8_fp8 v[52:55], v[114:115], v[228:229], v[24:27]
	s_nop 2
	v_add_f32_e32 v60, 0, v56
	v_add_f32_e32 v61, v205, v227
	v_add_f32_e32 v60, v61, v60
	v_add_f32_e32 v61, v230, v231
	v_mfma_f32_16x16x32_fp8_fp8 v[56:59], v[116:117], v[228:229], v[32:35]
	s_nop 2
	v_add_f32_e32 v64, v61, v60
	v_add_f32_e32 v65, v232, v233
	v_add_f32_e32 v64, v65, v64
	s_waitcnt vmcnt(16)
	v_mfma_f32_16x16x32_fp8_fp8 v[60:63], v[134:135], v[228:229], v[28:31]
	v_add_f32_e32 v204, v3, v64
	v_mfma_f32_16x16x32_fp8_fp8 v[64:67], v[136:137], v[228:229], v[4:7]
	s_nop 1
	s_branch .LBB0_968

; template <bool SLC, bool NOMASK> ...
;     ...
;     const int pos0 = SLC ? (dcur & 0xfffff) : dcur;
;     const int lo = SLC ? ((((dcur >> 20) == qi) | ((dcur >> 20) == 4)) ? 0 : (1 << 30)) : lo_in;
;     load_frag8(nxt, KF, VF, SLC ? (dnext & 0xfffff) : dnext, lane);
;     f32x4 sa[2] = {(f32x4){0.f, 0.f, 0.f, 0.f}, (f32x4){0.f, 0.f, 0.f, 0.f}};
; #pragma unroll
;     for (int T = 0; T < 2; ++T)
; #pragma unroll
;         for (int s2 = 0; s2 < 4; ++s2) sa[T] = __builtin_amdgcn_mfma_f32_16x16x32_fp8_fp8(cur.k[T][s2], qf[s2], sa[T], 0, 0, 0);
;     float sc[8]; bool vd[8]; float mx = -1e30f;
;     const bool act = lo == 0 || !SLC;
;     if (NOMASK) {
; #pragma unroll
;         for (int j = 0; j < 8; ++j) { sc[j] = sa[j >> 2][j & 3]; vd[j] = act; }
;         mx = fmaxf(fmaxf(fmaxf(sc[0], sc[1]), fmaxf(sc[2], sc[3])), fmaxf(fmaxf(sc[4], sc[5]), fmaxf(sc[6], sc[7])));
;         mx = act ? mx : -1e30f;
;     } else {
; #pragma unroll
;         for (int T = 0; T < 2; ++T)
; #pragma unroll
;             for (int r = 0; r < 4; ++r) { const int p = pos0 + 16 * T + 4 * kq + r; const bool v = (p >= lo) & (p <= hi); const float x = sa[T][r];
;                 sc[4 * T + r] = x; vd[4 * T + r] = v; mx = v ? fmaxf(mx, x) : mx; }
;     }
;     if (__builtin_amdgcn_ballot_w64(mx > st.m + 4.f) != 0ull) {
;         mx = fmaxf(mx, __shfl_xor(mx, 16)); mx = fmaxf(mx, __shfl_xor(mx, 32));
;         const float mn = fmaxf(st.m, mx), alpha = __builtin_amdgcn_exp2f(st.m - mn); st.m = mn; st.l *= alpha;
; #pragma unroll
;         for (int j = 0; j < 8; ++j) st.o[j] = st.o[j] * alpha;
;     }
;     f32x4 pa, pb; float ps = 0.f;
;     const float mref = st.m - 4.f;
;     if (NOMASK) {
; #pragma unroll
;         for (int j = 0; j < 4; ++j) { pa[j] = __builtin_amdgcn_exp2f(sc[j] - mref); pb[j] = __builtin_amdgcn_exp2f(sc[4 + j] - mref); }
;         if (SLC) {
; #pragma unroll
;             for (int j = 0; j < 4; ++j) { pa[j] = act ? pa[j] : 0.f; pb[j] = act ? pb[j] : 0.f; }
;         }
; #pragma unroll
;         for (int j = 0; j < 4; ++j) ps += pa[j] + pb[j];
;     } else {
; #pragma unroll
;         for (int j = 0; j < 4; ++j) { pa[j] = vd[j] ? __builtin_amdgcn_exp2f(sc[j] - mref) : 0.f; pb[j] = vd[4 + j] ? __builtin_amdgcn_exp2f(sc[4 + j] - mref) : 0.f; ps += pa[j] + pb[j]; }
;     }
;     st.l += ps;
;     const u32x2 pw = pack8_fp8(pa, pb);
.LBB0_982:
	s_cmp_lt_u32 s56, s54
	s_cselect_b32 s10, s56, s55
	s_lshl_b32 s10, s10, 2
	s_add_i32 s10, s3, s10
	v_mov_b32_e32 v0, s10
	ds_read_b32 v0, v0 offset:13632
	s_and_b32 s13, s66, 2.0
	s_ashr_i32 s12, s66, 20
	s_mov_b64 s[10:11], -1
	s_cmp_eq_u32 s13, 0
	s_waitcnt lgkmcnt(0)
	v_readfirstlane_b32 s92, v0
	v_add_f32_e32 v0, 4.0, v203
	s_cbranch_scc1 .LBB0_986
	s_and_b32 s13, s12, 0xfffffbff
	s_cmp_eq_u32 s13, 4
	s_cselect_b64 s[10:11], -1, 0
	s_lshl_b32 s14, s92, 7
	s_and_b32 s50, s14, 0x7fff800
	v_lshl_add_u64 v[10:11], v[86:87], 0, s[50:51]
	s_and_b32 s50, s14, 0x7fff000
	v_lshl_add_u64 v[246:247], v[10:11], 0, v[120:121]
	global_load_dwordx4 v[154:157], v[246:247], off
	global_load_dwordx4 v[158:161], v[246:247], off offset:1024
	global_load_dwordx4 v[162:165], v[246:247], off offset:2048
	global_load_dwordx4 v[166:169], v[246:247], off offset:3072
	v_lshl_add_u64 v[10:11], v[88:89], 0, s[50:51]
	v_lshl_add_u64 v[244:245], v[10:11], 0, v[120:121]
	global_load_dwordx4 v[106:109], v[244:245], off
	global_load_dwordx4 v[110:113], v[244:245], off offset:1024
	global_load_dwordx4 v[114:117], v[244:245], off offset:2048
	global_load_dwordx4 v[134:137], v[244:245], off offset:3072
	s_waitcnt vmcnt(20)
	v_mfma_f32_16x16x32_fp8_fp8 v[2:5], v[186:187], v[78:79], 0
	v_cmp_eq_u32_e32 vcc, s13, v209
	s_or_b64 s[10:11], s[10:11], vcc
	v_mfma_f32_16x16x32_fp8_fp8 v[6:9], v[194:195], v[78:79], 0
	v_mfma_f32_16x16x32_fp8_fp8 v[2:5], v[188:189], v[80:81], v[2:5]
	v_mfma_f32_16x16x32_fp8_fp8 v[6:9], v[196:197], v[80:81], v[6:9]
	v_mov_b32_e32 v202, v203
	v_mfma_f32_16x16x32_fp8_fp8 v[2:5], v[190:191], v[82:83], v[2:5]
	v_mfma_f32_16x16x32_fp8_fp8 v[6:9], v[198:199], v[82:83], v[6:9]
	v_mov_b32_e32 v133, v204
	v_mfma_f32_16x16x32_fp8_fp8 v[2:5], v[192:193], v[84:85], v[2:5]
	v_mfma_f32_16x16x32_fp8_fp8 v[6:9], v[200:201], v[84:85], v[6:9]
	s_nop 6
	v_max_f32_e32 v10, v3, v3
	v_max_f32_e32 v11, v2, v2
	v_max_f32_e32 v10, v11, v10
	v_max_f32_e32 v11, v5, v5
	v_max_f32_e32 v12, v4, v4
	v_max_f32_e32 v11, v12, v11
	v_max_f32_e32 v12, v9, v9
	v_max_f32_e32 v13, v8, v8
	v_max_f32_e32 v12, v13, v12
	v_max3_f32 v12, v6, v7, v12
	v_max3_f32 v10, v10, v11, v12
	v_cndmask_b32_e64 v34, v220, v10, s[10:11]
	v_cmp_gt_f32_e32 vcc, v34, v0
	s_cbranch_vccz .LBB0_985
	ds_bpermute_b32 v10, v225, v34
	v_max_f32_e32 v11, v34, v34
	s_waitcnt lgkmcnt(0)
	v_max_f32_e32 v10, v10, v10
	v_max_f32_e32 v10, v11, v10
	ds_bpermute_b32 v11, v224, v10
	s_waitcnt lgkmcnt(0)
	v_max3_f32 v202, v203, v10, v11
	v_sub_f32_e32 v10, v203, v202
	v_exp_f32_e32 v34, v10
	s_nop 0
	v_mul_f32_e32 v133, v204, v34
	v_pk_mul_f32 v[38:39], v[38:39], v[34:35] op_sel_hi:[1,0]
	v_pk_mul_f32 v[36:37], v[36:37], v[34:35] op_sel_hi:[1,0]
	v_pk_mul_f32 v[42:43], v[42:43], v[34:35] op_sel_hi:[1,0]
	v_pk_mul_f32 v[40:41], v[40:41], v[34:35] op_sel_hi:[1,0]
	v_pk_mul_f32 v[46:47], v[46:47], v[34:35] op_sel_hi:[1,0]
	v_pk_mul_f32 v[44:45], v[44:45], v[34:35] op_sel_hi:[1,0]
	v_pk_mul_f32 v[50:51], v[50:51], v[34:35] op_sel_hi:[1,0]
	v_pk_mul_f32 v[48:49], v[48:49], v[34:35] op_sel_hi:[1,0]
	v_pk_mul_f32 v[54:55], v[54:55], v[34:35] op_sel_hi:[1,0]
	v_pk_mul_f32 v[52:53], v[52:53], v[34:35] op_sel_hi:[1,0]
	v_pk_mul_f32 v[58:59], v[58:59], v[34:35] op_sel_hi:[1,0]
	v_pk_mul_f32 v[56:57], v[56:57], v[34:35] op_sel_hi:[1,0]
	v_pk_mul_f32 v[62:63], v[62:63], v[34:35] op_sel_hi:[1,0]
	v_pk_mul_f32 v[60:61], v[60:61], v[34:35] op_sel_hi:[1,0]
	v_pk_mul_f32 v[66:67], v[66:67], v[34:35] op_sel_hi:[1,0]
	v_pk_mul_f32 v[64:65], v[64:65], v[34:35] op_sel_hi:[1,0]
.LBB0_985:
	v_add_f32_e32 v34, -4.0, v202
	v_sub_f32_e32 v2, v2, v34
	v_sub_f32_e32 v6, v6, v34
	v_sub_f32_e32 v3, v3, v34
	v_sub_f32_e32 v7, v7, v34
	v_exp_f32_e32 v2, v2
	v_exp_f32_e32 v6, v6
	v_exp_f32_e32 v3, v3
	v_exp_f32_e32 v7, v7
	v_sub_f32_e32 v4, v4, v34
	v_sub_f32_e32 v8, v8, v34
	v_sub_f32_e32 v5, v5, v34
	v_sub_f32_e32 v9, v9, v34
	v_exp_f32_e32 v4, v4
	v_exp_f32_e32 v8, v8
	v_exp_f32_e32 v5, v5
	v_exp_f32_e32 v9, v9
	v_cndmask_b32_e64 v34, 0, v2, s[10:11]
	v_cndmask_b32_e64 v6, 0, v6, s[10:11]
	v_cndmask_b32_e64 v35, 0, v3, s[10:11]
	v_cndmask_b32_e64 v7, 0, v7, s[10:11]
	v_mov_b32_e32 v2, v1
	v_mov_b32_e32 v3, v1
	v_cvt_pk_fp8_f32 v2, v34, v35
	v_cvt_pk_fp8_f32 v3, v6, v7
	v_cndmask_b32_e64 v4, 0, v4, s[10:11]
	v_cndmask_b32_e64 v205, 0, v8, s[10:11]
	v_cndmask_b32_e64 v5, 0, v5, s[10:11]
	v_cndmask_b32_e64 v227, 0, v9, s[10:11]
	v_add_f32_e32 v6, v34, v6
	v_cvt_pk_fp8_f32 v2, v4, v5 op_sel:[0,0,1]
	v_cvt_pk_fp8_f32 v3, v205, v227 op_sel:[0,0,1]
	v_add_f32_e32 v6, 0, v6
	v_add_f32_e32 v7, v35, v7
	v_add_f32_e32 v6, v7, v6
	v_add_f32_e32 v4, v4, v205
	v_add_f32_e32 v4, v4, v6
	v_add_f32_e32 v5, v5, v227
	v_add_f32_e32 v4, v5, v4
	s_waitcnt vmcnt(19)
	v_mfma_f32_16x16x32_fp8_fp8 v[8:11], v[170:171], v[2:3], v[36:39]
	v_add_f32_e32 v133, v133, v4
	s_mov_b64 s[10:11], 0
	v_mfma_f32_16x16x32_fp8_fp8 v[12:15], v[172:173], v[2:3], v[40:43]
	s_waitcnt vmcnt(18)
	v_mfma_f32_16x16x32_fp8_fp8 v[16:19], v[174:175], v[2:3], v[44:47]
	v_mfma_f32_16x16x32_fp8_fp8 v[20:23], v[176:177], v[2:3], v[48:51]
	s_waitcnt vmcnt(17)
	v_mfma_f32_16x16x32_fp8_fp8 v[24:27], v[178:179], v[2:3], v[52:55]
	v_mfma_f32_16x16x32_fp8_fp8 v[32:35], v[180:181], v[2:3], v[56:59]
	s_waitcnt vmcnt(16)
	v_mfma_f32_16x16x32_fp8_fp8 v[28:31], v[182:183], v[2:3], v[60:63]
	v_mfma_f32_16x16x32_fp8_fp8 v[4:7], v[184:185], v[2:3], v[64:67]
	s_nop 1

; template <bool SLC, bool NOMASK> ...
;     ...
;     load_frag8(nxt, KF, VF, SLC ? (dnext & 0xfffff) : dnext, lane);
;     f32x4 sa[2] = {(f32x4){0.f, 0.f, 0.f, 0.f}, (f32x4){0.f, 0.f, 0.f, 0.f}};
; #pragma unroll
;     for (int T = 0; T < 2; ++T)
; #pragma unroll
;         for (int s2 = 0; s2 < 4; ++s2) sa[T] = __builtin_amdgcn_mfma_f32_16x16x32_fp8_fp8(cur.k[T][s2], qf[s2], sa[T], 0, 0, 0);
;     float sc[8]; bool vd[8]; float mx = -1e30f;
;     const bool act = lo == 0 || !SLC;
;     if (NOMASK) {
; #pragma unroll
;         for (int j = 0; j < 8; ++j) { sc[j] = sa[j >> 2][j & 3]; vd[j] = act; }
;         mx = fmaxf(fmaxf(fmaxf(sc[0], sc[1]), fmaxf(sc[2], sc[3])), fmaxf(fmaxf(sc[4], sc[5]), fmaxf(sc[6], sc[7])));
;         mx = act ? mx : -1e30f;
;     } else {
; #pragma unroll
;         for (int T = 0; T < 2; ++T)
; #pragma unroll
;             for (int r = 0; r < 4; ++r) { const int p = pos0 + 16 * T + 4 * kq + r; const bool v = (p >= lo) & (p <= hi); const float x = sa[T][r];
;                 sc[4 * T + r] = x; vd[4 * T + r] = v; mx = v ? fmaxf(mx, x) : mx; }
;     }
;     if (__builtin_amdgcn_ballot_w64(mx > st.m + 4.f) != 0ull) {
;         mx = fmaxf(mx, __shfl_xor(mx, 16)); mx = fmaxf(mx, __shfl_xor(mx, 32));
;         const float mn = fmaxf(st.m, mx), alpha = __builtin_amdgcn_exp2f(st.m - mn); st.m = mn; st.l *= alpha;
; #pragma unroll
;         for (int j = 0; j < 8; ++j) st.o[j] = st.o[j] * alpha;
;     }
;     f32x4 pa, pb; float ps = 0.f;
;     const float mref = st.m - 4.f;
;     if (NOMASK) {
; #pragma unroll
;         for (int j = 0; j < 4; ++j) { pa[j] = __builtin_amdgcn_exp2f(sc[j] - mref); pb[j] = __builtin_amdgcn_exp2f(sc[4 + j] - mref); }
;         if (SLC) {
; #pragma unroll
;             for (int j = 0; j < 4; ++j) { pa[j] = act ? pa[j] : 0.f; pb[j] = act ? pb[j] : 0.f; }
;         }
; #pragma unroll
;         for (int j = 0; j < 4; ++j) ps += pa[j] + pb[j];
;     } else {
; #pragma unroll
;         for (int j = 0; j < 4; ++j) { pa[j] = vd[j] ? __builtin_amdgcn_exp2f(sc[j] - mref) : 0.f; pb[j] = vd[4 + j] ? __builtin_amdgcn_exp2f(sc[4 + j] - mref) : 0.f; ps += pa[j] + pb[j]; }
;     }
;     st.l += ps;
;     const u32x2 pw = pack8_fp8(pa, pb);
;     const i64_t pf = __builtin_bit_cast(i64_t, pw);
; #pragma unroll
;     for (int db = 0; db < 8; ++db) st.o[db] = __builtin_amdgcn_mfma_f32_16x16x32_fp8_fp8(cur.v[db], pf, st.o[db], 0, 0, 0);
.LBB0_1002:
	v_lshl_add_u64 v[246:247], v[204:205], 0, v[120:121]
	global_load_dwordx4 v[186:189], v[246:247], off
	global_load_dwordx4 v[190:193], v[246:247], off offset:1024
	global_load_dwordx4 v[194:197], v[246:247], off offset:2048
	global_load_dwordx4 v[198:201], v[246:247], off offset:3072
	v_lshl_add_u64 v[244:245], v[202:203], 0, v[120:121]
	global_load_dwordx4 v[170:173], v[244:245], off
	global_load_dwordx4 v[174:177], v[244:245], off offset:1024
	global_load_dwordx4 v[178:181], v[244:245], off offset:2048
	global_load_dwordx4 v[182:185], v[244:245], off offset:3072
	s_waitcnt vmcnt(20)
	v_mfma_f32_16x16x32_fp8_fp8 v[2:5], v[138:139], v[78:79], 0
	v_mfma_f32_16x16x32_fp8_fp8 v[6:9], v[146:147], v[78:79], 0
	v_mfma_f32_16x16x32_fp8_fp8 v[2:5], v[140:141], v[80:81], v[2:5]
	v_mov_b32_e32 v228, v133
	v_mfma_f32_16x16x32_fp8_fp8 v[6:9], v[148:149], v[80:81], v[6:9]
	v_mfma_f32_16x16x32_fp8_fp8 v[2:5], v[142:143], v[82:83], v[2:5]
	v_mfma_f32_16x16x32_fp8_fp8 v[6:9], v[150:151], v[82:83], v[6:9]
	v_mov_b32_e32 v34, v227
	v_mfma_f32_16x16x32_fp8_fp8 v[2:5], v[144:145], v[84:85], v[2:5]
	v_mfma_f32_16x16x32_fp8_fp8 v[6:9], v[152:153], v[84:85], v[6:9]
	s_nop 6
	v_max_f32_e32 v0, v3, v3
	v_max_f32_e32 v10, v2, v2
	v_max_f32_e32 v0, v10, v0
	v_max_f32_e32 v10, v5, v5
	v_max_f32_e32 v11, v4, v4
	v_max_f32_e32 v10, v11, v10
	v_max_f32_e32 v11, v9, v9
	v_max_f32_e32 v12, v8, v8
	v_max_f32_e32 v11, v12, v11
	v_max3_f32 v11, v6, v7, v11
	v_max3_f32 v0, v0, v10, v11
	v_add_f32_e32 v10, 4.0, v133
	v_cmp_gt_f32_e32 vcc, v0, v10
	s_cbranch_vccz .LBB0_1004
	ds_bpermute_b32 v10, v225, v0
	v_max_f32_e32 v0, v0, v0
	s_waitcnt lgkmcnt(0)
	v_max_f32_e32 v10, v10, v10
	v_max_f32_e32 v0, v0, v10
	ds_bpermute_b32 v10, v224, v0
	s_waitcnt lgkmcnt(0)
	v_max3_f32 v228, v133, v0, v10
	v_sub_f32_e32 v0, v133, v228
	v_exp_f32_e32 v0, v0
	s_nop 0
	v_mul_f32_e32 v34, v227, v0
	v_pk_mul_f32 v[66:67], v[66:67], v[0:1] op_sel_hi:[1,0]
	v_pk_mul_f32 v[64:65], v[64:65], v[0:1] op_sel_hi:[1,0]
	v_pk_mul_f32 v[62:63], v[62:63], v[0:1] op_sel_hi:[1,0]
	v_pk_mul_f32 v[60:61], v[60:61], v[0:1] op_sel_hi:[1,0]
	v_pk_mul_f32 v[58:59], v[58:59], v[0:1] op_sel_hi:[1,0]
	v_pk_mul_f32 v[56:57], v[56:57], v[0:1] op_sel_hi:[1,0]
	v_pk_mul_f32 v[54:55], v[54:55], v[0:1] op_sel_hi:[1,0]
	v_pk_mul_f32 v[52:53], v[52:53], v[0:1] op_sel_hi:[1,0]
	v_pk_mul_f32 v[50:51], v[50:51], v[0:1] op_sel_hi:[1,0]
	v_pk_mul_f32 v[48:49], v[48:49], v[0:1] op_sel_hi:[1,0]
	v_pk_mul_f32 v[46:47], v[46:47], v[0:1] op_sel_hi:[1,0]
	v_pk_mul_f32 v[44:45], v[44:45], v[0:1] op_sel_hi:[1,0]
	v_pk_mul_f32 v[42:43], v[42:43], v[0:1] op_sel_hi:[1,0]
	v_pk_mul_f32 v[40:41], v[40:41], v[0:1] op_sel_hi:[1,0]
	v_pk_mul_f32 v[38:39], v[38:39], v[0:1] op_sel_hi:[1,0]
	v_pk_mul_f32 v[36:37], v[36:37], v[0:1] op_sel_hi:[1,0]
.LBB0_1004:
	v_add_f32_e32 v229, -4.0, v228
	v_sub_f32_e32 v0, v2, v229
	v_exp_f32_e32 v231, v0
	v_sub_f32_e32 v0, v6, v229
	v_exp_f32_e32 v234, v0
	v_sub_f32_e32 v0, v3, v229
	v_exp_f32_e32 v2, v0
	v_sub_f32_e32 v0, v7, v229
	v_exp_f32_e32 v0, v0
	v_sub_f32_e32 v3, v4, v229
	v_exp_f32_e32 v235, v3
	v_sub_f32_e32 v3, v8, v229
	v_exp_f32_e32 v236, v3
	v_sub_f32_e32 v3, v5, v229
	v_exp_f32_e32 v4, v3
	v_sub_f32_e32 v3, v9, v229
	v_mov_b32_e32 v232, v1
	v_mov_b32_e32 v233, v1
	v_exp_f32_e32 v230, v3
	v_cvt_pk_fp8_f32 v232, v231, v2
	v_cvt_pk_fp8_f32 v233, v234, v0
	v_add_f32_e32 v3, v231, v234
	v_pk_add_f32 v[2:3], v[2:3], v[0:1]
	v_cvt_pk_fp8_f32 v232, v235, v4 op_sel:[0,0,1]
	v_cvt_pk_fp8_f32 v233, v236, v230 op_sel:[0,0,1]
	v_pk_add_f32 v[2:3], v[2:3], v[2:3] op_sel_hi:[0,1]
	v_add_f32_e32 v5, v235, v236
	v_mov_b32_e32 v231, v3
	v_pk_add_f32 v[2:3], v[4:5], v[230:231]
	s_waitcnt vmcnt(19)
	v_mfma_f32_16x16x32_fp8_fp8 v[6:9], v[90:91], v[232:233], v[64:67]
	v_add_f32_e32 v0, v2, v3
	v_add_f32_e32 v34, v0, v34
	v_mfma_f32_16x16x32_fp8_fp8 v[10:13], v[92:93], v[232:233], v[60:63]
	s_waitcnt vmcnt(18)
	v_mfma_f32_16x16x32_fp8_fp8 v[14:17], v[94:95], v[232:233], v[56:59]
	v_mfma_f32_16x16x32_fp8_fp8 v[18:21], v[96:97], v[232:233], v[52:55]
	s_waitcnt vmcnt(17)
	v_mfma_f32_16x16x32_fp8_fp8 v[22:25], v[98:99], v[232:233], v[48:51]
	v_mfma_f32_16x16x32_fp8_fp8 v[26:29], v[100:101], v[232:233], v[44:47]
	s_waitcnt vmcnt(16)
	v_mfma_f32_16x16x32_fp8_fp8 v[30:33], v[102:103], v[232:233], v[40:43]
	v_mfma_f32_16x16x32_fp8_fp8 v[2:5], v[104:105], v[232:233], v[36:39]
	s_nop 1
	s_branch .LBB0_998

; template <bool SLC, bool NOMASK> ...
;     ...
;     load_frag8(nxt, KF, VF, SLC ? (dnext & 0xfffff) : dnext, lane);
;     f32x4 sa[2] = {(f32x4){0.f, 0.f, 0.f, 0.f}, (f32x4){0.f, 0.f, 0.f, 0.f}};
; #pragma unroll
;     for (int T = 0; T < 2; ++T)
; #pragma unroll
;         for (int s2 = 0; s2 < 4; ++s2) sa[T] = __builtin_amdgcn_mfma_f32_16x16x32_fp8_fp8(cur.k[T][s2], qf[s2], sa[T], 0, 0, 0);
;     float sc[8]; bool vd[8]; float mx = -1e30f;
;     const bool act = lo == 0 || !SLC;
;     if (NOMASK) {
; #pragma unroll
;         for (int j = 0; j < 8; ++j) { sc[j] = sa[j >> 2][j & 3]; vd[j] = act; }
;         mx = fmaxf(fmaxf(fmaxf(sc[0], sc[1]), fmaxf(sc[2], sc[3])), fmaxf(fmaxf(sc[4], sc[5]), fmaxf(sc[6], sc[7])));
;         mx = act ? mx : -1e30f;
;     } else {
; #pragma unroll
;         for (int T = 0; T < 2; ++T)
; #pragma unroll
;             for (int r = 0; r < 4; ++r) { const int p = pos0 + 16 * T + 4 * kq + r; const bool v = (p >= lo) & (p <= hi); const float x = sa[T][r];
;                 sc[4 * T + r] = x; vd[4 * T + r] = v; mx = v ? fmaxf(mx, x) : mx; }
;     }
;     if (__builtin_amdgcn_ballot_w64(mx > st.m + 4.f) != 0ull) {
;         mx = fmaxf(mx, __shfl_xor(mx, 16)); mx = fmaxf(mx, __shfl_xor(mx, 32));
;         const float mn = fmaxf(st.m, mx), alpha = __builtin_amdgcn_exp2f(st.m - mn); st.m = mn; st.l *= alpha;
; #pragma unroll
;         for (int j = 0; j < 8; ++j) st.o[j] = st.o[j] * alpha;
;     }
;     f32x4 pa, pb; float ps = 0.f;
;     const float mref = st.m - 4.f;
;     if (NOMASK) {
; #pragma unroll
;         for (int j = 0; j < 4; ++j) { pa[j] = __builtin_amdgcn_exp2f(sc[j] - mref); pb[j] = __builtin_amdgcn_exp2f(sc[4 + j] - mref); }
;         if (SLC) {
; #pragma unroll
;             for (int j = 0; j < 4; ++j) { pa[j] = act ? pa[j] : 0.f; pb[j] = act ? pb[j] : 0.f; }
;         }
; #pragma unroll
;         for (int j = 0; j < 4; ++j) ps += pa[j] + pb[j];
;     } else {
; #pragma unroll
;         for (int j = 0; j < 4; ++j) { pa[j] = vd[j] ? __builtin_amdgcn_exp2f(sc[j] - mref) : 0.f; pb[j] = vd[4 + j] ? __builtin_amdgcn_exp2f(sc[4 + j] - mref) : 0.f; ps += pa[j] + pb[j]; }
;     }
;     st.l += ps;
;     const u32x2 pw = pack8_fp8(pa, pb);
;     const i64_t pf = __builtin_bit_cast(i64_t, pw);
; #pragma unroll
;     for (int db = 0; db < 8; ++db) st.o[db] = __builtin_amdgcn_mfma_f32_16x16x32_fp8_fp8(cur.v[db], pf, st.o[db], 0, 0, 0);
.LBB0_1009:
	v_lshl_add_u64 v[246:247], v[204:205], 0, v[120:121]
	global_load_dwordx4 v[138:141], v[246:247], off
	global_load_dwordx4 v[142:145], v[246:247], off offset:1024
	global_load_dwordx4 v[146:149], v[246:247], off offset:2048
	global_load_dwordx4 v[150:153], v[246:247], off offset:3072
	v_lshl_add_u64 v[244:245], v[202:203], 0, v[120:121]
	global_load_dwordx4 v[90:93], v[244:245], off
	global_load_dwordx4 v[94:97], v[244:245], off offset:1024
	global_load_dwordx4 v[98:101], v[244:245], off offset:2048
	global_load_dwordx4 v[102:105], v[244:245], off offset:3072
	s_waitcnt vmcnt(20)
	v_mfma_f32_16x16x32_fp8_fp8 v[36:39], v[154:155], v[78:79], 0
	v_mfma_f32_16x16x32_fp8_fp8 v[40:43], v[162:163], v[78:79], 0
	v_mfma_f32_16x16x32_fp8_fp8 v[36:39], v[156:157], v[80:81], v[36:39]
	v_mov_b32_e32 v227, v228
	v_mfma_f32_16x16x32_fp8_fp8 v[40:43], v[164:165], v[80:81], v[40:43]
	v_mfma_f32_16x16x32_fp8_fp8 v[36:39], v[158:159], v[82:83], v[36:39]
	v_mfma_f32_16x16x32_fp8_fp8 v[40:43], v[166:167], v[82:83], v[40:43]
	v_mov_b32_e32 v229, v34
	v_mfma_f32_16x16x32_fp8_fp8 v[36:39], v[160:161], v[84:85], v[36:39]
	v_mfma_f32_16x16x32_fp8_fp8 v[40:43], v[168:169], v[84:85], v[40:43]
	s_nop 6
	v_max_f32_e32 v0, v37, v37
	v_max_f32_e32 v44, v36, v36
	v_max_f32_e32 v0, v44, v0
	v_max_f32_e32 v44, v39, v39
	v_max_f32_e32 v45, v38, v38
	v_max_f32_e32 v44, v45, v44
	v_max_f32_e32 v45, v43, v43
	v_max_f32_e32 v46, v42, v42
	v_max_f32_e32 v45, v46, v45
	v_max3_f32 v45, v40, v41, v45
	v_max3_f32 v0, v0, v44, v45
	v_cmp_gt_f32_e32 vcc, v0, v133
	s_cbranch_vccz .LBB0_1011
	ds_bpermute_b32 v44, v225, v0
	v_max_f32_e32 v0, v0, v0
	s_waitcnt lgkmcnt(0)
	v_max_f32_e32 v44, v44, v44
	v_max_f32_e32 v0, v0, v44
	ds_bpermute_b32 v44, v224, v0
	s_waitcnt lgkmcnt(0)
	v_max3_f32 v227, v228, v0, v44
	v_sub_f32_e32 v0, v228, v227
	v_exp_f32_e32 v0, v0
	s_nop 0
	v_mul_f32_e32 v229, v34, v0
	v_pk_mul_f32 v[8:9], v[8:9], v[0:1] op_sel_hi:[1,0]
	v_pk_mul_f32 v[6:7], v[6:7], v[0:1] op_sel_hi:[1,0]
	v_pk_mul_f32 v[12:13], v[12:13], v[0:1] op_sel_hi:[1,0]
	v_pk_mul_f32 v[10:11], v[10:11], v[0:1] op_sel_hi:[1,0]
	v_pk_mul_f32 v[16:17], v[16:17], v[0:1] op_sel_hi:[1,0]
	v_pk_mul_f32 v[14:15], v[14:15], v[0:1] op_sel_hi:[1,0]
	v_pk_mul_f32 v[20:21], v[20:21], v[0:1] op_sel_hi:[1,0]
	v_pk_mul_f32 v[18:19], v[18:19], v[0:1] op_sel_hi:[1,0]
	v_pk_mul_f32 v[24:25], v[24:25], v[0:1] op_sel_hi:[1,0]
	v_pk_mul_f32 v[22:23], v[22:23], v[0:1] op_sel_hi:[1,0]
	v_pk_mul_f32 v[28:29], v[28:29], v[0:1] op_sel_hi:[1,0]
	v_pk_mul_f32 v[26:27], v[26:27], v[0:1] op_sel_hi:[1,0]
	v_pk_mul_f32 v[32:33], v[32:33], v[0:1] op_sel_hi:[1,0]
	v_pk_mul_f32 v[30:31], v[30:31], v[0:1] op_sel_hi:[1,0]
	v_pk_mul_f32 v[4:5], v[4:5], v[0:1] op_sel_hi:[1,0]
	v_pk_mul_f32 v[2:3], v[2:3], v[0:1] op_sel_hi:[1,0]
.LBB0_1011:
	v_add_f32_e32 v231, -4.0, v227
	v_sub_f32_e32 v0, v36, v231
	v_exp_f32_e32 v233, v0
	v_sub_f32_e32 v0, v40, v231
	v_exp_f32_e32 v235, v0
	v_sub_f32_e32 v0, v37, v231
	v_exp_f32_e32 v230, v0
	v_sub_f32_e32 v0, v41, v231
	v_exp_f32_e32 v0, v0
	v_sub_f32_e32 v36, v38, v231
	v_exp_f32_e32 v238, v36
	v_sub_f32_e32 v36, v42, v231
	v_exp_f32_e32 v239, v36
	v_sub_f32_e32 v36, v39, v231
	v_exp_f32_e32 v232, v36
	v_sub_f32_e32 v36, v43, v231
	v_mov_b32_e32 v236, v1
	v_mov_b32_e32 v237, v1
	v_exp_f32_e32 v234, v36
	v_cvt_pk_fp8_f32 v236, v233, v230
	v_cvt_pk_fp8_f32 v237, v235, v0
	v_add_f32_e32 v231, v233, v235
	v_add_f32_e32 v233, v238, v239
	v_cvt_pk_fp8_f32 v236, v238, v232 op_sel:[0,0,1]
	v_cvt_pk_fp8_f32 v237, v239, v234 op_sel:[0,0,1]
	s_nop 0
	s_waitcnt vmcnt(19)
	v_mfma_f32_16x16x32_fp8_fp8 v[36:39], v[106:107], v[236:237], v[6:9]
	v_mfma_f32_16x16x32_fp8_fp8 v[44:47], v[110:111], v[236:237], v[14:17]
	s_waitcnt vmcnt(18)
	v_mfma_f32_16x16x32_fp8_fp8 v[52:55], v[114:115], v[236:237], v[22:25]
	s_nop 2
	v_add_f32_e64 v60, v230, v0
	v_add_f32_e64 v61, v231, v1
	v_mfma_f32_16x16x32_fp8_fp8 v[40:43], v[108:109], v[236:237], v[10:13]
	v_pk_add_f32 v[60:61], v[60:61], v[60:61] op_sel_hi:[0,1]
	v_mov_b32_e32 v235, v61
	s_waitcnt vmcnt(17)
	v_mfma_f32_16x16x32_fp8_fp8 v[48:51], v[112:113], v[236:237], v[18:21]
	v_mfma_f32_16x16x32_fp8_fp8 v[56:59], v[116:117], v[236:237], v[26:29]
	s_nop 2
	v_add_f32_e64 v64, v232, v234
	v_add_f32_e64 v65, v233, v235
	s_waitcnt vmcnt(16)
	v_mfma_f32_16x16x32_fp8_fp8 v[60:63], v[134:135], v[236:237], v[30:33]
	v_add_f32_e32 v0, v64, v65
	v_add_f32_e32 v229, v0, v229
	v_mfma_f32_16x16x32_fp8_fp8 v[64:67], v[136:137], v[236:237], v[2:5]
	s_nop 1
	s_branch .LBB0_1001

; template <bool SLC, bool NOMASK> ...
;     ...
;     const int pos0 = SLC ? (dcur & 0xfffff) : dcur;
;     const int lo = SLC ? ((((dcur >> 20) == qi) | ((dcur >> 20) == 4)) ? 0 : (1 << 30)) : lo_in;
;     load_frag8(nxt, KF, VF, SLC ? (dnext & 0xfffff) : dnext, lane);
;     f32x4 sa[2] = {(f32x4){0.f, 0.f, 0.f, 0.f}, (f32x4){0.f, 0.f, 0.f, 0.f}};
; #pragma unroll
;     for (int T = 0; T < 2; ++T)
; #pragma unroll
;         for (int s2 = 0; s2 < 4; ++s2) sa[T] = __builtin_amdgcn_mfma_f32_16x16x32_fp8_fp8(cur.k[T][s2], qf[s2], sa[T], 0, 0, 0);
;     float sc[8]; bool vd[8]; float mx = -1e30f;
;     const bool act = lo == 0 || !SLC;
;     if (NOMASK) {
; #pragma unroll
;         for (int j = 0; j < 8; ++j) { sc[j] = sa[j >> 2][j & 3]; vd[j] = act; }
;         mx = fmaxf(fmaxf(fmaxf(sc[0], sc[1]), fmaxf(sc[2], sc[3])), fmaxf(fmaxf(sc[4], sc[5]), fmaxf(sc[6], sc[7])));
;         mx = act ? mx : -1e30f;
;     } else {
; #pragma unroll
;         for (int T = 0; T < 2; ++T)
; #pragma unroll
;             for (int r = 0; r < 4; ++r) { const int p = pos0 + 16 * T + 4 * kq + r; const bool v = (p >= lo) & (p <= hi); const float x = sa[T][r];
;                 sc[4 * T + r] = x; vd[4 * T + r] = v; mx = v ? fmaxf(mx, x) : mx; }
;     }
;     if (__builtin_amdgcn_ballot_w64(mx > st.m + 4.f) != 0ull) {
;         mx = fmaxf(mx, __shfl_xor(mx, 16)); mx = fmaxf(mx, __shfl_xor(mx, 32));
;         const float mn = fmaxf(st.m, mx), alpha = __builtin_amdgcn_exp2f(st.m - mn); st.m = mn; st.l *= alpha;
; #pragma unroll
;         for (int j = 0; j < 8; ++j) st.o[j] = st.o[j] * alpha;
;     }
;     f32x4 pa, pb; float ps = 0.f;
;     const float mref = st.m - 4.f;
;     if (NOMASK) {
; #pragma unroll
;         for (int j = 0; j < 4; ++j) { pa[j] = __builtin_amdgcn_exp2f(sc[j] - mref); pb[j] = __builtin_amdgcn_exp2f(sc[4 + j] - mref); }
;         if (SLC) {
; #pragma unroll
;             for (int j = 0; j < 4; ++j) { pa[j] = act ? pa[j] : 0.f; pb[j] = act ? pb[j] : 0.f; }
;         }
; #pragma unroll
;         for (int j = 0; j < 4; ++j) ps += pa[j] + pb[j];
;     } else {
; #pragma unroll
;         for (int j = 0; j < 4; ++j) { pa[j] = vd[j] ? __builtin_amdgcn_exp2f(sc[j] - mref) : 0.f; pb[j] = vd[4 + j] ? __builtin_amdgcn_exp2f(sc[4 + j] - mref) : 0.f; ps += pa[j] + pb[j]; }
;     }
;     st.l += ps;
;     const u32x2 pw = pack8_fp8(pa, pb);
.LBB0_1015:
	s_cmp_lt_i32 s57, s54
	s_cselect_b64 s[10:11], -1, 0
	s_or_b32 s12, s57, 31
	s_cmp_gt_i32 s12, s90
	s_cselect_b64 s[12:13], -1, 0
	s_or_b64 s[10:11], s[10:11], s[12:13]
	s_and_b64 s[10:11], s[10:11], exec
	s_cselect_b32 s10, 0, 2.0
	s_add_i32 s56, s56, 4
	s_or_b32 s14, s10, s57
	s_min_i32 s10, s56, s27
	s_add_i32 s12, s10, s26
	s_lshl_b32 s43, s12, 5
	s_and_b32 s10, s43, 0x3fffffe0
	s_lshr_b32 s50, s10, 4
	s_lshl_b64 s[10:11], s[50:51], 11
	s_and_b32 s50, s12, 0x1ffffff
	s_lshl_b64 s[12:13], s[50:51], 12
	s_cmp_lt_u32 s14, 2.0
	v_lshl_add_u64 v[204:205], v[86:87], 0, s[10:11]
	v_lshl_add_u64 v[202:203], v[88:89], 0, s[12:13]
	s_mov_b64 s[10:11], -1
	v_add_f32_e32 v228, 4.0, v227
	s_cbranch_scc1 .LBB0_1019
	v_lshl_add_u64 v[246:247], v[204:205], 0, v[120:121]
	global_load_dwordx4 v[154:157], v[246:247], off
	global_load_dwordx4 v[158:161], v[246:247], off offset:1024
	global_load_dwordx4 v[162:165], v[246:247], off offset:2048
	global_load_dwordx4 v[166:169], v[246:247], off offset:3072
	v_lshl_add_u64 v[244:245], v[202:203], 0, v[120:121]
	global_load_dwordx4 v[106:109], v[244:245], off
	global_load_dwordx4 v[110:113], v[244:245], off offset:1024
	global_load_dwordx4 v[114:117], v[244:245], off offset:2048
	global_load_dwordx4 v[134:137], v[244:245], off offset:3072
	s_waitcnt vmcnt(20)
	v_mfma_f32_16x16x32_fp8_fp8 v[2:5], v[186:187], v[78:79], 0
	v_mfma_f32_16x16x32_fp8_fp8 v[6:9], v[194:195], v[78:79], 0
	v_mfma_f32_16x16x32_fp8_fp8 v[2:5], v[188:189], v[80:81], v[2:5]
	v_mov_b32_e32 v133, v227
	v_mfma_f32_16x16x32_fp8_fp8 v[6:9], v[196:197], v[80:81], v[6:9]
	v_mfma_f32_16x16x32_fp8_fp8 v[2:5], v[190:191], v[82:83], v[2:5]
	v_mfma_f32_16x16x32_fp8_fp8 v[6:9], v[198:199], v[82:83], v[6:9]
	v_mov_b32_e32 v34, v229
	v_mfma_f32_16x16x32_fp8_fp8 v[2:5], v[192:193], v[84:85], v[2:5]
	v_mfma_f32_16x16x32_fp8_fp8 v[6:9], v[200:201], v[84:85], v[6:9]
	s_nop 6
	v_max_f32_e32 v0, v3, v3
	v_max_f32_e32 v10, v2, v2
	v_max_f32_e32 v0, v10, v0
	v_max_f32_e32 v10, v5, v5
	v_max_f32_e32 v11, v4, v4
	v_max_f32_e32 v10, v11, v10
	v_max_f32_e32 v11, v9, v9
	v_max_f32_e32 v12, v8, v8
	v_max_f32_e32 v11, v12, v11
	v_max3_f32 v11, v6, v7, v11
	v_max3_f32 v0, v0, v10, v11
	v_cmp_gt_f32_e32 vcc, v0, v228
	s_cbranch_vccz .LBB0_1018
	ds_bpermute_b32 v10, v225, v0
	v_max_f32_e32 v0, v0, v0
	s_waitcnt lgkmcnt(0)
	v_max_f32_e32 v10, v10, v10
	v_max_f32_e32 v0, v0, v10
	ds_bpermute_b32 v10, v224, v0
	s_waitcnt lgkmcnt(0)
	v_max3_f32 v133, v227, v0, v10
	v_sub_f32_e32 v0, v227, v133
	v_exp_f32_e32 v0, v0
	s_nop 0
	v_mul_f32_e32 v34, v229, v0
	v_pk_mul_f32 v[38:39], v[38:39], v[0:1] op_sel_hi:[1,0]
	v_pk_mul_f32 v[36:37], v[36:37], v[0:1] op_sel_hi:[1,0]
	v_pk_mul_f32 v[42:43], v[42:43], v[0:1] op_sel_hi:[1,0]
	v_pk_mul_f32 v[40:41], v[40:41], v[0:1] op_sel_hi:[1,0]
	v_pk_mul_f32 v[46:47], v[46:47], v[0:1] op_sel_hi:[1,0]
	v_pk_mul_f32 v[44:45], v[44:45], v[0:1] op_sel_hi:[1,0]
	v_pk_mul_f32 v[50:51], v[50:51], v[0:1] op_sel_hi:[1,0]
	v_pk_mul_f32 v[48:49], v[48:49], v[0:1] op_sel_hi:[1,0]
	v_pk_mul_f32 v[54:55], v[54:55], v[0:1] op_sel_hi:[1,0]
	v_pk_mul_f32 v[52:53], v[52:53], v[0:1] op_sel_hi:[1,0]
	v_pk_mul_f32 v[58:59], v[58:59], v[0:1] op_sel_hi:[1,0]
	v_pk_mul_f32 v[56:57], v[56:57], v[0:1] op_sel_hi:[1,0]
	v_pk_mul_f32 v[62:63], v[62:63], v[0:1] op_sel_hi:[1,0]
	v_pk_mul_f32 v[60:61], v[60:61], v[0:1] op_sel_hi:[1,0]
	v_pk_mul_f32 v[66:67], v[66:67], v[0:1] op_sel_hi:[1,0]
	v_pk_mul_f32 v[64:65], v[64:65], v[0:1] op_sel_hi:[1,0]
.LBB0_1018:
	v_add_f32_e32 v230, -4.0, v133
	v_sub_f32_e32 v0, v2, v230
	v_exp_f32_e32 v231, v0
	v_sub_f32_e32 v0, v6, v230
	v_exp_f32_e32 v234, v0
	v_sub_f32_e32 v0, v3, v230
	v_exp_f32_e32 v2, v0
	v_sub_f32_e32 v0, v7, v230
	v_exp_f32_e32 v0, v0
	v_sub_f32_e32 v3, v4, v230
	v_exp_f32_e32 v235, v3
	v_sub_f32_e32 v3, v8, v230
	v_exp_f32_e32 v236, v3
	v_sub_f32_e32 v3, v5, v230
	v_exp_f32_e32 v4, v3
	v_sub_f32_e32 v3, v9, v230
	v_mov_b32_e32 v232, v1
	v_mov_b32_e32 v233, v1
	v_exp_f32_e32 v230, v3
	v_cvt_pk_fp8_f32 v232, v231, v2
	v_cvt_pk_fp8_f32 v233, v234, v0
	v_add_f32_e32 v3, v231, v234
	v_pk_add_f32 v[2:3], v[2:3], v[0:1]
	v_cvt_pk_fp8_f32 v232, v235, v4 op_sel:[0,0,1]
	v_cvt_pk_fp8_f32 v233, v236, v230 op_sel:[0,0,1]
	v_pk_add_f32 v[2:3], v[2:3], v[2:3] op_sel_hi:[0,1]
	v_add_f32_e32 v5, v235, v236
	v_mov_b32_e32 v231, v3
	v_pk_add_f32 v[2:3], v[4:5], v[230:231]
	s_waitcnt vmcnt(19)
	v_mfma_f32_16x16x32_fp8_fp8 v[6:9], v[170:171], v[232:233], v[36:39]
	v_add_f32_e32 v0, v2, v3
	v_add_f32_e32 v34, v0, v34
	s_mov_b64 s[10:11], 0
	v_mfma_f32_16x16x32_fp8_fp8 v[10:13], v[172:173], v[232:233], v[40:43]
	s_waitcnt vmcnt(18)
	v_mfma_f32_16x16x32_fp8_fp8 v[14:17], v[174:175], v[232:233], v[44:47]
	v_mfma_f32_16x16x32_fp8_fp8 v[18:21], v[176:177], v[232:233], v[48:51]
	s_waitcnt vmcnt(17)
	v_mfma_f32_16x16x32_fp8_fp8 v[22:25], v[178:179], v[232:233], v[52:55]
	v_mfma_f32_16x16x32_fp8_fp8 v[26:29], v[180:181], v[232:233], v[56:59]
	s_waitcnt vmcnt(16)
	v_mfma_f32_16x16x32_fp8_fp8 v[30:33], v[182:183], v[232:233], v[60:63]
	v_mfma_f32_16x16x32_fp8_fp8 v[2:5], v[184:185], v[232:233], v[64:67]
	s_nop 1
